# RMSNorm passes fused: EpiRes emits sum-of-squares partials, mini-phase computes rinv + folds extra rows, P2/P8 read X and scale rows by rinv in their epilogues; hand-written EpiRes and EpiFfn
# speedup vs baseline: 1.0314x; 1.0314x over previous
; __device__ __forceinline__ unsigned cvt_pk_bf16(float lo, float hi) { unsigned r; asm volatile("v_cvt_pk_bf16_f32 %0, %1, %2" : "=v"(r) : "v"(lo), "v"(hi)); return r; }
; __device__ __forceinline__ float bflo(unsigned w) { return __uint_as_float(w << 16); }
; __device__ __forceinline__ float bfhi(unsigned w) { return __uint_as_float(w & 0xffff0000u); }
; __device__ __forceinline__ void norm_phase(KP p, bool first, int nslab) {
;     ...
;         f32x4 v[4]; float s = 0.f;
;         if (first) { const f32x4* xr = (const f32x4*)src_row(p, m) + lane;
; #pragma unroll
;             for (int j = 0; j < 4; ++j) v[j] = __builtin_nontemporal_load(xr + 64 * j); }
;         else { const u32x2* xr = (const u32x2*)(X + (size_t)m * D) + lane;
; #pragma unroll
;             for (int j = 0; j < 4; ++j) { const u32x2 w = __builtin_nontemporal_load(xr + 64 * j); v[j] = (f32x4){bflo(w.x), bfhi(w.x), bflo(w.y), bfhi(w.y)}; } }
;         const bool fold = (!first) && m >= 64 * 256;
;         if (fold) { const f32x4* sl = (const f32x4*)(p->ws + WS_SLAB) + (size_t)(m - 64 * 256) * (D / 4) + lane;
;             for (int q = 0; q < nslab; ++q) {
; #pragma unroll
;                 for (int j = 0; j < 4; ++j) v[j] += sl[(size_t)q * 256 * (D / 4) + 64 * j]; } }
;         if (first || fold) { u32x2* xo = (u32x2*)(X + (size_t)m * D) + lane;
; #pragma unroll
;             for (int j = 0; j < 4; ++j) { u32x2 w; w.x = cvt_pk_bf16(v[j][0], v[j][1]); w.y = cvt_pk_bf16(v[j][2], v[j][3]); xo[64 * j] = w; } }
; #pragma unroll
;         for (int j = 0; j < 4; ++j) s += (v[j][0] * v[j][0] + v[j][1] * v[j][1]) + (v[j][2] * v[j][2] + v[j][3] * v[j][3]);
;         const float rinv = rsqrtf(wave_sum(s) * (1.f / D) + EPS);
.LBB0_59:
	s_waitcnt lgkmcnt(0)
	s_cmp_eq_u32 s56, 0
	s_cbranch_scc1 .Lp1_orig
	s_mov_b64 s[4:5], s[0:1]
	v_mov_b32_e32 v0, v209
	s_load_dwordx2 s[8:9], s[4:5], 0xe8
	v_and_b32_e32 v2, 63, v0
	v_readfirstlane_b32 s6, v0
	s_nop 3
	s_lshr_b32 s6, s6, 6
	s_waitcnt lgkmcnt(0)
	s_add_u32 s10, s8, 0x25c8000
	s_addc_u32 s11, s9, 0
	s_add_u32 s12, s8, 0x18c48000
	s_addc_u32 s13, s9, 0
	s_add_u32 s14, s8, 0x19068000
	s_addc_u32 s15, s9, 0
	s_cmpk_lt_u32 s2, 32
	s_cbranch_scc1 .Lnm_part2_p1
	s_cmpk_lt_u32 s2, 0xe0
	s_cbranch_scc1 .Lp1m_exit
	s_sub_i32 s16, s2, 0xe0
	s_lshl_b32 s16, s16, 3
	s_add_i32 s16, s16, s6
	s_add_i32 s18, s16, 0x4000
	s_lshl_b32 s19, s18, 2
	s_lshl_b32 s18, s18, 11
	s_add_u32 s10, s10, s18
	s_addc_u32 s11, s11, 0
	s_add_u32 s14, s14, s19
	s_addc_u32 s15, s15, 0
	v_lshlrev_b32_e32 v5, 3, v2
	v_lshlrev_b32_e32 v6, 4, v2
	global_load_dwordx2 v[18:19], v5, s[10:11]
	global_load_dwordx2 v[20:21], v5, s[10:11] offset:512
	global_load_dwordx2 v[22:23], v5, s[10:11] offset:1024
	global_load_dwordx2 v[24:25], v5, s[10:11] offset:1536
	s_lshl_b32 s18, s16, 12
	s_add_u32 s18, s8, s18
	s_addc_u32 s19, s9, 0
	s_add_u32 s18, s18, 0x1a3ac000
	s_addc_u32 s19, s19, 0
	global_load_dwordx4 v[32:35], v6, s[18:19]
	global_load_dwordx4 v[36:39], v6, s[18:19] offset:1024
	global_load_dwordx4 v[40:43], v6, s[18:19] offset:2048
	global_load_dwordx4 v[44:47], v6, s[18:19] offset:3072
	s_add_u32 s18, s18, 0x100000
	s_addc_u32 s19, s19, 0
	global_load_dwordx4 v[48:51], v6, s[18:19]
	global_load_dwordx4 v[52:55], v6, s[18:19] offset:1024
	global_load_dwordx4 v[56:59], v6, s[18:19] offset:2048
	global_load_dwordx4 v[60:63], v6, s[18:19] offset:3072
	s_add_u32 s18, s18, 0x100000
	s_addc_u32 s19, s19, 0
	global_load_dwordx4 v[64:67], v6, s[18:19]
	global_load_dwordx4 v[68:71], v6, s[18:19] offset:1024
	global_load_dwordx4 v[72:75], v6, s[18:19] offset:2048
	global_load_dwordx4 v[76:79], v6, s[18:19] offset:3072
	s_add_u32 s18, s18, 0x100000
	s_addc_u32 s19, s19, 0
	global_load_dwordx4 v[80:83], v6, s[18:19]
	global_load_dwordx4 v[84:87], v6, s[18:19] offset:1024
	global_load_dwordx4 v[88:91], v6, s[18:19] offset:2048
	global_load_dwordx4 v[92:95], v6, s[18:19] offset:3072
	s_add_u32 s18, s18, 0x100000
	s_addc_u32 s19, s19, 0
	global_load_dwordx4 v[96:99], v6, s[18:19]
	global_load_dwordx4 v[100:103], v6, s[18:19] offset:1024
	global_load_dwordx4 v[104:107], v6, s[18:19] offset:2048
	global_load_dwordx4 v[108:111], v6, s[18:19] offset:3072
	s_add_u32 s18, s18, 0x100000
	s_addc_u32 s19, s19, 0
	global_load_dwordx4 v[112:115], v6, s[18:19]
	global_load_dwordx4 v[116:119], v6, s[18:19] offset:1024
	global_load_dwordx4 v[120:123], v6, s[18:19] offset:2048
	global_load_dwordx4 v[124:127], v6, s[18:19] offset:3072
	s_add_u32 s18, s18, 0x100000
	s_addc_u32 s19, s19, 0
	global_load_dwordx4 v[128:131], v6, s[18:19]
	global_load_dwordx4 v[132:135], v6, s[18:19] offset:1024
	global_load_dwordx4 v[136:139], v6, s[18:19] offset:2048
	global_load_dwordx4 v[140:143], v6, s[18:19] offset:3072
	s_add_u32 s18, s18, 0x100000
	s_addc_u32 s19, s19, 0
	global_load_dwordx4 v[144:147], v6, s[18:19]
	global_load_dwordx4 v[148:151], v6, s[18:19] offset:1024
	global_load_dwordx4 v[152:155], v6, s[18:19] offset:2048
	global_load_dwordx4 v[156:159], v6, s[18:19] offset:3072
	s_add_u32 s18, s18, 0x100000
	s_addc_u32 s19, s19, 0
	s_waitcnt vmcnt(32)
	v_lshlrev_b32_e32 v224, 16, v18
	v_and_b32_e32 v225, 0xffff0000, v18
	v_lshlrev_b32_e32 v226, 16, v19
	v_and_b32_e32 v227, 0xffff0000, v19
	v_lshlrev_b32_e32 v228, 16, v20
	v_and_b32_e32 v229, 0xffff0000, v20
	v_lshlrev_b32_e32 v230, 16, v21
	v_and_b32_e32 v231, 0xffff0000, v21
	v_lshlrev_b32_e32 v232, 16, v22
	v_and_b32_e32 v233, 0xffff0000, v22
	v_lshlrev_b32_e32 v234, 16, v23
	v_and_b32_e32 v235, 0xffff0000, v23
	v_lshlrev_b32_e32 v236, 16, v24
	v_and_b32_e32 v237, 0xffff0000, v24
	v_lshlrev_b32_e32 v238, 16, v25
	v_and_b32_e32 v239, 0xffff0000, v25
	s_waitcnt vmcnt(28)
	v_add_f32_e32 v224, v224, v32
	v_add_f32_e32 v225, v225, v33
	v_add_f32_e32 v226, v226, v34
	v_add_f32_e32 v227, v227, v35
	v_add_f32_e32 v228, v228, v36
	v_add_f32_e32 v229, v229, v37
	v_add_f32_e32 v230, v230, v38
	v_add_f32_e32 v231, v231, v39
	v_add_f32_e32 v232, v232, v40
	v_add_f32_e32 v233, v233, v41
	v_add_f32_e32 v234, v234, v42
	v_add_f32_e32 v235, v235, v43
	v_add_f32_e32 v236, v236, v44
	v_add_f32_e32 v237, v237, v45
	v_add_f32_e32 v238, v238, v46
	v_add_f32_e32 v239, v239, v47
	s_waitcnt vmcnt(24)
	v_add_f32_e32 v224, v224, v48
	v_add_f32_e32 v225, v225, v49
	v_add_f32_e32 v226, v226, v50
	v_add_f32_e32 v227, v227, v51
	v_add_f32_e32 v228, v228, v52
	v_add_f32_e32 v229, v229, v53
	v_add_f32_e32 v230, v230, v54
	v_add_f32_e32 v231, v231, v55
	v_add_f32_e32 v232, v232, v56
	v_add_f32_e32 v233, v233, v57
	v_add_f32_e32 v234, v234, v58
	v_add_f32_e32 v235, v235, v59
	v_add_f32_e32 v236, v236, v60
	v_add_f32_e32 v237, v237, v61
	v_add_f32_e32 v238, v238, v62
	v_add_f32_e32 v239, v239, v63
	s_waitcnt vmcnt(20)
	v_add_f32_e32 v224, v224, v64
	v_add_f32_e32 v225, v225, v65
	v_add_f32_e32 v226, v226, v66
	v_add_f32_e32 v227, v227, v67
	v_add_f32_e32 v228, v228, v68
	v_add_f32_e32 v229, v229, v69
	v_add_f32_e32 v230, v230, v70
	v_add_f32_e32 v231, v231, v71
	v_add_f32_e32 v232, v232, v72
	v_add_f32_e32 v233, v233, v73
	v_add_f32_e32 v234, v234, v74
	v_add_f32_e32 v235, v235, v75
	v_add_f32_e32 v236, v236, v76
	v_add_f32_e32 v237, v237, v77
	v_add_f32_e32 v238, v238, v78
	v_add_f32_e32 v239, v239, v79
	s_waitcnt vmcnt(16)
; __device__ __forceinline__ unsigned cvt_pk_bf16(float lo, float hi) { unsigned r; asm volatile("v_cvt_pk_bf16_f32 %0, %1, %2" : "=v"(r) : "v"(lo), "v"(hi)); return r; }
; __device__ __forceinline__ void norm_phase(KP p, bool first, int nslab) {
;     ...
;         if (fold) { const f32x4* sl = (const f32x4*)(p->ws + WS_SLAB) + (size_t)(m - 64 * 256) * (D / 4) + lane;
;             for (int q = 0; q < nslab; ++q) {
; #pragma unroll
;                 for (int j = 0; j < 4; ++j) v[j] += sl[(size_t)q * 256 * (D / 4) + 64 * j]; } }
;         if (first || fold) { u32x2* xo = (u32x2*)(X + (size_t)m * D) + lane;
; #pragma unroll
;             for (int j = 0; j < 4; ++j) { u32x2 w; w.x = cvt_pk_bf16(v[j][0], v[j][1]); w.y = cvt_pk_bf16(v[j][2], v[j][3]); xo[64 * j] = w; } }
; #pragma unroll
;         for (int j = 0; j < 4; ++j) s += (v[j][0] * v[j][0] + v[j][1] * v[j][1]) + (v[j][2] * v[j][2] + v[j][3] * v[j][3]);
;         const float rinv = rsqrtf(wave_sum(s) * (1.f / D) + EPS);
	v_add_f32_e32 v224, v224, v80
	v_add_f32_e32 v225, v225, v81
	v_add_f32_e32 v226, v226, v82
	v_add_f32_e32 v227, v227, v83
	v_add_f32_e32 v228, v228, v84
	v_add_f32_e32 v229, v229, v85
	v_add_f32_e32 v230, v230, v86
	v_add_f32_e32 v231, v231, v87
	v_add_f32_e32 v232, v232, v88
	v_add_f32_e32 v233, v233, v89
	v_add_f32_e32 v234, v234, v90
	v_add_f32_e32 v235, v235, v91
	v_add_f32_e32 v236, v236, v92
	v_add_f32_e32 v237, v237, v93
	v_add_f32_e32 v238, v238, v94
	v_add_f32_e32 v239, v239, v95
	s_waitcnt vmcnt(12)
	v_add_f32_e32 v224, v224, v96
	v_add_f32_e32 v225, v225, v97
	v_add_f32_e32 v226, v226, v98
	v_add_f32_e32 v227, v227, v99
	v_add_f32_e32 v228, v228, v100
	v_add_f32_e32 v229, v229, v101
	v_add_f32_e32 v230, v230, v102
	v_add_f32_e32 v231, v231, v103
	v_add_f32_e32 v232, v232, v104
	v_add_f32_e32 v233, v233, v105
	v_add_f32_e32 v234, v234, v106
	v_add_f32_e32 v235, v235, v107
	v_add_f32_e32 v236, v236, v108
	v_add_f32_e32 v237, v237, v109
	v_add_f32_e32 v238, v238, v110
	v_add_f32_e32 v239, v239, v111
	s_waitcnt vmcnt(8)
	v_add_f32_e32 v224, v224, v112
	v_add_f32_e32 v225, v225, v113
	v_add_f32_e32 v226, v226, v114
	v_add_f32_e32 v227, v227, v115
	v_add_f32_e32 v228, v228, v116
	v_add_f32_e32 v229, v229, v117
	v_add_f32_e32 v230, v230, v118
	v_add_f32_e32 v231, v231, v119
	v_add_f32_e32 v232, v232, v120
	v_add_f32_e32 v233, v233, v121
	v_add_f32_e32 v234, v234, v122
	v_add_f32_e32 v235, v235, v123
	v_add_f32_e32 v236, v236, v124
	v_add_f32_e32 v237, v237, v125
	v_add_f32_e32 v238, v238, v126
	v_add_f32_e32 v239, v239, v127
	s_waitcnt vmcnt(4)
	v_add_f32_e32 v224, v224, v128
	v_add_f32_e32 v225, v225, v129
	v_add_f32_e32 v226, v226, v130
	v_add_f32_e32 v227, v227, v131
	v_add_f32_e32 v228, v228, v132
	v_add_f32_e32 v229, v229, v133
	v_add_f32_e32 v230, v230, v134
	v_add_f32_e32 v231, v231, v135
	v_add_f32_e32 v232, v232, v136
	v_add_f32_e32 v233, v233, v137
	v_add_f32_e32 v234, v234, v138
	v_add_f32_e32 v235, v235, v139
	v_add_f32_e32 v236, v236, v140
	v_add_f32_e32 v237, v237, v141
	v_add_f32_e32 v238, v238, v142
	v_add_f32_e32 v239, v239, v143
	s_waitcnt vmcnt(0)
	v_add_f32_e32 v224, v224, v144
	v_add_f32_e32 v225, v225, v145
	v_add_f32_e32 v226, v226, v146
	v_add_f32_e32 v227, v227, v147
	v_add_f32_e32 v228, v228, v148
	v_add_f32_e32 v229, v229, v149
	v_add_f32_e32 v230, v230, v150
	v_add_f32_e32 v231, v231, v151
	v_add_f32_e32 v232, v232, v152
	v_add_f32_e32 v233, v233, v153
	v_add_f32_e32 v234, v234, v154
	v_add_f32_e32 v235, v235, v155
	v_add_f32_e32 v236, v236, v156
	v_add_f32_e32 v237, v237, v157
	v_add_f32_e32 v238, v238, v158
	v_add_f32_e32 v239, v239, v159
	global_load_dwordx4 v[32:35], v6, s[18:19]
	global_load_dwordx4 v[36:39], v6, s[18:19] offset:1024
	global_load_dwordx4 v[40:43], v6, s[18:19] offset:2048
	global_load_dwordx4 v[44:47], v6, s[18:19] offset:3072
	s_add_u32 s18, s18, 0x100000
	s_addc_u32 s19, s19, 0
	global_load_dwordx4 v[48:51], v6, s[18:19]
	global_load_dwordx4 v[52:55], v6, s[18:19] offset:1024
	global_load_dwordx4 v[56:59], v6, s[18:19] offset:2048
	global_load_dwordx4 v[60:63], v6, s[18:19] offset:3072
	s_add_u32 s18, s18, 0x100000
	s_addc_u32 s19, s19, 0
	global_load_dwordx4 v[64:67], v6, s[18:19]
	global_load_dwordx4 v[68:71], v6, s[18:19] offset:1024
	global_load_dwordx4 v[72:75], v6, s[18:19] offset:2048
	global_load_dwordx4 v[76:79], v6, s[18:19] offset:3072
	s_add_u32 s18, s18, 0x100000
	s_addc_u32 s19, s19, 0
	s_waitcnt vmcnt(8)
	v_add_f32_e32 v224, v224, v32
	v_add_f32_e32 v225, v225, v33
	v_add_f32_e32 v226, v226, v34
	v_add_f32_e32 v227, v227, v35
	v_add_f32_e32 v228, v228, v36
	v_add_f32_e32 v229, v229, v37
	v_add_f32_e32 v230, v230, v38
	v_add_f32_e32 v231, v231, v39
	v_add_f32_e32 v232, v232, v40
	v_add_f32_e32 v233, v233, v41
	v_add_f32_e32 v234, v234, v42
	v_add_f32_e32 v235, v235, v43
	v_add_f32_e32 v236, v236, v44
	v_add_f32_e32 v237, v237, v45
	v_add_f32_e32 v238, v238, v46
	v_add_f32_e32 v239, v239, v47
	s_waitcnt vmcnt(4)
	v_add_f32_e32 v224, v224, v48
	v_add_f32_e32 v225, v225, v49
	v_add_f32_e32 v226, v226, v50
	v_add_f32_e32 v227, v227, v51
	v_add_f32_e32 v228, v228, v52
	v_add_f32_e32 v229, v229, v53
	v_add_f32_e32 v230, v230, v54
	v_add_f32_e32 v231, v231, v55
	v_add_f32_e32 v232, v232, v56
	v_add_f32_e32 v233, v233, v57
	v_add_f32_e32 v234, v234, v58
	v_add_f32_e32 v235, v235, v59
	v_add_f32_e32 v236, v236, v60
	v_add_f32_e32 v237, v237, v61
	v_add_f32_e32 v238, v238, v62
	v_add_f32_e32 v239, v239, v63
	s_waitcnt vmcnt(0)
	v_add_f32_e32 v224, v224, v64
	v_add_f32_e32 v225, v225, v65
	v_add_f32_e32 v226, v226, v66
	v_add_f32_e32 v227, v227, v67
	v_add_f32_e32 v228, v228, v68
	v_add_f32_e32 v229, v229, v69
	v_add_f32_e32 v230, v230, v70
	v_add_f32_e32 v231, v231, v71
	v_add_f32_e32 v232, v232, v72
	v_add_f32_e32 v233, v233, v73
	v_add_f32_e32 v234, v234, v74
	v_add_f32_e32 v235, v235, v75
	v_add_f32_e32 v236, v236, v76
	v_add_f32_e32 v237, v237, v77
	v_add_f32_e32 v238, v238, v78
	v_add_f32_e32 v239, v239, v79
	v_cvt_pk_bf16_f32 v26, v224, v225
	v_cvt_pk_bf16_f32 v27, v226, v227
	global_store_dwordx2 v5, v[26:27], s[10:11]
	v_cvt_pk_bf16_f32 v28, v228, v229
	v_cvt_pk_bf16_f32 v29, v230, v231
	global_store_dwordx2 v5, v[28:29], s[10:11] offset:512
	v_cvt_pk_bf16_f32 v30, v232, v233
	v_cvt_pk_bf16_f32 v31, v234, v235
	global_store_dwordx2 v5, v[30:31], s[10:11] offset:1024
	v_cvt_pk_bf16_f32 v32, v236, v237
	v_cvt_pk_bf16_f32 v33, v238, v239
	global_store_dwordx2 v5, v[32:33], s[10:11] offset:1536
	v_mul_f32_e32 v7, v224, v224
	v_fmac_f32_e32 v7, v225, v225
	v_fmac_f32_e32 v7, v226, v226
	v_fmac_f32_e32 v7, v227, v227
	v_fmac_f32_e32 v7, v228, v228
	v_fmac_f32_e32 v7, v229, v229
	v_fmac_f32_e32 v7, v230, v230
	v_fmac_f32_e32 v7, v231, v231
	v_fmac_f32_e32 v7, v232, v232
	v_fmac_f32_e32 v7, v233, v233
	v_fmac_f32_e32 v7, v234, v234
	v_fmac_f32_e32 v7, v235, v235
	v_fmac_f32_e32 v7, v236, v236
	v_fmac_f32_e32 v7, v237, v237
	v_fmac_f32_e32 v7, v238, v238
	v_fmac_f32_e32 v7, v239, v239
	v_xor_b32_e32 v10, 1, v2
	v_lshlrev_b32_e32 v10, 2, v10
	ds_bpermute_b32 v10, v10, v7
	s_waitcnt lgkmcnt(0)
	v_add_f32_e32 v7, v7, v10
	v_xor_b32_e32 v10, 2, v2
	v_lshlrev_b32_e32 v10, 2, v10
	ds_bpermute_b32 v10, v10, v7
	s_waitcnt lgkmcnt(0)
	v_add_f32_e32 v7, v7, v10
	v_xor_b32_e32 v10, 4, v2
	v_lshlrev_b32_e32 v10, 2, v10
	ds_bpermute_b32 v10, v10, v7
	s_waitcnt lgkmcnt(0)
	v_add_f32_e32 v7, v7, v10
	v_xor_b32_e32 v10, 8, v2
	v_lshlrev_b32_e32 v10, 2, v10
	ds_bpermute_b32 v10, v10, v7
	s_waitcnt lgkmcnt(0)
	v_add_f32_e32 v7, v7, v10
	v_xor_b32_e32 v10, 16, v2
	v_lshlrev_b32_e32 v10, 2, v10
	ds_bpermute_b32 v10, v10, v7
	s_waitcnt lgkmcnt(0)
	v_add_f32_e32 v7, v7, v10
	v_xor_b32_e32 v10, 32, v2
	v_lshlrev_b32_e32 v10, 2, v10
	ds_bpermute_b32 v10, v10, v7
	s_waitcnt lgkmcnt(0)
	v_add_f32_e32 v7, v7, v10
	v_fmamk_f32 v7, v7, 0x3a800000, v213
	v_rsq_f32_e32 v7, v7
	s_nop 0
	global_store_dword v1, v7, s[14:15]
	s_branch .Lp1m_exit
; __device__ __forceinline__ int tid_() { int t = threadIdx.x; asm volatile("" : "+v"(t)); return t; }
; __device__ __forceinline__ int bid_() { int t = blockIdx.x; asm volatile("" : "+s"(t)); return t; }
; __device__ __forceinline__ int gdim_() { int t = gridDim.x; asm volatile("" : "+s"(t)); return t; }
; __device__ __forceinline__ void norm_phase(KP p, bool first, int nslab) {
;     const int tid = tid_(), lane = tid & 63, wave = __builtin_amdgcn_readfirstlane(tid >> 6);
;     const int gw = bid_() * 8 + wave, NGW = gdim_() * 8;
;     bf16_t* X = (bf16_t*)(p->ws + WS_X); bf16_t* XN = (bf16_t*)(p->ws + WS_R2);
;     const bool xaware = gdim_() == 256; const int cb = bid_(), xl = cb & 7, jl = cb >> 3;
;     for (int it = 0; it < 9; ++it) {
;         int m;
;         if (xaware) { if (it < 8) m = 2048 * xl + 256 * it + jl * 8 + wave; else { if (gw >= 256) break; m = 64 * 256 + gw; } }
;         else { m = gw + it * NGW; if (m >= M) break; }
;     ...
;         for (int j = 0; j < 4; ++j) s += (v[j][0] * v[j][0] + v[j][1] * v[j][1]) + (v[j][2] * v[j][2] + v[j][3] * v[j][3]);
;         const float rinv = rsqrtf(wave_sum(s) * (1.f / D) + EPS);
.Lnm_part2_p1:
	v_lshl_add_u32 v5, s2, 9, v0
	v_lshlrev_b32_e32 v6, 8, v5
	global_load_dwordx4 v[32:35], v6, s[12:13]
	global_load_dwordx4 v[36:39], v6, s[12:13] offset:16
	global_load_dwordx4 v[40:43], v6, s[12:13] offset:32
	global_load_dwordx4 v[44:47], v6, s[12:13] offset:48
	global_load_dwordx4 v[48:51], v6, s[12:13] offset:64
	global_load_dwordx4 v[52:55], v6, s[12:13] offset:80
	global_load_dwordx4 v[56:59], v6, s[12:13] offset:96
	global_load_dwordx4 v[60:63], v6, s[12:13] offset:112
	global_load_dwordx4 v[64:67], v6, s[12:13] offset:128
	global_load_dwordx4 v[68:71], v6, s[12:13] offset:144
	global_load_dwordx4 v[72:75], v6, s[12:13] offset:160
	global_load_dwordx4 v[76:79], v6, s[12:13] offset:176
	global_load_dwordx4 v[80:83], v6, s[12:13] offset:192
	global_load_dwordx4 v[84:87], v6, s[12:13] offset:208
	global_load_dwordx4 v[88:91], v6, s[12:13] offset:224
	global_load_dwordx4 v[92:95], v6, s[12:13] offset:240
	s_waitcnt vmcnt(0)
	v_add_f32_e32 v7, v32, v33
	v_add_f32_e32 v7, v7, v34
	v_add_f32_e32 v7, v7, v35
	v_add_f32_e32 v7, v7, v36
	v_add_f32_e32 v7, v7, v37
	v_add_f32_e32 v7, v7, v38
	v_add_f32_e32 v7, v7, v39
	v_add_f32_e32 v7, v7, v40
	v_add_f32_e32 v7, v7, v41
	v_add_f32_e32 v7, v7, v42
	v_add_f32_e32 v7, v7, v43
	v_add_f32_e32 v7, v7, v44
	v_add_f32_e32 v7, v7, v45
	v_add_f32_e32 v7, v7, v46
	v_add_f32_e32 v7, v7, v47
	v_add_f32_e32 v7, v7, v48
	v_add_f32_e32 v7, v7, v49
	v_add_f32_e32 v7, v7, v50
	v_add_f32_e32 v7, v7, v51
	v_add_f32_e32 v7, v7, v52
	v_add_f32_e32 v7, v7, v53
	v_add_f32_e32 v7, v7, v54
	v_add_f32_e32 v7, v7, v55
	v_add_f32_e32 v7, v7, v56
	v_add_f32_e32 v7, v7, v57
	v_add_f32_e32 v7, v7, v58
	v_add_f32_e32 v7, v7, v59
	v_add_f32_e32 v7, v7, v60
	v_add_f32_e32 v7, v7, v61
	v_add_f32_e32 v7, v7, v62
	v_add_f32_e32 v7, v7, v63
	v_add_f32_e32 v7, v7, v64
	v_add_f32_e32 v7, v7, v65
	v_add_f32_e32 v7, v7, v66
	v_add_f32_e32 v7, v7, v67
	v_add_f32_e32 v7, v7, v68
	v_add_f32_e32 v7, v7, v69
	v_add_f32_e32 v7, v7, v70
	v_add_f32_e32 v7, v7, v71
	v_add_f32_e32 v7, v7, v72
	v_add_f32_e32 v7, v7, v73
	v_add_f32_e32 v7, v7, v74
	v_add_f32_e32 v7, v7, v75
	v_add_f32_e32 v7, v7, v76
	v_add_f32_e32 v7, v7, v77
	v_add_f32_e32 v7, v7, v78
	v_add_f32_e32 v7, v7, v79
	v_add_f32_e32 v7, v7, v80
	v_add_f32_e32 v7, v7, v81
	v_add_f32_e32 v7, v7, v82
	v_add_f32_e32 v7, v7, v83
	v_add_f32_e32 v7, v7, v84
	v_add_f32_e32 v7, v7, v85
	v_add_f32_e32 v7, v7, v86
	v_add_f32_e32 v7, v7, v87
	v_add_f32_e32 v7, v7, v88
	v_add_f32_e32 v7, v7, v89
	v_add_f32_e32 v7, v7, v90
	v_add_f32_e32 v7, v7, v91
	v_add_f32_e32 v7, v7, v92
	v_add_f32_e32 v7, v7, v93
	v_add_f32_e32 v7, v7, v94
	v_add_f32_e32 v7, v7, v95
	v_fmamk_f32 v7, v7, 0x3a800000, v213
	v_rsq_f32_e32 v7, v7
	v_lshlrev_b32_e32 v10, 2, v5
	global_store_dword v10, v7, s[14:15]
.Lp1m_exit:
	s_movk_i32 s20, 0x4000
	s_lshl_b32 s21, s2, 3
	s_add_i32 s21, s21, s6
	s_addk_i32 s21, 0x4000
	s_branch .LBB0_88
.Lp1_orig:
	s_mov_b64 s[4:5], s[0:1]
	v_mov_b32_e32 v0, v209
	s_mov_b32 s12, s2
	v_readfirstlane_b32 s10, v0
	s_ashr_i32 s16, s10, 6
	s_mov_b32 s10, s2
	s_lshl_b32 s18, s10, 3
	s_mov_b32 s10, s3
	s_load_dwordx2 s[24:25], s[4:5], 0xe8
	s_add_i32 s18, s18, s16
	s_lshl_b32 s19, s10, 3
	s_mov_b32 s10, s3
	v_and_b32_e32 v2, 63, v0
	s_cmpk_lg_i32 s10, 0x100
	s_cselect_b64 s[10:11], -1, 0
	s_lshl_b32 s13, s12, 11
	v_lshlrev_b32_e32 v0, 3, v2
	s_and_b32 s23, s13, 0x3800
	s_and_b32 s34, s12, -8
	s_waitcnt lgkmcnt(0)
	v_lshl_add_u64 v[4:5], s[24:25], 0, v[0:1]
	v_lshlrev_b32_e32 v0, 4, v2
	s_cmpk_lt_i32 s18, 0x100
	v_lshl_add_u64 v[6:7], s[24:25], 0, v[0:1]
	s_mov_b64 s[24:25], 0x1a3ac000
	s_cselect_b64 s[12:13], -1, 0
	s_mov_b64 s[14:15], 0x25c8000
	v_lshl_add_u64 v[108:109], v[6:7], 0, s[24:25]
	s_mov_b64 s[24:25], 0x14a48000
	s_add_i32 s23, s16, s23
	s_add_i32 s21, s18, 0x4000
	v_lshl_add_u64 v[106:107], v[4:5], 0, s[14:15]
	s_xor_b64 s[14:15], s[6:7], -1
	v_lshl_add_u64 v[110:111], v[4:5], 0, s[24:25]
	s_add_i32 s23, s23, s34
	s_mov_b32 s24, 0
	v_lshlrev_b32_e32 v0, 4, v2
	s_mov_b32 s25, s18
	s_mov_b32 s34, 0
	s_movk_i32 s20, 0x4000
	s_mov_b32 s43, 0x800000
	s_branch .LBB0_62
; __device__ __forceinline__ unsigned cvt_pk_bf16(float lo, float hi) { unsigned r; asm volatile("v_cvt_pk_bf16_f32 %0, %1, %2" : "=v"(r) : "v"(lo), "v"(hi)); return r; }
; __device__ __forceinline__ void norm_phase(KP p, bool first, int nslab) {
;     ...
;         for (int j = 0; j < 4; ++j) s += (v[j][0] * v[j][0] + v[j][1] * v[j][1]) + (v[j][2] * v[j][2] + v[j][3] * v[j][3]);
;         const float rinv = rsqrtf(wave_sum(s) * (1.f / D) + EPS);
;         u32x2* o8 = (u32x2*)(XN + (size_t)m * D) + lane;
; #pragma unroll
;         for (int j = 0; j < 4; ++j) { u32x2 w; w.x = cvt_pk_bf16(v[j][0] * rinv, v[j][1] * rinv); w.y = cvt_pk_bf16(v[j][2] * rinv, v[j][3] * rinv); o8[64 * j] = w; }
.LBB0_60:
	s_waitcnt vmcnt(3)
	v_mov_b32_e32 v18, v16
	v_mov_b32_e32 v19, v14
	v_mov_b32_e32 v20, v17
	v_mov_b32_e32 v21, v15
	s_waitcnt vmcnt(2)
	v_mov_b32_e32 v22, v8
	v_mov_b32_e32 v23, v6
	v_pk_mul_f32 v[18:19], v[18:19], v[18:19]
	v_mov_b32_e32 v24, v9
	v_mov_b32_e32 v25, v7
	v_pk_fma_f32 v[18:19], v[20:21], v[20:21], v[18:19]
	v_pk_mul_f32 v[20:21], v[22:23], v[22:23]
	v_pk_add_f32 v[18:19], v[18:19], v[18:19] op_sel_hi:[0,1]
	v_pk_fma_f32 v[20:21], v[24:25], v[24:25], v[20:21]
	s_waitcnt vmcnt(1)
	v_mul_f32_e32 v18, v10, v10
	v_pk_add_f32 v[20:21], v[20:21], v[20:21] op_sel_hi:[0,1]
	v_mul_f32_e32 v25, v12, v12
	v_mul_f32_e32 v27, v13, v13
	s_waitcnt vmcnt(0)
	v_mov_b32_e32 v26, v5
	v_mov_b32_e32 v24, v5
	v_pk_fma_f32 v[22:23], v[10:11], v[10:11], v[18:19] op_sel_hi:[1,1,0]
	v_mul_f32_e32 v18, v2, v2
	v_mul_f32_e32 v20, v3, v3
	v_pk_add_f32 v[24:25], v[26:27], v[24:25]
	v_mul_f32_e32 v22, v4, v4
	v_pk_add_f32 v[18:19], v[20:21], v[18:19]
	v_mul_f32_e32 v20, v5, v5
	v_mov_b32_e32 v21, v25
	v_pk_add_f32 v[20:21], v[20:21], v[22:23]
	s_add_i32 s34, s34, 1
	v_pk_add_f32 v[18:19], v[20:21], v[18:19]
	v_xor_b32_e32 v20, 1, v207
	v_add_f32_e32 v18, v18, v19
	v_and_b32_e32 v19, 64, v207
	v_add_u32_e32 v19, 64, v19
	v_cmp_lt_i32_e32 vcc, v20, v19
	s_addk_i32 s24, 0x100
	s_add_i32 s25, s25, s19
	v_cndmask_b32_e32 v20, v207, v20, vcc
	v_lshlrev_b32_e32 v20, 2, v20
	ds_bpermute_b32 v20, v20, v18
	s_cmpk_eq_i32 s24, 0x900
	s_waitcnt lgkmcnt(0)
	v_add_f32_e32 v18, v18, v20
	v_xor_b32_e32 v20, 2, v207
	v_cmp_lt_i32_e32 vcc, v20, v19
	s_nop 1
	v_cndmask_b32_e32 v20, v207, v20, vcc
	v_lshlrev_b32_e32 v20, 2, v20
	ds_bpermute_b32 v20, v20, v18
	s_waitcnt lgkmcnt(0)
	v_add_f32_e32 v18, v18, v20
	v_xor_b32_e32 v20, 4, v207
	v_cmp_lt_i32_e32 vcc, v20, v19
	s_nop 1
	v_cndmask_b32_e32 v20, v207, v20, vcc
	v_lshlrev_b32_e32 v20, 2, v20
	ds_bpermute_b32 v20, v20, v18
	s_waitcnt lgkmcnt(0)
	v_add_f32_e32 v18, v18, v20
	v_xor_b32_e32 v20, 8, v207
	v_cmp_lt_i32_e32 vcc, v20, v19
	s_nop 1
	v_cndmask_b32_e32 v20, v207, v20, vcc
	v_lshlrev_b32_e32 v20, 2, v20
	ds_bpermute_b32 v20, v20, v18
	s_waitcnt lgkmcnt(0)
	v_add_f32_e32 v18, v18, v20
	v_xor_b32_e32 v20, 16, v207
	v_cmp_lt_i32_e32 vcc, v20, v19
	s_nop 1
	v_cndmask_b32_e32 v20, v207, v20, vcc
	v_lshlrev_b32_e32 v20, 2, v20
	ds_bpermute_b32 v20, v20, v18
	s_waitcnt lgkmcnt(0)
	v_add_f32_e32 v18, v18, v20
	v_xor_b32_e32 v20, 32, v207
	v_cmp_lt_i32_e32 vcc, v20, v19
	s_nop 1
	v_cndmask_b32_e32 v19, v207, v20, vcc
	v_lshlrev_b32_e32 v19, 2, v19
	ds_bpermute_b32 v19, v19, v18
	s_waitcnt lgkmcnt(0)
	v_add_f32_e32 v18, v18, v19
	v_fmamk_f32 v18, v18, 0x3a800000, v213
	v_mul_f32_e32 v19, 0x4b800000, v18
	v_cmp_gt_f32_e32 vcc, s43, v18
	s_nop 1
	v_cndmask_b32_e32 v18, v18, v19, vcc
	v_rsq_f32_e32 v18, v18
	s_nop 0
	v_mul_f32_e32 v19, 0x45800000, v18
	v_cndmask_b32_e32 v20, v18, v19, vcc
	v_readfirstlane_b32 s44, v110
	v_readfirstlane_b32 s45, v111
	s_mul_hi_u32 s16, s60, 0x800000
	v_mov_b32_e32 v30, s16
	v_add_u32_e32 v30, 0x4620000, v30
	s_nop 2
	global_store_dword v30, v20, s[44:45]
	v_mul_f32_e32 v14, v14, v20
	v_mul_f32_e32 v15, v15, v20
	v_lshl_add_u64 v[18:19], v[110:111], 0, s[60:61]
	v_cvt_pk_bf16_f32 v14, v14, v15
	v_mul_f32_e32 v15, v16, v20
	v_mul_f32_e32 v6, v6, v20
	v_mul_f32_e32 v7, v7, v20
	v_mul_f32_e32 v16, v17, v20
	v_cvt_pk_bf16_f32 v15, v15, v16
	global_store_dwordx2 v[18:19], v[14:15], off
	v_cvt_pk_bf16_f32 v6, v6, v7
	v_mul_f32_e32 v7, v8, v20
	v_mul_f32_e32 v8, v9, v20
	v_cvt_pk_bf16_f32 v7, v7, v8
	global_store_dwordx2 v[18:19], v[6:7], off offset:512
	v_mul_f32_e32 v6, v10, v20
	v_mul_f32_e32 v7, v11, v20
	v_cvt_pk_bf16_f32 v6, v6, v7
	v_mul_f32_e32 v7, v12, v20
	v_mul_f32_e32 v2, v2, v20
	v_mul_f32_e32 v3, v3, v20
	v_mul_f32_e32 v8, v13, v20
	v_cvt_pk_bf16_f32 v7, v7, v8
	global_store_dwordx2 v[18:19], v[6:7], off offset:1024
	v_cvt_pk_bf16_f32 v2, v2, v3
	v_mul_f32_e32 v3, v4, v20
	s_cselect_b64 s[60:61], -1, 0
	v_mul_f32_e32 v4, v5, v20
	v_cvt_pk_bf16_f32 v3, v3, v4
	global_store_dwordx2 v[18:19], v[2:3], off offset:1536

; __device__ __forceinline__ KP kargs() { KP k = (KP)__builtin_amdgcn_kernarg_segment_ptr(); asm volatile("" : "+s"(k)); return k; }
; __device__ __forceinline__ int bid_() { int t = blockIdx.x; asm volatile("" : "+s"(t)); return t; }
; #define PG8_WAIT_V(n) asm volatile("s_waitcnt vmcnt(" #n ")" ::: "memory")
; template <class Epi, bool ALIGN_EPI = true, bool SP2 = true>
; __device__ __forceinline__ void gemm_phase(LAS unsigned char* lds, const Gemm g, const Order& S, const Epi& E) {
;     ...
;     for (int i = 0; i < 2; ++i) { int R, C; stage_rc(tid * 16 + i * 8192, R, C); const int Rb = Epi::PERM ? ((R & ~31) + perm32(R & 31)) : R;
;         voffA[i] = (unsigned)(R * lda + C) * 2u; voffB[i] = (unsigned)(Rb * K + C) * 2u; }
;     const size_t kstep = (size_t)(BK * 2);
;     const size_t hstepA = (size_t)HALF * lda * 2, hstepB = (size_t)HALF * K * 2;
;     const size_t tstepA = 2 * hstepA, tstepB = 2 * hstepB;
;     const unsigned ldsw = (unsigned)wid * 1024u;
;     const int aoff = lds_byte(wr * 64 + fr, fq * 8), boff = lds_byte(wc * 32 + fr, fq * 8);
;     ...
;     Unit cur, nxt; int ui = 0;
;     if (!S.next(0, cur)) return;
;     f32x4 acc[2][2][4][2];
; #pragma unroll
;     for (int a = 0; a < 2; ++a)
; #pragma unroll
;         for (int b = 0; b < 2; ++b)
; #pragma unroll
;             for (int m = 0; m < 4; ++m)
; #pragma unroll
;                 for (int n = 0; n < 2; ++n) acc[a][b][m][n] = (f32x4){0.f, 0.f, 0.f, 0.f};
;     bf16x8 At[4][2], B0[2][2], B1[2][2];
;     const char* cA = (const char*)(cur.z ? g.A1 : g.A0) + (size_t)cur.pm * tstepA + (size_t)cur.kt0 * kstep; const char* cB = (const char*)(cur.z ? g.B1 : g.B0) + (size_t)cur.pn * tstepB + (size_t)cur.kt0 * kstep;
;     if constexpr (SP2) {
;         PG8_STAGE(PG8_SB(0, 0), cB, voffB); PG8_STAGE(PG8_SB(0, 1), cB + hstepB, voffB); PG8_STAGE(PG8_SA(0, 0), cA, voffA); PG8_STAGE(PG8_SA(0, 1), cA + hstepA, voffA);
;         if (wr == 1) PG8_BAR;
;         PG8_WAIT_V(2); PG8_BAR;
;         PG8_STAGE(PG8_SB(1, 0), cB + kstep, voffB); PG8_STAGE(PG8_SA(1, 0), cA + kstep, voffA); PG8_STAGE(PG8_SB(1, 1), cB + hstepB + kstep, voffB);
; __global__ void __launch_bounds__(512, 2) fwd_megakernel(Params pv) {
;     ...
;         { KP p = kargs(); unsigned char* ws = p->ws; pg8::Gemm g{(const bf16_t*)(ws + WS_R2), nullptr, (const bf16_t*)(ws + WS_WIN), nullptr, D, D}; pg8::Order S; S.init(M, DIN, D, gdim_(), bid_(), 1, 0);
.LBB0_148:
	s_mov_b32 s57, s17
	s_mul_hi_u32 s1, s56, 0x3000
	s_mul_i32 s43, s56, 0x3000
	s_andn2_b64 vcc, exec, s[10:11]
	s_lshl_b64 s[84:85], s[56:57], 18
	s_cbranch_vccnz .LBB0_206
	v_ashrrev_i32_e32 v3, 31, v0
	v_lshrrev_b32_e32 v3, 26, v3
	v_add_u32_e32 v3, v0, v3
	v_ashrrev_i32_e32 v10, 6, v3
	v_bfe_i32 v3, v0, 27, 1
	v_lshlrev_b32_e32 v2, 4, v0
	v_lshrrev_b32_e32 v3, 22, v3
	v_add_u32_e32 v3, v2, v3
	v_and_b32_e32 v3, 0xfffffc00, v3
	v_sub_u32_e32 v3, v2, v3
	v_lshrrev_b32_e32 v4, 4, v3
	v_bitop3_b32 v4, v4, v3, 32 bitop3:0x6c
	v_ashrrev_i32_e32 v3, 31, v3
	v_lshrrev_b32_e32 v3, 26, v3
	v_add_u32_e32 v3, v4, v3
	v_ashrrev_i32_e32 v11, 6, v3
	v_lshlrev_b32_e32 v5, 3, v10
	v_mul_i32_i24_e32 v6, 64, v11
	v_and_b32_e32 v5, -16, v5
	v_sub_u32_e32 v4, v4, v6
	v_add_u32_e32 v3, v11, v5
	v_lshlrev_b32_e32 v5, 5, v10
	v_ashrrev_i16_sdwa v4, v218, sext(v4) dst_sel:DWORD dst_unused:UNUSED_PAD src0_sel:DWORD src1_sel:BYTE_0
	v_and_b32_e32 v5, 32, v5
	v_bfe_i32 v12, v4, 0, 16
	v_and_b32_e32 v7, 3, v11
	s_mov_b32 s0, 0x1fffe0
	v_add_lshl_u32 v5, v5, v12, 1
	v_add_u32_e32 v2, 0x2000, v2
	v_lshlrev_b32_e32 v4, 1, v3
	v_lshrrev_b32_e32 v6, 2, v3
	v_and_or_b32 v7, v3, s0, v7
	v_lshl_add_u32 v162, v3, 11, v5
	v_ashrrev_i32_e32 v3, 31, v2
	v_lshrrev_b32_e32 v3, 22, v3
	v_add_u32_e32 v3, v2, v3
	v_ashrrev_i32_e32 v13, 10, v3
	v_mul_i32_i24_e32 v3, 0x400, v13
	s_ashr_i32 s10, s46, 6
	v_sub_u32_e32 v2, v2, v3
	v_and_b32_e32 v4, 24, v4
	v_and_b32_e32 v6, 4, v6
	v_lshrrev_b32_e32 v3, 4, v2
	s_ashr_i32 s11, s46, 8
	s_lshl_b32 s21, s10, 10
	v_or3_b32 v4, v7, v6, v4
	v_bitop3_b32 v2, v3, v2, 32 bitop3:0x6c
	s_waitcnt lgkmcnt(0)
	s_add_u32 s23, s60, 0x25c8000
	v_lshl_add_u32 v164, v4, 11, v5
	v_ashrrev_i32_e32 v4, 31, v2
	s_addc_u32 s24, s61, 0
	s_ashr_i32 s97, s96, 31
	v_lshrrev_b32_e32 v4, 26, v4
	s_lshl_b64 s[12:13], s[96:97], 19
	v_add_u32_e32 v4, v2, v4
	s_add_u32 s12, s23, s12
	v_lshlrev_b32_e32 v3, 3, v13
	v_ashrrev_i32_e32 v14, 6, v4
	v_and_b32_e32 v4, 0xc0, v4
	s_addc_u32 s13, s24, s13
	s_ashr_i32 s95, s94, 31
	v_and_b32_e32 v3, -16, v3
	v_sub_u32_e32 v2, v2, v4
	s_lshl_b64 s[14:15], s[94:95], 19
	v_add_u32_e32 v3, v14, v3
	v_ashrrev_i16_sdwa v2, v218, sext(v2) dst_sel:DWORD dst_unused:UNUSED_PAD src0_sel:DWORD src1_sel:BYTE_0
	s_add_u32 s14, s60, s14
	v_lshlrev_b32_e32 v5, 5, v13
	v_bfe_i32 v15, v2, 0, 16
	v_lshlrev_b32_e32 v2, 1, v3
	v_lshrrev_b32_e32 v4, 2, v3
	v_and_b32_e32 v6, 3, v14
	s_addc_u32 s15, s61, s15
	s_add_i32 s25, s21, 0
	v_and_b32_e32 v5, 32, v5
	v_and_b32_e32 v2, 24, v2
	v_and_b32_e32 v4, 4, v4
	v_and_or_b32 v6, v3, s0, v6
	s_add_i32 m0, s25, 0x10000
	v_or3_b32 v2, v6, v4, v2
	v_add_lshl_u32 v4, v5, v15, 1
	global_load_lds_dwordx4 v164, s[14:15]
	s_add_i32 m0, s25, 0x12000
	v_lshl_add_u32 v168, v2, 11, v4
	s_add_u32 s34, s14, 0x40000
	global_load_lds_dwordx4 v168, s[14:15]
	s_addc_u32 s35, s15, 0
	s_add_i32 m0, s25, 0x14000
	v_lshl_add_u32 v166, v3, 11, v4
	global_load_lds_dwordx4 v164, s[34:35]
	s_add_i32 m0, s25, 0x16000
	v_mov_b32_e32 v165, v1
	global_load_lds_dwordx4 v168, s[34:35]
	s_add_i32 s34, s25, 0x2000
	s_mov_b32 m0, s25
	s_add_u32 s44, s12, 0x40000
	global_load_lds_dwordx4 v162, s[12:13]
	s_mov_b32 m0, s34
	s_addc_u32 s45, s13, 0
	s_add_i32 s35, s25, 0x4000
	global_load_lds_dwordx4 v166, s[12:13]
	s_mov_b32 m0, s35
	s_add_i32 s40, s25, 0x6000
	global_load_lds_dwordx4 v162, s[44:45]
	s_mov_b32 m0, s40
	v_mov_b32_e32 v169, v1
	global_load_lds_dwordx4 v166, s[44:45]
	v_mov_b32_e32 v163, v1
	v_mov_b32_e32 v167, v1
	s_cmp_eq_u32 s11, 1
	v_lshl_add_u64 v[8:9], s[14:15], 0, v[164:165]
	v_lshl_add_u64 v[6:7], s[14:15], 0, v[168:169]
	v_lshl_add_u64 v[2:3], s[12:13], 0, v[162:163]
	s_cselect_b64 s[62:63], -1, 0
	s_cmp_lg_u32 s11, 1
	v_lshl_add_u64 v[4:5], s[12:13], 0, v[166:167]
	s_cbranch_scc1 .LBB0_151
	s_barrier

;     __device__ __forceinline__ void operator()(const f32x4 (&acc)[2][2][4][2], const Unit& u, int wr, int wc, int fr, int fq) const {
;         const int rbase = u.pm * BM + wr * 64 + fr;
;         if (u.pn >= 16) {
.LBB0_164:
	s_lshl_b32 s14, s96, 8
	s_add_i32 s14, s14, s42
	s_lshl_b32 s14, s14, 2
	s_add_u32 s12, s64, 0x129a0000
	s_addc_u32 s13, s65, 0
	s_add_u32 s12, s12, s14
	s_addc_u32 s13, s13, 0
	v_lshlrev_b32_e32 v191, 2, v184
	global_load_dword v176, v191, s[12:13]
	global_load_dword v177, v191, s[12:13] offset:64
	global_load_dword v178, v191, s[12:13] offset:128
	global_load_dword v179, v191, s[12:13] offset:192
	global_load_dword v180, v191, s[12:13] offset:512
	global_load_dword v181, v191, s[12:13] offset:576
	global_load_dword v182, v191, s[12:13] offset:640
	global_load_dword v183, v191, s[12:13] offset:704
	s_waitcnt vmcnt(0)
	v_mul_f32_e32 v126, v176, v126
	v_mul_f32_e32 v127, v176, v127
	v_mul_f32_e32 v128, v176, v128
	v_mul_f32_e32 v129, v176, v129
	v_mul_f32_e32 v122, v176, v122
	v_mul_f32_e32 v123, v176, v123
	v_mul_f32_e32 v124, v176, v124
	v_mul_f32_e32 v125, v176, v125
	v_mul_f32_e32 v118, v176, v118
	v_mul_f32_e32 v119, v176, v119
	v_mul_f32_e32 v120, v176, v120
	v_mul_f32_e32 v121, v176, v121
	v_mul_f32_e32 v114, v176, v114
	v_mul_f32_e32 v115, v176, v115
	v_mul_f32_e32 v116, v176, v116
	v_mul_f32_e32 v117, v176, v117
	v_mul_f32_e32 v110, v177, v110
	v_mul_f32_e32 v111, v177, v111
	v_mul_f32_e32 v112, v177, v112
	v_mul_f32_e32 v113, v177, v113
	v_mul_f32_e32 v106, v177, v106
	v_mul_f32_e32 v107, v177, v107
	v_mul_f32_e32 v108, v177, v108
	v_mul_f32_e32 v109, v177, v109
	v_mul_f32_e32 v102, v177, v102
	v_mul_f32_e32 v103, v177, v103
	v_mul_f32_e32 v104, v177, v104
	v_mul_f32_e32 v105, v177, v105
	v_mul_f32_e32 v98, v177, v98
	v_mul_f32_e32 v99, v177, v99
	v_mul_f32_e32 v100, v177, v100
	v_mul_f32_e32 v101, v177, v101
	v_mul_f32_e32 v94, v178, v94
	v_mul_f32_e32 v95, v178, v95
	v_mul_f32_e32 v96, v178, v96
	v_mul_f32_e32 v97, v178, v97
	v_mul_f32_e32 v90, v178, v90
	v_mul_f32_e32 v91, v178, v91
	v_mul_f32_e32 v92, v178, v92
	v_mul_f32_e32 v93, v178, v93
	v_mul_f32_e32 v86, v178, v86
	v_mul_f32_e32 v87, v178, v87
	v_mul_f32_e32 v88, v178, v88
	v_mul_f32_e32 v89, v178, v89
	v_mul_f32_e32 v82, v178, v82
	v_mul_f32_e32 v83, v178, v83
	v_mul_f32_e32 v84, v178, v84
	v_mul_f32_e32 v85, v178, v85
	v_mul_f32_e32 v78, v179, v78
	v_mul_f32_e32 v79, v179, v79
	v_mul_f32_e32 v80, v179, v80
	v_mul_f32_e32 v81, v179, v81
	v_mul_f32_e32 v74, v179, v74
	v_mul_f32_e32 v75, v179, v75
	v_mul_f32_e32 v76, v179, v76
	v_mul_f32_e32 v77, v179, v77
	v_mul_f32_e32 v70, v179, v70
	v_mul_f32_e32 v71, v179, v71
	v_mul_f32_e32 v72, v179, v72
	v_mul_f32_e32 v73, v179, v73
	v_mul_f32_e32 v66, v179, v66
	v_mul_f32_e32 v67, v179, v67
	v_mul_f32_e32 v68, v179, v68
	v_mul_f32_e32 v69, v179, v69
	v_mul_f32_e32 v62, v180, v62
	v_mul_f32_e32 v63, v180, v63
	v_mul_f32_e32 v64, v180, v64
	v_mul_f32_e32 v65, v180, v65
	v_mul_f32_e32 v58, v180, v58
	v_mul_f32_e32 v59, v180, v59
	v_mul_f32_e32 v60, v180, v60
	v_mul_f32_e32 v61, v180, v61
	v_mul_f32_e32 v54, v180, v54
	v_mul_f32_e32 v55, v180, v55
	v_mul_f32_e32 v56, v180, v56
	v_mul_f32_e32 v57, v180, v57
	v_mul_f32_e32 v46, v180, v46
	v_mul_f32_e32 v47, v180, v47
	v_mul_f32_e32 v48, v180, v48
	v_mul_f32_e32 v49, v180, v49
	v_mul_f32_e32 v50, v181, v50
	v_mul_f32_e32 v51, v181, v51
	v_mul_f32_e32 v52, v181, v52
	v_mul_f32_e32 v53, v181, v53
	v_mul_f32_e32 v42, v181, v42
	v_mul_f32_e32 v43, v181, v43
	v_mul_f32_e32 v44, v181, v44
	v_mul_f32_e32 v45, v181, v45
	v_mul_f32_e32 v38, v181, v38
	v_mul_f32_e32 v39, v181, v39
	v_mul_f32_e32 v40, v181, v40
	v_mul_f32_e32 v41, v181, v41
	v_mul_f32_e32 v30, v181, v30
	v_mul_f32_e32 v31, v181, v31
	v_mul_f32_e32 v32, v181, v32
	v_mul_f32_e32 v33, v181, v33
	v_mul_f32_e32 v34, v182, v34
	v_mul_f32_e32 v35, v182, v35
	v_mul_f32_e32 v36, v182, v36
	v_mul_f32_e32 v37, v182, v37
	v_mul_f32_e32 v26, v182, v26
	v_mul_f32_e32 v27, v182, v27
	v_mul_f32_e32 v28, v182, v28
	v_mul_f32_e32 v29, v182, v29
	v_mul_f32_e32 v22, v182, v22
	v_mul_f32_e32 v23, v182, v23
	v_mul_f32_e32 v24, v182, v24
	v_mul_f32_e32 v25, v182, v25
	v_mul_f32_e32 v14, v182, v14
	v_mul_f32_e32 v15, v182, v15
	v_mul_f32_e32 v16, v182, v16
	v_mul_f32_e32 v17, v182, v17
	v_mul_f32_e32 v18, v183, v18
	v_mul_f32_e32 v19, v183, v19
	v_mul_f32_e32 v20, v183, v20
	v_mul_f32_e32 v21, v183, v21
	v_mul_f32_e32 v10, v183, v10
	v_mul_f32_e32 v11, v183, v11
	v_mul_f32_e32 v12, v183, v12
	v_mul_f32_e32 v13, v183, v13
	v_mul_f32_e32 v6, v183, v6
	v_mul_f32_e32 v7, v183, v7
	v_mul_f32_e32 v8, v183, v8
	v_mul_f32_e32 v9, v183, v9
	v_mul_f32_e32 v2, v183, v2
	v_mul_f32_e32 v3, v183, v3
	v_mul_f32_e32 v4, v183, v4
	v_mul_f32_e32 v5, v183, v5
	s_lshl_b32 s14, s96, 8
	s_add_i32 s55, s14, s42
	v_or_b32_e32 v190, s55, v184
	s_cmp_lt_i32 s94, 16
	s_mov_b64 s[12:13], -1
	s_cbranch_scc0 .LBB0_195
;     __device__ __forceinline__ void operator()(const f32x4 (&acc)[2][2][4][2], const Unit& u, int wr, int wc, int fr, int fq) const {
;     ...
;         const int xch = u.pn * 64 + wc * 16 + 4 * fq;
;         const f32x4 w0 = *(const f32x4*)(cw + xch), w1 = *(const f32x4*)(cw + D + xch), w2 = *(const f32x4*)(cw + 2 * D + xch);
;         const f32x4 bm = *(const f32x4*)(bias + u.pn * BM + HALF + wc * 32 + 8 * fq + 4);
;         const int b0 = (u.pm * BM) / TP, rb = (b0 + 1) * TP;
; #pragma unroll
;         for (int ai = 0; ai < 2; ++ai) {
;             f32x4 z[4];
; #pragma unroll
;             for (int m = 0; m < 4; ++m) z[m] = acc[ai][0][m][1] * acc[ai][1][m][0];
;             if (u.pm == 64 && ai == 1) {
; #pragma unroll
;                 for (int m = 0; m < 4; ++m) { const int r = rbase + HALF + 16 * m, sb = r - MP;
;                     const f32x4 z2 = *(const f32x4*)(st + (size_t)(sb * 2) * D + xch), z1 = *(const f32x4*)(st + (size_t)(sb * 2 + 1) * D + xch);
;                     const f32x4 ua = acc[1][0][m][0] * (w0 * z2 + w1 * z1 + w2 * z[m]), ma = acc[1][1][m][1] + bm;
;                     bf16_t* rowp = O + (size_t)r * DP + xch;
;                     u32x2 a; a.x = cvt_pk_bf16(ua[0], ua[1]); a.y = cvt_pk_bf16(ua[2], ua[3]); *(u32x2*)(rowp + C_UA) = a;
;                     u32x2 g; g.x = cvt_pk_bf16(ma[0], ma[1]); g.y = cvt_pk_bf16(ma[2], ma[3]); *(u32x2*)(rowp + C_MA) = g;
;                     *(f32x4*)(outs + (size_t)(sb * 2) * D + xch) = z1; *(f32x4*)(outs + (size_t)(sb * 2 + 1) * D + xch) = z[m]; }
;             } else {
; #pragma unroll
;                 for (int m = 0; m < 4; ++m) { const int r = rbase + ai * HALF + 16 * m; const bool hi = r >= rb; const int t = hi ? r - rb : r - b0 * TP, b = hi ? b0 + 1 : b0;
;                     f32x4 z1, z2;
; #pragma unroll
;                     for (int e = 0; e < 4; ++e) { float a1 = dpp_ror1(z[m][e]), a2 = dpp_ror2(z[m][e]);
;                         if (m > 0) { const float xp = z[m > 0 ? m - 1 : 0][e]; const float p1 = dpp_ror1(xp), p2 = dpp_ror2(xp); a1 = fr >= 1 ? a1 : p1; a2 = fr >= 2 ? a2 : p2; }
;                         if (t == 0) a1 = 0.f; if (t <= 1) a2 = 0.f; z1[e] = a1; z2[e] = a2; }
;                     const f32x4 gb = acc[ai][0][m][0], ua = gb * (w0 * z2 + w1 * z1 + w2 * z[m]), ma = acc[ai][1][m][1] + bm;
;                     bf16_t* rowp = O + (size_t)r * DP + xch;
	v_lshl_or_b32 v176, s94, 6, v186
	v_ashrrev_i32_e32 v177, 31, v176
	v_lshlrev_b64 v[178:179], 2, v[176:177]
	v_lshl_add_u64 v[130:131], s[72:73], 0, v[178:179]
	s_lshl_b32 s12, s94, 8
	v_lshl_add_u64 v[132:133], s[82:83], 0, v[178:179]
	global_load_dwordx4 v[134:137], v[130:131], off
	global_load_dwordx4 v[142:145], v[132:133], off
	v_lshl_add_u64 v[130:131], s[84:85], 0, v[178:179]
	s_ashr_i32 s13, s12, 31
	global_load_dwordx4 v[138:141], v[130:131], off
	v_lshl_add_u64 v[130:131], s[12:13], 2, v[170:171]
	global_load_dwordx4 v[130:133], v[130:131], off offset:528
	s_mul_hi_i32 s12, s14, 0xfe03f81
	s_lshr_b32 s13, s12, 31
	s_ashr_i32 s50, s12, 7
	s_add_i32 s50, s50, s13
	s_add_i32 s51, s50, 1
	s_mul_i32 s52, s51, 0x810
	s_mul_i32 s53, s50, 0xfffff7f0
	s_sub_i32 s54, 0, s52
	v_mov_b32_e32 v0, s54
	v_mov_b32_e32 v150, s53
	v_cmp_gt_i32_e32 vcc, s52, v190
	v_pk_mul_f32 v[148:149], v[120:121], v[124:125]
	v_pk_mul_f32 v[146:147], v[118:119], v[122:123]
	v_cndmask_b32_e32 v0, v0, v150, vcc
	v_mov_b64_e32 v[150:151], s[64:65]
	v_mov_b32_e32 v152, v1
	v_mov_b32_e32 v155, v1
	v_mov_b32_e32 v153, v1
	v_mov_b32_e32 v157, v1
	v_mov_b32_e32 v154, v1
	v_mov_b32_e32 v158, v1
	v_mov_b32_e32 v156, v1
	v_mov_b32_e32 v159, v1
	v_mad_i64_i32 v[150:151], s[12:13], v190, s33, v[150:151]
	v_add_u32_e32 v0, v0, v190
	v_mov_b32_dpp v152, v146 row_ror:1 row_mask:0xf bank_mask:0xf
	v_mov_b32_dpp v155, v146 row_ror:2 row_mask:0xf bank_mask:0xf
	v_mov_b32_dpp v153, v147 row_ror:1 row_mask:0xf bank_mask:0xf
	v_mov_b32_dpp v157, v147 row_ror:2 row_mask:0xf bank_mask:0xf
	v_mov_b32_dpp v154, v148 row_ror:1 row_mask:0xf bank_mask:0xf
	v_mov_b32_dpp v158, v148 row_ror:2 row_mask:0xf bank_mask:0xf
	v_mov_b32_dpp v156, v149 row_ror:1 row_mask:0xf bank_mask:0xf
	v_mov_b32_dpp v159, v149 row_ror:2 row_mask:0xf bank_mask:0xf
	v_lshl_add_u64 v[150:151], v[176:177], 1, v[150:151]
	s_and_saveexec_b64 s[14:15], s[4:5]
	s_cbranch_execz .LBB0_167
	v_cmp_gt_i32_e64 s[12:13], 2, v0
	s_nop 1
	v_cndmask_b32_e64 v160, v155, 0, s[12:13]
	v_cndmask_b32_e64 v161, v157, 0, s[12:13]
	v_cndmask_b32_e64 v158, v158, 0, s[12:13]
	v_cndmask_b32_e64 v159, v159, 0, s[12:13]
	v_cmp_eq_u32_e64 s[12:13], 0, v0
	s_waitcnt vmcnt(0)
	v_pk_mul_f32 v[158:159], v[136:137], v[158:159]
	v_cndmask_b32_e64 v152, v152, 0, s[12:13]
	v_cndmask_b32_e64 v153, v153, 0, s[12:13]
	v_cndmask_b32_e64 v155, v156, 0, s[12:13]
	v_pk_mul_f32 v[156:157], v[134:135], v[160:161]
	v_cndmask_b32_e64 v154, v154, 0, s[12:13]
	v_pk_fma_f32 v[152:153], v[142:143], v[152:153], v[156:157]
	v_pk_fma_f32 v[154:155], v[144:145], v[154:155], v[158:159]
	v_pk_fma_f32 v[152:153], v[146:147], v[138:139], v[152:153]
	v_pk_fma_f32 v[154:155], v[148:149], v[140:141], v[154:155]
	v_pk_mul_f32 v[152:153], v[126:127], v[152:153]
	v_pk_mul_f32 v[154:155], v[128:129], v[154:155]
	v_cvt_pk_bf16_f32 v152, v152, v153
	s_nop 0
	v_cvt_pk_bf16_f32 v153, v154, v155
	global_store_dwordx2 v[150:151], v[152:153], off

; __device__ __forceinline__ u32x4 pack8(const float (&f)[8]) { u32x4 o; o.x = cvt_pk_bf16(f[0], f[1]); o.y = cvt_pk_bf16(f[2], f[3]); o.z = cvt_pk_bf16(f[4], f[5]); o.w = cvt_pk_bf16(f[6], f[7]); return o; }
;     __device__ __forceinline__ void operator()(const f32x4 (&acc)[2][2][4][2], const Unit& u, int wr, int wc, int fr, int fq) const {
;         const int row0 = u.pm * BM + wr * 64 + fr, col0 = u.pn * BM + wc * 32 + 8 * fq;
;         if (u.nkt == ntFull) {
; #pragma unroll
;             for (int ai = 0; ai < 2; ++ai)
; #pragma unroll
;                 for (int m = 0; m < 4; ++m) { bf16_t* rowp = X + (size_t)(row0 + ai * HALF + m * 16) * D + col0;
; #pragma unroll
;                     for (int bj = 0; bj < 2; ++bj) { u32x4* p = (u32x4*)(rowp + bj * HALF); float x[8]; unpack8(*p, x); const f32x4 a0 = acc[ai][bj][m][0], a1 = acc[ai][bj][m][1];
; #pragma unroll
;                         for (int e = 0; e < 4; ++e) { x[e] += a0[e]; x[4 + e] += a1[e]; }
;                         *p = pack8(x); }
;                     asm volatile("" ::: "memory"); }
.LBB0_728:
	v_lshl_add_u32 v252, s53, 8, v136
	v_lshlrev_b32_e32 v162, 11, v252
	v_lshl_add_u32 v162, v158, 1, v162
	v_lshrrev_b32_e32 v163, 8, v158
	v_bfe_u32 v248, v158, 3, 4
	v_lshl_or_b32 v163, v163, 4, v248
	v_lshlrev_b32_e32 v163, 2, v163
	v_lshl_add_u32 v163, v252, 8, v163
	s_mov_b32 s70, s8
	s_mov_b32 s71, s9
	global_load_dwordx4 v[164:167], v162, s[70:71]
	global_load_dwordx4 v[168:171], v162, s[70:71] offset:256
	s_add_u32 s70, s70, 0x8000
	s_addc_u32 s71, s71, 0
	global_load_dwordx4 v[172:175], v162, s[70:71]
	global_load_dwordx4 v[176:179], v162, s[70:71] offset:256
	s_add_u32 s70, s70, 0x8000
	s_addc_u32 s71, s71, 0
	global_load_dwordx4 v[180:183], v162, s[70:71]
	global_load_dwordx4 v[184:187], v162, s[70:71] offset:256
	s_add_u32 s70, s70, 0x8000
	s_addc_u32 s71, s71, 0
	global_load_dwordx4 v[188:191], v162, s[70:71]
	global_load_dwordx4 v[192:195], v162, s[70:71] offset:256
	s_add_u32 s70, s70, 0x28000
	s_addc_u32 s71, s71, 0
	global_load_dwordx4 v[196:199], v162, s[70:71]
	global_load_dwordx4 v[200:203], v162, s[70:71] offset:256
	s_add_u32 s70, s70, 0x8000
	s_addc_u32 s71, s71, 0
	global_load_dwordx4 v[224:227], v162, s[70:71]
	global_load_dwordx4 v[228:231], v162, s[70:71] offset:256
	s_add_u32 s70, s70, 0x8000
	s_addc_u32 s71, s71, 0
	global_load_dwordx4 v[232:235], v162, s[70:71]
	global_load_dwordx4 v[236:239], v162, s[70:71] offset:256
	s_add_u32 s70, s70, 0x8000
	s_addc_u32 s71, s71, 0
	global_load_dwordx4 v[240:243], v162, s[70:71]
	global_load_dwordx4 v[244:247], v162, s[70:71] offset:256
	s_mov_b32 s70, s8
	s_mov_b32 s71, s9
	s_add_u32 s72, s8, 0x16680000
	s_addc_u32 s73, s9, 0
	s_waitcnt vmcnt(15)
	v_lshlrev_b32_e32 v248, 16, v164
	v_lshlrev_b32_e32 v249, 16, v165
	v_lshlrev_b32_e32 v250, 16, v166
	v_lshlrev_b32_e32 v251, 16, v167
	v_and_b32_e32 v164, 0xffff0000, v164
	v_and_b32_e32 v165, 0xffff0000, v165
	v_and_b32_e32 v166, 0xffff0000, v166
	v_and_b32_e32 v167, 0xffff0000, v167
	v_add_f32_e32 v126, v126, v248
	v_add_f32_e32 v127, v127, v164
	v_add_f32_e32 v128, v128, v249
	v_add_f32_e32 v129, v129, v165
	v_add_f32_e32 v122, v122, v250
	v_add_f32_e32 v123, v123, v166
	v_add_f32_e32 v124, v124, v251
	v_add_f32_e32 v125, v125, v167
	v_mul_f32_e32 v158, v126, v126
	v_fmac_f32_e32 v158, v127, v127
	v_fmac_f32_e32 v158, v128, v128
	v_fmac_f32_e32 v158, v129, v129
	v_fmac_f32_e32 v158, v122, v122
	v_fmac_f32_e32 v158, v123, v123
	v_fmac_f32_e32 v158, v124, v124
	v_fmac_f32_e32 v158, v125, v125
	v_cvt_pk_bf16_f32 v164, v126, v127
	v_cvt_pk_bf16_f32 v165, v128, v129
	v_cvt_pk_bf16_f32 v166, v122, v123
	v_cvt_pk_bf16_f32 v167, v124, v125
	global_store_dwordx4 v162, v[164:167], s[70:71]
	s_waitcnt vmcnt(15)
	v_lshlrev_b32_e32 v248, 16, v168
	v_lshlrev_b32_e32 v249, 16, v169
	v_lshlrev_b32_e32 v250, 16, v170
	v_lshlrev_b32_e32 v251, 16, v171
	v_and_b32_e32 v168, 0xffff0000, v168
	v_and_b32_e32 v169, 0xffff0000, v169
	v_and_b32_e32 v170, 0xffff0000, v170
	v_and_b32_e32 v171, 0xffff0000, v171
	v_add_f32_e32 v118, v118, v248
	v_add_f32_e32 v119, v119, v168
	v_add_f32_e32 v120, v120, v249
	v_add_f32_e32 v121, v121, v169
	v_add_f32_e32 v114, v114, v250
	v_add_f32_e32 v115, v115, v170
	v_add_f32_e32 v116, v116, v251
	v_add_f32_e32 v117, v117, v171
	v_fmac_f32_e32 v158, v118, v118
	v_fmac_f32_e32 v158, v119, v119
	v_fmac_f32_e32 v158, v120, v120
	v_fmac_f32_e32 v158, v121, v121
	v_fmac_f32_e32 v158, v114, v114
	v_fmac_f32_e32 v158, v115, v115
	v_fmac_f32_e32 v158, v116, v116
	v_fmac_f32_e32 v158, v117, v117
	v_cvt_pk_bf16_f32 v168, v118, v119
	v_cvt_pk_bf16_f32 v169, v120, v121
	v_cvt_pk_bf16_f32 v170, v114, v115
	v_cvt_pk_bf16_f32 v171, v116, v117
	global_store_dwordx4 v162, v[168:171], s[70:71] offset:256
	global_store_dword v163, v158, s[72:73]
	s_add_u32 s70, s70, 0x8000
	s_addc_u32 s71, s71, 0
	s_add_u32 s72, s72, 0x1000
	s_addc_u32 s73, s73, 0
	s_waitcnt vmcnt(15)
	v_lshlrev_b32_e32 v248, 16, v172
	v_lshlrev_b32_e32 v249, 16, v173
	v_lshlrev_b32_e32 v250, 16, v174
	v_lshlrev_b32_e32 v251, 16, v175
	v_and_b32_e32 v172, 0xffff0000, v172
	v_and_b32_e32 v173, 0xffff0000, v173
	v_and_b32_e32 v174, 0xffff0000, v174
	v_and_b32_e32 v175, 0xffff0000, v175
	v_add_f32_e32 v110, v110, v248
	v_add_f32_e32 v111, v111, v172
	v_add_f32_e32 v112, v112, v249
	v_add_f32_e32 v113, v113, v173
	v_add_f32_e32 v106, v106, v250
	v_add_f32_e32 v107, v107, v174
	v_add_f32_e32 v108, v108, v251
	v_add_f32_e32 v109, v109, v175
	v_mul_f32_e32 v159, v110, v110
	v_fmac_f32_e32 v159, v111, v111
	v_fmac_f32_e32 v159, v112, v112
	v_fmac_f32_e32 v159, v113, v113
	v_fmac_f32_e32 v159, v106, v106
	v_fmac_f32_e32 v159, v107, v107
	v_fmac_f32_e32 v159, v108, v108
	v_fmac_f32_e32 v159, v109, v109
	v_cvt_pk_bf16_f32 v172, v110, v111
	v_cvt_pk_bf16_f32 v173, v112, v113
	v_cvt_pk_bf16_f32 v174, v106, v107
	v_cvt_pk_bf16_f32 v175, v108, v109
	global_store_dwordx4 v162, v[172:175], s[70:71]
	s_waitcnt vmcnt(15)
	v_lshlrev_b32_e32 v248, 16, v176
	v_lshlrev_b32_e32 v249, 16, v177
	v_lshlrev_b32_e32 v250, 16, v178
	v_lshlrev_b32_e32 v251, 16, v179
	v_and_b32_e32 v176, 0xffff0000, v176
	v_and_b32_e32 v177, 0xffff0000, v177
	v_and_b32_e32 v178, 0xffff0000, v178
	v_and_b32_e32 v179, 0xffff0000, v179
	v_add_f32_e32 v102, v102, v248
	v_add_f32_e32 v103, v103, v176
	v_add_f32_e32 v104, v104, v249
	v_add_f32_e32 v105, v105, v177
	v_add_f32_e32 v98, v98, v250
	v_add_f32_e32 v99, v99, v178
	v_add_f32_e32 v100, v100, v251
	v_add_f32_e32 v101, v101, v179
	v_fmac_f32_e32 v159, v102, v102
	v_fmac_f32_e32 v159, v103, v103
	v_fmac_f32_e32 v159, v104, v104
	v_fmac_f32_e32 v159, v105, v105
	v_fmac_f32_e32 v159, v98, v98
	v_fmac_f32_e32 v159, v99, v99
	v_fmac_f32_e32 v159, v100, v100
	v_fmac_f32_e32 v159, v101, v101
	v_cvt_pk_bf16_f32 v176, v102, v103
	v_cvt_pk_bf16_f32 v177, v104, v105
	v_cvt_pk_bf16_f32 v178, v98, v99
	v_cvt_pk_bf16_f32 v179, v100, v101
	global_store_dwordx4 v162, v[176:179], s[70:71] offset:256
	global_store_dword v163, v159, s[72:73]
	s_add_u32 s70, s70, 0x8000
	s_addc_u32 s71, s71, 0
	s_add_u32 s72, s72, 0x1000
	s_addc_u32 s73, s73, 0
	s_waitcnt vmcnt(15)
; __device__ __forceinline__ u32x4 pack8(const float (&f)[8]) { u32x4 o; o.x = cvt_pk_bf16(f[0], f[1]); o.y = cvt_pk_bf16(f[2], f[3]); o.z = cvt_pk_bf16(f[4], f[5]); o.w = cvt_pk_bf16(f[6], f[7]); return o; }
;     __device__ __forceinline__ void operator()(const f32x4 (&acc)[2][2][4][2], const Unit& u, int wr, int wc, int fr, int fq) const {
;     ...
;                 for (int m = 0; m < 4; ++m) { bf16_t* rowp = X + (size_t)(row0 + ai * HALF + m * 16) * D + col0;
; #pragma unroll
;                     for (int bj = 0; bj < 2; ++bj) { u32x4* p = (u32x4*)(rowp + bj * HALF); float x[8]; unpack8(*p, x); const f32x4 a0 = acc[ai][bj][m][0], a1 = acc[ai][bj][m][1];
; #pragma unroll
;                         for (int e = 0; e < 4; ++e) { x[e] += a0[e]; x[4 + e] += a1[e]; }
;                         *p = pack8(x); }
;                     asm volatile("" ::: "memory"); }
	v_lshlrev_b32_e32 v248, 16, v180
	v_lshlrev_b32_e32 v249, 16, v181
	v_lshlrev_b32_e32 v250, 16, v182
	v_lshlrev_b32_e32 v251, 16, v183
	v_and_b32_e32 v180, 0xffff0000, v180
	v_and_b32_e32 v181, 0xffff0000, v181
	v_and_b32_e32 v182, 0xffff0000, v182
	v_and_b32_e32 v183, 0xffff0000, v183
	v_add_f32_e32 v94, v94, v248
	v_add_f32_e32 v95, v95, v180
	v_add_f32_e32 v96, v96, v249
	v_add_f32_e32 v97, v97, v181
	v_add_f32_e32 v90, v90, v250
	v_add_f32_e32 v91, v91, v182
	v_add_f32_e32 v92, v92, v251
	v_add_f32_e32 v93, v93, v183
	v_mul_f32_e32 v205, v94, v94
	v_fmac_f32_e32 v205, v95, v95
	v_fmac_f32_e32 v205, v96, v96
	v_fmac_f32_e32 v205, v97, v97
	v_fmac_f32_e32 v205, v90, v90
	v_fmac_f32_e32 v205, v91, v91
	v_fmac_f32_e32 v205, v92, v92
	v_fmac_f32_e32 v205, v93, v93
	v_cvt_pk_bf16_f32 v180, v94, v95
	v_cvt_pk_bf16_f32 v181, v96, v97
	v_cvt_pk_bf16_f32 v182, v90, v91
	v_cvt_pk_bf16_f32 v183, v92, v93
	global_store_dwordx4 v162, v[180:183], s[70:71]
	s_waitcnt vmcnt(15)
	v_lshlrev_b32_e32 v248, 16, v184
	v_lshlrev_b32_e32 v249, 16, v185
	v_lshlrev_b32_e32 v250, 16, v186
	v_lshlrev_b32_e32 v251, 16, v187
	v_and_b32_e32 v184, 0xffff0000, v184
	v_and_b32_e32 v185, 0xffff0000, v185
	v_and_b32_e32 v186, 0xffff0000, v186
	v_and_b32_e32 v187, 0xffff0000, v187
	v_add_f32_e32 v86, v86, v248
	v_add_f32_e32 v87, v87, v184
	v_add_f32_e32 v88, v88, v249
	v_add_f32_e32 v89, v89, v185
	v_add_f32_e32 v82, v82, v250
	v_add_f32_e32 v83, v83, v186
	v_add_f32_e32 v84, v84, v251
	v_add_f32_e32 v85, v85, v187
	v_fmac_f32_e32 v205, v86, v86
	v_fmac_f32_e32 v205, v87, v87
	v_fmac_f32_e32 v205, v88, v88
	v_fmac_f32_e32 v205, v89, v89
	v_fmac_f32_e32 v205, v82, v82
	v_fmac_f32_e32 v205, v83, v83
	v_fmac_f32_e32 v205, v84, v84
	v_fmac_f32_e32 v205, v85, v85
	v_cvt_pk_bf16_f32 v184, v86, v87
	v_cvt_pk_bf16_f32 v185, v88, v89
	v_cvt_pk_bf16_f32 v186, v82, v83
	v_cvt_pk_bf16_f32 v187, v84, v85
	global_store_dwordx4 v162, v[184:187], s[70:71] offset:256
	global_store_dword v163, v205, s[72:73]
	s_add_u32 s70, s70, 0x8000
	s_addc_u32 s71, s71, 0
	s_add_u32 s72, s72, 0x1000
	s_addc_u32 s73, s73, 0
	s_waitcnt vmcnt(15)
	v_lshlrev_b32_e32 v248, 16, v188
	v_lshlrev_b32_e32 v249, 16, v189
	v_lshlrev_b32_e32 v250, 16, v190
	v_lshlrev_b32_e32 v251, 16, v191
	v_and_b32_e32 v188, 0xffff0000, v188
	v_and_b32_e32 v189, 0xffff0000, v189
	v_and_b32_e32 v190, 0xffff0000, v190
	v_and_b32_e32 v191, 0xffff0000, v191
	v_add_f32_e32 v78, v78, v248
	v_add_f32_e32 v79, v79, v188
	v_add_f32_e32 v80, v80, v249
	v_add_f32_e32 v81, v81, v189
	v_add_f32_e32 v74, v74, v250
	v_add_f32_e32 v75, v75, v190
	v_add_f32_e32 v76, v76, v251
	v_add_f32_e32 v77, v77, v191
	v_mul_f32_e32 v206, v78, v78
	v_fmac_f32_e32 v206, v79, v79
	v_fmac_f32_e32 v206, v80, v80
	v_fmac_f32_e32 v206, v81, v81
	v_fmac_f32_e32 v206, v74, v74
	v_fmac_f32_e32 v206, v75, v75
	v_fmac_f32_e32 v206, v76, v76
	v_fmac_f32_e32 v206, v77, v77
	v_cvt_pk_bf16_f32 v188, v78, v79
	v_cvt_pk_bf16_f32 v189, v80, v81
	v_cvt_pk_bf16_f32 v190, v74, v75
	v_cvt_pk_bf16_f32 v191, v76, v77
	global_store_dwordx4 v162, v[188:191], s[70:71]
	s_waitcnt vmcnt(15)
	v_lshlrev_b32_e32 v248, 16, v192
	v_lshlrev_b32_e32 v249, 16, v193
	v_lshlrev_b32_e32 v250, 16, v194
	v_lshlrev_b32_e32 v251, 16, v195
	v_and_b32_e32 v192, 0xffff0000, v192
	v_and_b32_e32 v193, 0xffff0000, v193
	v_and_b32_e32 v194, 0xffff0000, v194
	v_and_b32_e32 v195, 0xffff0000, v195
	v_add_f32_e32 v70, v70, v248
	v_add_f32_e32 v71, v71, v192
	v_add_f32_e32 v72, v72, v249
	v_add_f32_e32 v73, v73, v193
	v_add_f32_e32 v66, v66, v250
	v_add_f32_e32 v67, v67, v194
	v_add_f32_e32 v68, v68, v251
	v_add_f32_e32 v69, v69, v195
	v_fmac_f32_e32 v206, v70, v70
	v_fmac_f32_e32 v206, v71, v71
	v_fmac_f32_e32 v206, v72, v72
	v_fmac_f32_e32 v206, v73, v73
	v_fmac_f32_e32 v206, v66, v66
	v_fmac_f32_e32 v206, v67, v67
	v_fmac_f32_e32 v206, v68, v68
	v_fmac_f32_e32 v206, v69, v69
	v_cvt_pk_bf16_f32 v192, v70, v71
	v_cvt_pk_bf16_f32 v193, v72, v73
	v_cvt_pk_bf16_f32 v194, v66, v67
	v_cvt_pk_bf16_f32 v195, v68, v69
	global_store_dwordx4 v162, v[192:195], s[70:71] offset:256
	global_store_dword v163, v206, s[72:73]
	s_add_u32 s70, s70, 0x28000
	s_addc_u32 s71, s71, 0
	s_add_u32 s72, s72, 0x5000
	s_addc_u32 s73, s73, 0
	s_waitcnt vmcnt(15)
	v_lshlrev_b32_e32 v248, 16, v196
	v_lshlrev_b32_e32 v249, 16, v197
	v_lshlrev_b32_e32 v250, 16, v198
	v_lshlrev_b32_e32 v251, 16, v199
	v_and_b32_e32 v196, 0xffff0000, v196
	v_and_b32_e32 v197, 0xffff0000, v197
	v_and_b32_e32 v198, 0xffff0000, v198
	v_and_b32_e32 v199, 0xffff0000, v199
	v_add_f32_e32 v62, v62, v248
	v_add_f32_e32 v63, v63, v196
	v_add_f32_e32 v64, v64, v249
	v_add_f32_e32 v65, v65, v197
	v_add_f32_e32 v58, v58, v250
	v_add_f32_e32 v59, v59, v198
	v_add_f32_e32 v60, v60, v251
	v_add_f32_e32 v61, v61, v199
	v_mul_f32_e32 v208, v62, v62
	v_fmac_f32_e32 v208, v63, v63
	v_fmac_f32_e32 v208, v64, v64
	v_fmac_f32_e32 v208, v65, v65
	v_fmac_f32_e32 v208, v58, v58
	v_fmac_f32_e32 v208, v59, v59
	v_fmac_f32_e32 v208, v60, v60
	v_fmac_f32_e32 v208, v61, v61
	v_cvt_pk_bf16_f32 v196, v62, v63
	v_cvt_pk_bf16_f32 v197, v64, v65
	v_cvt_pk_bf16_f32 v198, v58, v59
	v_cvt_pk_bf16_f32 v199, v60, v61
	global_store_dwordx4 v162, v[196:199], s[70:71]
	s_waitcnt vmcnt(15)
; __device__ __forceinline__ u32x4 pack8(const float (&f)[8]) { u32x4 o; o.x = cvt_pk_bf16(f[0], f[1]); o.y = cvt_pk_bf16(f[2], f[3]); o.z = cvt_pk_bf16(f[4], f[5]); o.w = cvt_pk_bf16(f[6], f[7]); return o; }
;     __device__ __forceinline__ void operator()(const f32x4 (&acc)[2][2][4][2], const Unit& u, int wr, int wc, int fr, int fq) const {
;     ...
;                 for (int m = 0; m < 4; ++m) { bf16_t* rowp = X + (size_t)(row0 + ai * HALF + m * 16) * D + col0;
; #pragma unroll
;                     for (int bj = 0; bj < 2; ++bj) { u32x4* p = (u32x4*)(rowp + bj * HALF); float x[8]; unpack8(*p, x); const f32x4 a0 = acc[ai][bj][m][0], a1 = acc[ai][bj][m][1];
; #pragma unroll
;                         for (int e = 0; e < 4; ++e) { x[e] += a0[e]; x[4 + e] += a1[e]; }
;                         *p = pack8(x); }
;                     asm volatile("" ::: "memory"); }
	v_lshlrev_b32_e32 v248, 16, v200
	v_lshlrev_b32_e32 v249, 16, v201
	v_lshlrev_b32_e32 v250, 16, v202
	v_lshlrev_b32_e32 v251, 16, v203
	v_and_b32_e32 v200, 0xffff0000, v200
	v_and_b32_e32 v201, 0xffff0000, v201
	v_and_b32_e32 v202, 0xffff0000, v202
	v_and_b32_e32 v203, 0xffff0000, v203
	v_add_f32_e32 v54, v54, v248
	v_add_f32_e32 v55, v55, v200
	v_add_f32_e32 v56, v56, v249
	v_add_f32_e32 v57, v57, v201
	v_add_f32_e32 v50, v50, v250
	v_add_f32_e32 v51, v51, v202
	v_add_f32_e32 v52, v52, v251
	v_add_f32_e32 v53, v53, v203
	v_fmac_f32_e32 v208, v54, v54
	v_fmac_f32_e32 v208, v55, v55
	v_fmac_f32_e32 v208, v56, v56
	v_fmac_f32_e32 v208, v57, v57
	v_fmac_f32_e32 v208, v50, v50
	v_fmac_f32_e32 v208, v51, v51
	v_fmac_f32_e32 v208, v52, v52
	v_fmac_f32_e32 v208, v53, v53
	v_cvt_pk_bf16_f32 v200, v54, v55
	v_cvt_pk_bf16_f32 v201, v56, v57
	v_cvt_pk_bf16_f32 v202, v50, v51
	v_cvt_pk_bf16_f32 v203, v52, v53
	global_store_dwordx4 v162, v[200:203], s[70:71] offset:256
	global_store_dword v163, v208, s[72:73]
	s_add_u32 s70, s70, 0x8000
	s_addc_u32 s71, s71, 0
	s_add_u32 s72, s72, 0x1000
	s_addc_u32 s73, s73, 0
	s_waitcnt vmcnt(15)
	v_lshlrev_b32_e32 v248, 16, v224
	v_lshlrev_b32_e32 v249, 16, v225
	v_lshlrev_b32_e32 v250, 16, v226
	v_lshlrev_b32_e32 v251, 16, v227
	v_and_b32_e32 v224, 0xffff0000, v224
	v_and_b32_e32 v225, 0xffff0000, v225
	v_and_b32_e32 v226, 0xffff0000, v226
	v_and_b32_e32 v227, 0xffff0000, v227
	v_add_f32_e32 v46, v46, v248
	v_add_f32_e32 v47, v47, v224
	v_add_f32_e32 v48, v48, v249
	v_add_f32_e32 v49, v49, v225
	v_add_f32_e32 v42, v42, v250
	v_add_f32_e32 v43, v43, v226
	v_add_f32_e32 v44, v44, v251
	v_add_f32_e32 v45, v45, v227
	v_mul_f32_e32 v210, v46, v46
	v_fmac_f32_e32 v210, v47, v47
	v_fmac_f32_e32 v210, v48, v48
	v_fmac_f32_e32 v210, v49, v49
	v_fmac_f32_e32 v210, v42, v42
	v_fmac_f32_e32 v210, v43, v43
	v_fmac_f32_e32 v210, v44, v44
	v_fmac_f32_e32 v210, v45, v45
	v_cvt_pk_bf16_f32 v224, v46, v47
	v_cvt_pk_bf16_f32 v225, v48, v49
	v_cvt_pk_bf16_f32 v226, v42, v43
	v_cvt_pk_bf16_f32 v227, v44, v45
	global_store_dwordx4 v162, v[224:227], s[70:71]
	s_waitcnt vmcnt(15)
	v_lshlrev_b32_e32 v248, 16, v228
	v_lshlrev_b32_e32 v249, 16, v229
	v_lshlrev_b32_e32 v250, 16, v230
	v_lshlrev_b32_e32 v251, 16, v231
	v_and_b32_e32 v228, 0xffff0000, v228
	v_and_b32_e32 v229, 0xffff0000, v229
	v_and_b32_e32 v230, 0xffff0000, v230
	v_and_b32_e32 v231, 0xffff0000, v231
	v_add_f32_e32 v38, v38, v248
	v_add_f32_e32 v39, v39, v228
	v_add_f32_e32 v40, v40, v249
	v_add_f32_e32 v41, v41, v229
	v_add_f32_e32 v34, v34, v250
	v_add_f32_e32 v35, v35, v230
	v_add_f32_e32 v36, v36, v251
	v_add_f32_e32 v37, v37, v231
	v_fmac_f32_e32 v210, v38, v38
	v_fmac_f32_e32 v210, v39, v39
	v_fmac_f32_e32 v210, v40, v40
	v_fmac_f32_e32 v210, v41, v41
	v_fmac_f32_e32 v210, v34, v34
	v_fmac_f32_e32 v210, v35, v35
	v_fmac_f32_e32 v210, v36, v36
	v_fmac_f32_e32 v210, v37, v37
	v_cvt_pk_bf16_f32 v228, v38, v39
	v_cvt_pk_bf16_f32 v229, v40, v41
	v_cvt_pk_bf16_f32 v230, v34, v35
	v_cvt_pk_bf16_f32 v231, v36, v37
	global_store_dwordx4 v162, v[228:231], s[70:71] offset:256
	global_store_dword v163, v210, s[72:73]
	s_add_u32 s70, s70, 0x8000
	s_addc_u32 s71, s71, 0
	s_add_u32 s72, s72, 0x1000
	s_addc_u32 s73, s73, 0
	s_waitcnt vmcnt(15)
; __device__ __forceinline__ u32x4 pack8(const float (&f)[8]) { u32x4 o; o.x = cvt_pk_bf16(f[0], f[1]); o.y = cvt_pk_bf16(f[2], f[3]); o.z = cvt_pk_bf16(f[4], f[5]); o.w = cvt_pk_bf16(f[6], f[7]); return o; }
;     __device__ __forceinline__ void operator()(const f32x4 (&acc)[2][2][4][2], const Unit& u, int wr, int wc, int fr, int fq) const {
;     ...
;                 for (int m = 0; m < 4; ++m) { bf16_t* rowp = X + (size_t)(row0 + ai * HALF + m * 16) * D + col0;
; #pragma unroll
;                     for (int bj = 0; bj < 2; ++bj) { u32x4* p = (u32x4*)(rowp + bj * HALF); float x[8]; unpack8(*p, x); const f32x4 a0 = acc[ai][bj][m][0], a1 = acc[ai][bj][m][1];
; #pragma unroll
;                         for (int e = 0; e < 4; ++e) { x[e] += a0[e]; x[4 + e] += a1[e]; }
;                         *p = pack8(x); }
;                     asm volatile("" ::: "memory"); }
	v_lshlrev_b32_e32 v248, 16, v232
	v_lshlrev_b32_e32 v249, 16, v233
	v_lshlrev_b32_e32 v250, 16, v234
	v_lshlrev_b32_e32 v251, 16, v235
	v_and_b32_e32 v232, 0xffff0000, v232
	v_and_b32_e32 v233, 0xffff0000, v233
	v_and_b32_e32 v234, 0xffff0000, v234
	v_and_b32_e32 v235, 0xffff0000, v235
	v_add_f32_e32 v30, v30, v248
	v_add_f32_e32 v31, v31, v232
	v_add_f32_e32 v32, v32, v249
	v_add_f32_e32 v33, v33, v233
	v_add_f32_e32 v26, v26, v250
	v_add_f32_e32 v27, v27, v234
	v_add_f32_e32 v28, v28, v251
	v_add_f32_e32 v29, v29, v235
	v_mul_f32_e32 v211, v30, v30
	v_fmac_f32_e32 v211, v31, v31
	v_fmac_f32_e32 v211, v32, v32
	v_fmac_f32_e32 v211, v33, v33
	v_fmac_f32_e32 v211, v26, v26
	v_fmac_f32_e32 v211, v27, v27
	v_fmac_f32_e32 v211, v28, v28
	v_fmac_f32_e32 v211, v29, v29
	v_cvt_pk_bf16_f32 v232, v30, v31
	v_cvt_pk_bf16_f32 v233, v32, v33
	v_cvt_pk_bf16_f32 v234, v26, v27
	v_cvt_pk_bf16_f32 v235, v28, v29
	global_store_dwordx4 v162, v[232:235], s[70:71]
	s_waitcnt vmcnt(15)
	v_lshlrev_b32_e32 v248, 16, v236
	v_lshlrev_b32_e32 v249, 16, v237
	v_lshlrev_b32_e32 v250, 16, v238
	v_lshlrev_b32_e32 v251, 16, v239
	v_and_b32_e32 v236, 0xffff0000, v236
	v_and_b32_e32 v237, 0xffff0000, v237
	v_and_b32_e32 v238, 0xffff0000, v238
	v_and_b32_e32 v239, 0xffff0000, v239
	v_add_f32_e32 v22, v22, v248
	v_add_f32_e32 v23, v23, v236
	v_add_f32_e32 v24, v24, v249
	v_add_f32_e32 v25, v25, v237
	v_add_f32_e32 v18, v18, v250
	v_add_f32_e32 v19, v19, v238
	v_add_f32_e32 v20, v20, v251
	v_add_f32_e32 v21, v21, v239
	v_fmac_f32_e32 v211, v22, v22
	v_fmac_f32_e32 v211, v23, v23
	v_fmac_f32_e32 v211, v24, v24
	v_fmac_f32_e32 v211, v25, v25
	v_fmac_f32_e32 v211, v18, v18
	v_fmac_f32_e32 v211, v19, v19
	v_fmac_f32_e32 v211, v20, v20
	v_fmac_f32_e32 v211, v21, v21
	v_cvt_pk_bf16_f32 v236, v22, v23
	v_cvt_pk_bf16_f32 v237, v24, v25
	v_cvt_pk_bf16_f32 v238, v18, v19
	v_cvt_pk_bf16_f32 v239, v20, v21
	global_store_dwordx4 v162, v[236:239], s[70:71] offset:256
	global_store_dword v163, v211, s[72:73]
	s_add_u32 s70, s70, 0x8000
	s_addc_u32 s71, s71, 0
	s_add_u32 s72, s72, 0x1000
	s_addc_u32 s73, s73, 0
	s_waitcnt vmcnt(15)
	v_lshlrev_b32_e32 v248, 16, v240
	v_lshlrev_b32_e32 v249, 16, v241
	v_lshlrev_b32_e32 v250, 16, v242
	v_lshlrev_b32_e32 v251, 16, v243
	v_and_b32_e32 v240, 0xffff0000, v240
	v_and_b32_e32 v241, 0xffff0000, v241
	v_and_b32_e32 v242, 0xffff0000, v242
	v_and_b32_e32 v243, 0xffff0000, v243
	v_add_f32_e32 v14, v14, v248
	v_add_f32_e32 v15, v15, v240
	v_add_f32_e32 v16, v16, v249
	v_add_f32_e32 v17, v17, v241
	v_add_f32_e32 v10, v10, v250
	v_add_f32_e32 v11, v11, v242
	v_add_f32_e32 v12, v12, v251
	v_add_f32_e32 v13, v13, v243
	v_mul_f32_e32 v212, v14, v14
	v_fmac_f32_e32 v212, v15, v15
	v_fmac_f32_e32 v212, v16, v16
	v_fmac_f32_e32 v212, v17, v17
	v_fmac_f32_e32 v212, v10, v10
	v_fmac_f32_e32 v212, v11, v11
	v_fmac_f32_e32 v212, v12, v12
	v_fmac_f32_e32 v212, v13, v13
	v_cvt_pk_bf16_f32 v240, v14, v15
	v_cvt_pk_bf16_f32 v241, v16, v17
	v_cvt_pk_bf16_f32 v242, v10, v11
	v_cvt_pk_bf16_f32 v243, v12, v13
	global_store_dwordx4 v162, v[240:243], s[70:71]
	s_waitcnt vmcnt(15)
	v_lshlrev_b32_e32 v248, 16, v244
	v_lshlrev_b32_e32 v249, 16, v245
	v_lshlrev_b32_e32 v250, 16, v246
	v_lshlrev_b32_e32 v251, 16, v247
	v_and_b32_e32 v244, 0xffff0000, v244
	v_and_b32_e32 v245, 0xffff0000, v245
	v_and_b32_e32 v246, 0xffff0000, v246
	v_and_b32_e32 v247, 0xffff0000, v247
	v_add_f32_e32 v6, v6, v248
	v_add_f32_e32 v7, v7, v244
	v_add_f32_e32 v8, v8, v249
	v_add_f32_e32 v9, v9, v245
	v_add_f32_e32 v2, v2, v250
	v_add_f32_e32 v3, v3, v246
	v_add_f32_e32 v4, v4, v251
	v_add_f32_e32 v5, v5, v247
	v_fmac_f32_e32 v212, v6, v6
	v_fmac_f32_e32 v212, v7, v7
	v_fmac_f32_e32 v212, v8, v8
	v_fmac_f32_e32 v212, v9, v9
	v_fmac_f32_e32 v212, v2, v2
	v_fmac_f32_e32 v212, v3, v3
	v_fmac_f32_e32 v212, v4, v4
	v_fmac_f32_e32 v212, v5, v5
	v_cvt_pk_bf16_f32 v244, v6, v7
	v_cvt_pk_bf16_f32 v245, v8, v9
	v_cvt_pk_bf16_f32 v246, v2, v3
	v_cvt_pk_bf16_f32 v247, v4, v5
	global_store_dwordx4 v162, v[244:247], s[70:71] offset:256
	global_store_dword v163, v212, s[72:73]
	s_and_b64 vcc, exec, s[4:5]
	s_mov_b64 s[4:5], -1
	s_cbranch_vccnz .LBB0_710
	s_branch .LBB0_735

; __device__ __forceinline__ int tid_() { int t = threadIdx.x; asm volatile("" : "+v"(t)); return t; }
; __device__ __forceinline__ int bid_() { int t = blockIdx.x; asm volatile("" : "+s"(t)); return t; }
; __device__ __forceinline__ int gdim_() { int t = gridDim.x; asm volatile("" : "+s"(t)); return t; }
; __device__ __forceinline__ unsigned cvt_pk_bf16(float lo, float hi) { unsigned r; asm volatile("v_cvt_pk_bf16_f32 %0, %1, %2" : "=v"(r) : "v"(lo), "v"(hi)); return r; }
; __device__ __forceinline__ void norm_phase(KP p, bool first, int nslab) {
;     const int tid = tid_(), lane = tid & 63, wave = __builtin_amdgcn_readfirstlane(tid >> 6);
;     const int gw = bid_() * 8 + wave, NGW = gdim_() * 8;
;     bf16_t* X = (bf16_t*)(p->ws + WS_X); bf16_t* XN = (bf16_t*)(p->ws + WS_R2);
;     const bool xaware = gdim_() == 256; const int cb = bid_(), xl = cb & 7, jl = cb >> 3;
;     for (int it = 0; it < 9; ++it) {
;         int m;
;         if (xaware) { if (it < 8) m = 2048 * xl + 256 * it + jl * 8 + wave; else { if (gw >= 256) break; m = 64 * 256 + gw; } }
;         else { m = gw + it * NGW; if (m >= M) break; }
;         f32x4 v[4]; float s = 0.f;
;         if (first) { const f32x4* xr = (const f32x4*)src_row(p, m) + lane;
; #pragma unroll
;             for (int j = 0; j < 4; ++j) v[j] = __builtin_nontemporal_load(xr + 64 * j); }
;         else { const u32x2* xr = (const u32x2*)(X + (size_t)m * D) + lane;
; #pragma unroll
;             for (int j = 0; j < 4; ++j) { const u32x2 w = __builtin_nontemporal_load(xr + 64 * j); v[j] = (f32x4){bflo(w.x), bfhi(w.x), bflo(w.y), bfhi(w.y)}; } }
;         const bool fold = (!first) && m >= 64 * 256;
;         if (fold) { const f32x4* sl = (const f32x4*)(p->ws + WS_SLAB) + (size_t)(m - 64 * 256) * (D / 4) + lane;
;             for (int q = 0; q < nslab; ++q) {
; #pragma unroll
;                 for (int j = 0; j < 4; ++j) v[j] += sl[(size_t)q * 256 * (D / 4) + 64 * j]; } }
;         if (first || fold) { u32x2* xo = (u32x2*)(X + (size_t)m * D) + lane;
; #pragma unroll
;             for (int j = 0; j < 4; ++j) { u32x2 w; w.x = cvt_pk_bf16(v[j][0], v[j][1]); w.y = cvt_pk_bf16(v[j][2], v[j][3]); xo[64 * j] = w; } }
; #pragma unroll
;         for (int j = 0; j < 4; ++j) s += (v[j][0] * v[j][0] + v[j][1] * v[j][1]) + (v[j][2] * v[j][2] + v[j][3] * v[j][3]);
;         const float rinv = rsqrtf(wave_sum(s) * (1.f / D) + EPS);
.LBB0_790:
	s_or_b64 exec, exec, s[4:5]
	s_mov_b64 s[4:5], s[94:95]
	v_mov_b32_e32 v0, v209
	s_waitcnt lgkmcnt(0)
	s_barrier
	s_load_dwordx2 s[8:9], s[4:5], 0xe8
	v_and_b32_e32 v2, 63, v0
	v_readfirstlane_b32 s6, v0
	s_nop 3
	s_lshr_b32 s6, s6, 6
	s_waitcnt lgkmcnt(0)
	s_add_u32 s10, s8, 0x25c8000
	s_addc_u32 s11, s9, 0
	s_add_u32 s12, s8, 0x18c48000
	s_addc_u32 s13, s9, 0
	s_add_u32 s14, s8, 0x19068000
	s_addc_u32 s15, s9, 0
	s_cmpk_lt_u32 s2, 32
	s_cbranch_scc1 .Lnm_part2_p7
	s_cmpk_lt_u32 s2, 0xe0
	s_cbranch_scc1 .LBB0_807
	s_sub_i32 s16, s2, 0xe0
	s_lshl_b32 s16, s16, 3
	s_add_i32 s16, s16, s6
	s_add_i32 s18, s16, 0x4000
	s_lshl_b32 s19, s18, 2
	s_lshl_b32 s18, s18, 11
	s_add_u32 s10, s10, s18
	s_addc_u32 s11, s11, 0
	s_add_u32 s14, s14, s19
	s_addc_u32 s15, s15, 0
	v_lshlrev_b32_e32 v5, 3, v2
	v_lshlrev_b32_e32 v6, 4, v2
	global_load_dwordx2 v[18:19], v5, s[10:11]
	global_load_dwordx2 v[20:21], v5, s[10:11] offset:512
	global_load_dwordx2 v[22:23], v5, s[10:11] offset:1024
	global_load_dwordx2 v[24:25], v5, s[10:11] offset:1536
	s_lshl_b32 s18, s16, 12
	s_add_u32 s18, s8, s18
	s_addc_u32 s19, s9, 0
	s_add_u32 s18, s18, 0x1a3ac000
	s_addc_u32 s19, s19, 0
	global_load_dwordx4 v[32:35], v6, s[18:19]
	global_load_dwordx4 v[36:39], v6, s[18:19] offset:1024
	global_load_dwordx4 v[40:43], v6, s[18:19] offset:2048
	global_load_dwordx4 v[44:47], v6, s[18:19] offset:3072
	s_add_u32 s18, s18, 0x100000
	s_addc_u32 s19, s19, 0
	global_load_dwordx4 v[48:51], v6, s[18:19]
	global_load_dwordx4 v[52:55], v6, s[18:19] offset:1024
	global_load_dwordx4 v[56:59], v6, s[18:19] offset:2048
	global_load_dwordx4 v[60:63], v6, s[18:19] offset:3072
	s_add_u32 s18, s18, 0x100000
	s_addc_u32 s19, s19, 0
	global_load_dwordx4 v[64:67], v6, s[18:19]
	global_load_dwordx4 v[68:71], v6, s[18:19] offset:1024
	global_load_dwordx4 v[72:75], v6, s[18:19] offset:2048
	global_load_dwordx4 v[76:79], v6, s[18:19] offset:3072
	s_add_u32 s18, s18, 0x100000
	s_addc_u32 s19, s19, 0
	global_load_dwordx4 v[80:83], v6, s[18:19]
	global_load_dwordx4 v[84:87], v6, s[18:19] offset:1024
	global_load_dwordx4 v[88:91], v6, s[18:19] offset:2048
	global_load_dwordx4 v[92:95], v6, s[18:19] offset:3072
	s_add_u32 s18, s18, 0x100000
	s_addc_u32 s19, s19, 0
	s_waitcnt vmcnt(16)
	v_lshlrev_b32_e32 v224, 16, v18
	v_and_b32_e32 v225, 0xffff0000, v18
	v_lshlrev_b32_e32 v226, 16, v19
	v_and_b32_e32 v227, 0xffff0000, v19
	v_lshlrev_b32_e32 v228, 16, v20
	v_and_b32_e32 v229, 0xffff0000, v20
	v_lshlrev_b32_e32 v230, 16, v21
	v_and_b32_e32 v231, 0xffff0000, v21
	v_lshlrev_b32_e32 v232, 16, v22
	v_and_b32_e32 v233, 0xffff0000, v22
	v_lshlrev_b32_e32 v234, 16, v23
	v_and_b32_e32 v235, 0xffff0000, v23
	v_lshlrev_b32_e32 v236, 16, v24
	v_and_b32_e32 v237, 0xffff0000, v24
	v_lshlrev_b32_e32 v238, 16, v25
	v_and_b32_e32 v239, 0xffff0000, v25
	s_waitcnt vmcnt(12)
	v_add_f32_e32 v224, v224, v32
	v_add_f32_e32 v225, v225, v33
	v_add_f32_e32 v226, v226, v34
	v_add_f32_e32 v227, v227, v35
	v_add_f32_e32 v228, v228, v36
	v_add_f32_e32 v229, v229, v37
	v_add_f32_e32 v230, v230, v38
	v_add_f32_e32 v231, v231, v39
	v_add_f32_e32 v232, v232, v40
	v_add_f32_e32 v233, v233, v41
	v_add_f32_e32 v234, v234, v42
	v_add_f32_e32 v235, v235, v43
	v_add_f32_e32 v236, v236, v44
	v_add_f32_e32 v237, v237, v45
	v_add_f32_e32 v238, v238, v46
	v_add_f32_e32 v239, v239, v47
	s_waitcnt vmcnt(8)
	v_add_f32_e32 v224, v224, v48
	v_add_f32_e32 v225, v225, v49
	v_add_f32_e32 v226, v226, v50
	v_add_f32_e32 v227, v227, v51
	v_add_f32_e32 v228, v228, v52
	v_add_f32_e32 v229, v229, v53
	v_add_f32_e32 v230, v230, v54
	v_add_f32_e32 v231, v231, v55
	v_add_f32_e32 v232, v232, v56
	v_add_f32_e32 v233, v233, v57
	v_add_f32_e32 v234, v234, v58
	v_add_f32_e32 v235, v235, v59
	v_add_f32_e32 v236, v236, v60
	v_add_f32_e32 v237, v237, v61
	v_add_f32_e32 v238, v238, v62
	v_add_f32_e32 v239, v239, v63
	s_waitcnt vmcnt(4)
	v_add_f32_e32 v224, v224, v64
	v_add_f32_e32 v225, v225, v65
	v_add_f32_e32 v226, v226, v66
	v_add_f32_e32 v227, v227, v67
	v_add_f32_e32 v228, v228, v68
	v_add_f32_e32 v229, v229, v69
	v_add_f32_e32 v230, v230, v70
	v_add_f32_e32 v231, v231, v71
	v_add_f32_e32 v232, v232, v72
	v_add_f32_e32 v233, v233, v73
	v_add_f32_e32 v234, v234, v74
	v_add_f32_e32 v235, v235, v75
	v_add_f32_e32 v236, v236, v76
	v_add_f32_e32 v237, v237, v77
	v_add_f32_e32 v238, v238, v78
	v_add_f32_e32 v239, v239, v79
	s_waitcnt vmcnt(0)
	v_add_f32_e32 v224, v224, v80
	v_add_f32_e32 v225, v225, v81
	v_add_f32_e32 v226, v226, v82
	v_add_f32_e32 v227, v227, v83
	v_add_f32_e32 v228, v228, v84
	v_add_f32_e32 v229, v229, v85
	v_add_f32_e32 v230, v230, v86
	v_add_f32_e32 v231, v231, v87
	v_add_f32_e32 v232, v232, v88
	v_add_f32_e32 v233, v233, v89
	v_add_f32_e32 v234, v234, v90
	v_add_f32_e32 v235, v235, v91
	v_add_f32_e32 v236, v236, v92
	v_add_f32_e32 v237, v237, v93
	v_add_f32_e32 v238, v238, v94
	v_add_f32_e32 v239, v239, v95
	v_cvt_pk_bf16_f32 v26, v224, v225
	v_cvt_pk_bf16_f32 v27, v226, v227
	global_store_dwordx2 v5, v[26:27], s[10:11]
	v_cvt_pk_bf16_f32 v28, v228, v229
	v_cvt_pk_bf16_f32 v29, v230, v231
	global_store_dwordx2 v5, v[28:29], s[10:11] offset:512
	v_cvt_pk_bf16_f32 v30, v232, v233
	v_cvt_pk_bf16_f32 v31, v234, v235
	global_store_dwordx2 v5, v[30:31], s[10:11] offset:1024
	v_cvt_pk_bf16_f32 v32, v236, v237
	v_cvt_pk_bf16_f32 v33, v238, v239
	global_store_dwordx2 v5, v[32:33], s[10:11] offset:1536
	v_mul_f32_e32 v7, v224, v224
	v_fmac_f32_e32 v7, v225, v225
	v_fmac_f32_e32 v7, v226, v226
	v_fmac_f32_e32 v7, v227, v227
	v_fmac_f32_e32 v7, v228, v228
	v_fmac_f32_e32 v7, v229, v229
	v_fmac_f32_e32 v7, v230, v230
	v_fmac_f32_e32 v7, v231, v231
	v_fmac_f32_e32 v7, v232, v232
	v_fmac_f32_e32 v7, v233, v233
	v_fmac_f32_e32 v7, v234, v234
	v_fmac_f32_e32 v7, v235, v235
	v_fmac_f32_e32 v7, v236, v236
	v_fmac_f32_e32 v7, v237, v237
	v_fmac_f32_e32 v7, v238, v238
	v_fmac_f32_e32 v7, v239, v239
	v_xor_b32_e32 v10, 1, v2
	v_lshlrev_b32_e32 v10, 2, v10
	ds_bpermute_b32 v10, v10, v7
	s_waitcnt lgkmcnt(0)
	v_add_f32_e32 v7, v7, v10
	v_xor_b32_e32 v10, 2, v2
	v_lshlrev_b32_e32 v10, 2, v10
	ds_bpermute_b32 v10, v10, v7
	s_waitcnt lgkmcnt(0)
	v_add_f32_e32 v7, v7, v10
	v_xor_b32_e32 v10, 4, v2
	v_lshlrev_b32_e32 v10, 2, v10
	ds_bpermute_b32 v10, v10, v7
	s_waitcnt lgkmcnt(0)
	v_add_f32_e32 v7, v7, v10
	v_xor_b32_e32 v10, 8, v2
	v_lshlrev_b32_e32 v10, 2, v10
	ds_bpermute_b32 v10, v10, v7
	s_waitcnt lgkmcnt(0)
	v_add_f32_e32 v7, v7, v10
	v_xor_b32_e32 v10, 16, v2
	v_lshlrev_b32_e32 v10, 2, v10
	ds_bpermute_b32 v10, v10, v7
	s_waitcnt lgkmcnt(0)
	v_add_f32_e32 v7, v7, v10
	v_xor_b32_e32 v10, 32, v2
	v_lshlrev_b32_e32 v10, 2, v10
	ds_bpermute_b32 v10, v10, v7
	s_waitcnt lgkmcnt(0)
	v_add_f32_e32 v7, v7, v10
	v_fmamk_f32 v7, v7, 0x3a800000, v213
	v_rsq_f32_e32 v7, v7
	s_nop 0
	global_store_dword v1, v7, s[14:15]
	s_branch .LBB0_807

; __device__ __forceinline__ KP kargs() { KP k = (KP)__builtin_amdgcn_kernarg_segment_ptr(); asm volatile("" : "+s"(k)); return k; }
; __device__ __forceinline__ int bid_() { int t = blockIdx.x; asm volatile("" : "+s"(t)); return t; }
; #define PG8_WAIT_V(n) asm volatile("s_waitcnt vmcnt(" #n ")" ::: "memory")
; template <class Epi, bool ALIGN_EPI = true, bool SP2 = true>
; __device__ __forceinline__ void gemm_phase(LAS unsigned char* lds, const Gemm g, const Order& S, const Epi& E) {
;     ...
;     for (int i = 0; i < 2; ++i) { int R, C; stage_rc(tid * 16 + i * 8192, R, C); const int Rb = Epi::PERM ? ((R & ~31) + perm32(R & 31)) : R;
;         voffA[i] = (unsigned)(R * lda + C) * 2u; voffB[i] = (unsigned)(Rb * K + C) * 2u; }
;     const size_t kstep = (size_t)(BK * 2);
;     const size_t hstepA = (size_t)HALF * lda * 2, hstepB = (size_t)HALF * K * 2;
;     const size_t tstepA = 2 * hstepA, tstepB = 2 * hstepB;
;     const unsigned ldsw = (unsigned)wid * 1024u;
;     const int aoff = lds_byte(wr * 64 + fr, fq * 8), boff = lds_byte(wc * 32 + fr, fq * 8);
;     ...
;     Unit cur, nxt; int ui = 0;
;     if (!S.next(0, cur)) return;
;     f32x4 acc[2][2][4][2];
; #pragma unroll
;     for (int a = 0; a < 2; ++a)
; #pragma unroll
;         for (int b = 0; b < 2; ++b)
; #pragma unroll
;             for (int m = 0; m < 4; ++m)
; #pragma unroll
;                 for (int n = 0; n < 2; ++n) acc[a][b][m][n] = (f32x4){0.f, 0.f, 0.f, 0.f};
;     bf16x8 At[4][2], B0[2][2], B1[2][2];
;     const char* cA = (const char*)(cur.z ? g.A1 : g.A0) + (size_t)cur.pm * tstepA + (size_t)cur.kt0 * kstep; const char* cB = (const char*)(cur.z ? g.B1 : g.B0) + (size_t)cur.pn * tstepB + (size_t)cur.kt0 * kstep;
;     if constexpr (SP2) {
;         PG8_STAGE(PG8_SB(0, 0), cB, voffB); PG8_STAGE(PG8_SB(0, 1), cB + hstepB, voffB); PG8_STAGE(PG8_SA(0, 0), cA, voffA); PG8_STAGE(PG8_SA(0, 1), cA + hstepA, voffA);
;         if (wr == 1) PG8_BAR;
;         PG8_WAIT_V(2); PG8_BAR;
;         PG8_STAGE(PG8_SB(1, 0), cB + kstep, voffB); PG8_STAGE(PG8_SA(1, 0), cA + kstep, voffA); PG8_STAGE(PG8_SB(1, 1), cB + hstepB + kstep, voffB);
; __global__ void __launch_bounds__(512, 2) fwd_megakernel(Params pv) {
;     ...
;         { KP p = kargs(); unsigned char* ws = p->ws; pg8::Gemm g{(const bf16_t*)(ws + WS_R2), nullptr, (const bf16_t*)(ws + WS_WUG), nullptr, D, D}; pg8::Order S; S.init(M, DUG, D, gdim_(), bid_(), 1, 0);
.LBB0_867:
	s_mov_b32 s1, 0x8c000
	s_mov_b32 s20, 0x77000
	s_mov_b32 s25, 0x70000
	s_mov_b32 s24, 0x69000
	s_mov_b32 s97, 0x62000
	s_mov_b32 s96, 0x5b000
	s_mov_b32 s43, 0x54000
	s_mul_hi_u32 s67, s56, 0x8400
	s_mul_i32 s66, s56, 0x8400
	s_mul_hi_u32 s69, s56, 0x2c00
	s_andn2_b64 vcc, exec, s[12:13]
	s_mul_i32 s68, s56, 0x2c00
	s_cbranch_vccnz .LBB0_921
	v_ashrrev_i32_e32 v3, 31, v0
	v_lshrrev_b32_e32 v3, 26, v3
	v_add_u32_e32 v3, v0, v3
	v_ashrrev_i32_e32 v10, 6, v3
	v_bfe_i32 v3, v0, 27, 1
	v_lshlrev_b32_e32 v2, 4, v0
	v_lshrrev_b32_e32 v3, 22, v3
	v_add_u32_e32 v3, v2, v3
	v_and_b32_e32 v3, 0xfffffc00, v3
	v_sub_u32_e32 v3, v2, v3
	v_lshrrev_b32_e32 v4, 4, v3
	v_bitop3_b32 v4, v4, v3, 32 bitop3:0x6c
	v_ashrrev_i32_e32 v3, 31, v3
	v_lshrrev_b32_e32 v3, 26, v3
	v_add_u32_e32 v3, v4, v3
	v_ashrrev_i32_e32 v11, 6, v3
	v_lshlrev_b32_e32 v5, 3, v10
	v_mul_i32_i24_e32 v6, 64, v11
	v_and_b32_e32 v5, -16, v5
	v_sub_u32_e32 v4, v4, v6
	v_add_u32_e32 v3, v11, v5
	v_lshlrev_b32_e32 v5, 5, v10
	v_ashrrev_i16_sdwa v4, v218, sext(v4) dst_sel:DWORD dst_unused:UNUSED_PAD src0_sel:DWORD src1_sel:BYTE_0
	v_and_b32_e32 v5, 32, v5
	v_bfe_i32 v12, v4, 0, 16
	v_and_b32_e32 v7, 3, v11
	s_mov_b32 s0, 0x1fffe0
	v_add_lshl_u32 v5, v5, v12, 1
	v_add_u32_e32 v2, 0x2000, v2
	v_lshlrev_b32_e32 v4, 1, v3
	v_lshrrev_b32_e32 v6, 2, v3
	v_and_or_b32 v7, v3, s0, v7
	v_lshl_add_u32 v162, v3, 11, v5
	v_ashrrev_i32_e32 v3, 31, v2
	v_lshrrev_b32_e32 v3, 22, v3
	v_add_u32_e32 v3, v2, v3
	v_ashrrev_i32_e32 v13, 10, v3
	s_ashr_i32 s23, s21, 6
	s_ashr_i32 s19, s21, 8
	v_mul_i32_i24_e32 v3, 0x400, v13
	s_lshl_b32 s49, s23, 10
	v_sub_u32_e32 v2, v2, v3
	s_waitcnt lgkmcnt(0)
	s_add_u32 s50, s8, 0x25c8000
	v_and_b32_e32 v4, 24, v4
	v_and_b32_e32 v6, 4, v6
	v_lshrrev_b32_e32 v3, 4, v2
	s_addc_u32 s51, s9, 0
	v_or3_b32 v4, v7, v6, v4
	v_bitop3_b32 v2, v3, v2, 32 bitop3:0x6c
	s_add_u32 s52, s8, 0x1400000
	v_lshl_add_u32 v164, v4, 11, v5
	v_ashrrev_i32_e32 v4, 31, v2
	s_addc_u32 s53, s9, 0
	s_ashr_i32 s91, s90, 31
	v_lshrrev_b32_e32 v4, 26, v4
	s_lshl_b64 s[12:13], s[90:91], 19
	v_add_u32_e32 v4, v2, v4
	s_add_u32 s12, s50, s12
	v_lshlrev_b32_e32 v3, 3, v13
	v_ashrrev_i32_e32 v14, 6, v4
	v_and_b32_e32 v4, 0xc0, v4
	s_addc_u32 s13, s51, s13
	s_ashr_i32 s11, s10, 31
	v_and_b32_e32 v3, -16, v3
	v_sub_u32_e32 v2, v2, v4
	s_lshl_b64 s[34:35], s[10:11], 19
	v_add_u32_e32 v3, v14, v3
	v_ashrrev_i16_sdwa v2, v218, sext(v2) dst_sel:DWORD dst_unused:UNUSED_PAD src0_sel:DWORD src1_sel:BYTE_0
	s_add_u32 s92, s52, s34
	v_lshlrev_b32_e32 v5, 5, v13
	v_bfe_i32 v15, v2, 0, 16
	v_lshlrev_b32_e32 v2, 1, v3
	v_lshrrev_b32_e32 v4, 2, v3
	v_and_b32_e32 v6, 3, v14
	s_addc_u32 s93, s53, s35
	s_add_i32 s46, s49, 0
	v_and_b32_e32 v5, 32, v5
	v_and_b32_e32 v2, 24, v2
	v_and_b32_e32 v4, 4, v4
	v_and_or_b32 v6, v3, s0, v6
	s_add_i32 m0, s46, 0x10000
	v_or3_b32 v2, v6, v4, v2
	v_add_lshl_u32 v4, v5, v15, 1
	global_load_lds_dwordx4 v164, s[92:93]
	s_add_i32 m0, s46, 0x12000
	v_lshl_add_u32 v168, v2, 11, v4
	s_add_u32 s34, s92, 0x40000
	global_load_lds_dwordx4 v168, s[92:93]
	s_addc_u32 s35, s93, 0
	s_add_i32 m0, s46, 0x14000
	s_add_i32 s40, s46, 0x2000
	global_load_lds_dwordx4 v164, s[34:35]
	s_add_i32 m0, s46, 0x16000
	v_lshl_add_u32 v166, v3, 11, v4
	global_load_lds_dwordx4 v168, s[34:35]
	s_mov_b32 m0, s46
	s_add_u32 s34, s12, 0x40000
	global_load_lds_dwordx4 v162, s[12:13]
	s_mov_b32 m0, s40
	s_addc_u32 s35, s13, 0
	s_add_i32 s42, s46, 0x4000
	global_load_lds_dwordx4 v166, s[12:13]
	s_mov_b32 m0, s42
	s_add_i32 s44, s46, 0x6000
	global_load_lds_dwordx4 v162, s[34:35]
	s_mov_b32 m0, s44
	v_mov_b32_e32 v165, v1
	global_load_lds_dwordx4 v166, s[34:35]
	v_mov_b32_e32 v169, v1
	v_mov_b32_e32 v163, v1
	v_mov_b32_e32 v167, v1
	s_cmp_eq_u32 s19, 1
	v_lshl_add_u64 v[8:9], s[92:93], 0, v[164:165]
	v_lshl_add_u64 v[6:7], s[92:93], 0, v[168:169]
	v_lshl_add_u64 v[2:3], s[12:13], 0, v[162:163]
	s_cselect_b64 s[58:59], -1, 0
	s_cmp_lg_u32 s19, 1
	v_lshl_add_u64 v[4:5], s[12:13], 0, v[166:167]
	s_cbranch_scc1 .LBB0_870
	s_barrier

; __device__ __forceinline__ float sigmoidf_(float x) { return __builtin_amdgcn_rcpf(1.0f + __expf(-x)); }
;     __device__ __forceinline__ void operator()(const f32x4 (&acc)[2][2][4][2], const Unit& u, int wr, int wc, int fr, int fq) const {
;         const int ch0 = u.pn * 128 + wc * 32 + 8 * fq;
;         float w0[8], w1[8], w2[8], bb[8]; load8f(cw + ch0, w0); load8f(cw + DFF + ch0, w1); load8f(cw + 2 * DFF + ch0, w2); load8f(cb + ch0, bb);
;         const int rbase = u.pm * BM + wr * 64 + fr;
;         const int b0 = (u.pm * BM) / TP, rb = (b0 + 1) * TP;
; #pragma unroll
;         for (int ai = 0; ai < 2; ++ai) {
;             if (u.pm == 64 && ai == 1) {
; #pragma unroll
;                 for (int m = 0; m < 4; ++m) { const int r = rbase + HALF + 16 * m, sb = r - MP;
;                     float u2[8], u1[8], o[8], uu[8]; load8f(st + (size_t)(sb * 2) * DFF + ch0, u2); load8f(st + (size_t)(sb * 2 + 1) * DFF + ch0, u1);
; #pragma unroll
;                     for (int k = 0; k < 8; ++k) { const float x = acc[1][0][m][k >> 2][k & 3], g = acc[1][1][m][k >> 2][k & 3]; uu[k] = x;
;                         const float uc = w0[k] * u2[k] + w1[k] * u1[k] + w2[k] * x + bb[k]; o[k] = uc * sigmoidf_(uc) * g; }
;                     *(u32x4*)(ACT + (size_t)r * DFF + ch0) = pack8(o);
;                     store8f(outs + (size_t)(sb * 2) * DFF + ch0, u1); store8f(outs + (size_t)(sb * 2 + 1) * DFF + ch0, uu); }
;             } else {
; #pragma unroll
;                 for (int m = 0; m < 4; ++m) { const int r = rbase + ai * HALF + 16 * m; const bool hi = r >= rb; const int t = hi ? r - rb : r - b0 * TP, b = hi ? b0 + 1 : b0;
;                     float o[8], uu[8], gg[8];
; #pragma unroll
;                     for (int k = 0; k < 8; ++k) { const float x = acc[ai][0][m][k >> 2][k & 3], g = acc[ai][1][m][k >> 2][k & 3]; uu[k] = x; gg[k] = g;
;                         float u1 = dpp_ror1(x), u2 = dpp_ror2(x);
;                         if (m > 0) { const float xp = acc[ai][0][m > 0 ? m - 1 : 0][k >> 2][k & 3]; const float p1 = dpp_ror1(xp), p2 = dpp_ror2(xp); u1 = fr >= 1 ? u1 : p1; u2 = fr >= 2 ? u2 : p2; }
;                         if (t == 0) u1 = 0.f; if (t <= 1) u2 = 0.f;
;                         const float uc = w0[k] * u2 + w1[k] * u1 + w2[k] * x + bb[k]; o[k] = uc * sigmoidf_(uc) * g; }
.LBB0_883:
	v_lshl_or_b32 v174, s10, 7, v181
	v_lshlrev_b32_e32 v176, 2, v174
	s_lshl_b32 s91, s90, 8
	global_load_dwordx4 v[50:53], v176, s[66:67]
	global_load_dwordx4 v[54:57], v176, s[66:67] offset:16
	global_load_dwordx4 v[58:61], v176, s[78:79]
	global_load_dwordx4 v[62:65], v176, s[78:79] offset:16
	global_load_dwordx4 v[66:69], v176, s[80:81]
	global_load_dwordx4 v[70:73], v176, s[80:81] offset:16
	global_load_dwordx4 v[74:77], v176, s[68:69]
	global_load_dwordx4 v[78:81], v176, s[68:69] offset:16
	s_mul_hi_u32 s35, s91, 0xfe03f81
	s_lshr_b32 s35, s35, 7
	s_add_i32 s54, s35, 1
	s_mul_i32 s85, s54, 0x810
	s_add_i32 s91, s91, s18
	v_mul_u32_u24_e32 v183, s22, v178
	v_lshl_add_u32 v183, v174, 1, v183
	v_mul_u32_u24_e32 v236, s39, v178
	v_lshl_add_u32 v236, v174, 1, v236
	v_add_u32_e32 v237, s22, v236
	v_mul_i32_i24_e32 v238, s22, v180
	v_lshl_add_u32 v238, v174, 1, v238
	v_mul_i32_i24_e32 v239, s39, v180
	v_lshl_add_u32 v239, v174, 2, v239
	v_mul_u32_u24_e32 v248, 0x5800, v178
	v_lshl_add_u32 v248, v174, 2, v248
	s_add_u32 s94, s60, 0x129a0000
	s_addc_u32 s95, s61, 0
	s_lshl_b32 s10, s91, 2
	s_add_u32 s94, s94, s10
	s_addc_u32 s95, s95, 0
	v_lshlrev_b32_e32 v249, 2, v178
	global_load_dword v205, v249, s[94:95]
	global_load_dword v206, v249, s[94:95] offset:64
	global_load_dword v208, v249, s[94:95] offset:128
	global_load_dword v210, v249, s[94:95] offset:192
	global_load_dword v211, v249, s[94:95] offset:512
	global_load_dword v212, v249, s[94:95] offset:576
	global_load_dword v214, v249, s[94:95] offset:640
	global_load_dword v223, v249, s[94:95] offset:704
	s_waitcnt vmcnt(0)
	v_mul_f32_e32 v150, v205, v150
	v_mul_f32_e32 v151, v205, v151
	v_mul_f32_e32 v152, v205, v152
	v_mul_f32_e32 v153, v205, v153
	v_mul_f32_e32 v142, v205, v142
	v_mul_f32_e32 v143, v205, v143
	v_mul_f32_e32 v144, v205, v144
	v_mul_f32_e32 v145, v205, v145
	v_mul_f32_e32 v158, v205, v158
	v_mul_f32_e32 v159, v205, v159
	v_mul_f32_e32 v160, v205, v160
	v_mul_f32_e32 v161, v205, v161
	v_mul_f32_e32 v154, v205, v154
	v_mul_f32_e32 v155, v205, v155
	v_mul_f32_e32 v156, v205, v156
	v_mul_f32_e32 v157, v205, v157
	v_mul_f32_e32 v134, v206, v134
	v_mul_f32_e32 v135, v206, v135
	v_mul_f32_e32 v136, v206, v136
	v_mul_f32_e32 v137, v206, v137
	v_mul_f32_e32 v126, v206, v126
	v_mul_f32_e32 v127, v206, v127
	v_mul_f32_e32 v128, v206, v128
	v_mul_f32_e32 v129, v206, v129
	v_mul_f32_e32 v146, v206, v146
	v_mul_f32_e32 v147, v206, v147
	v_mul_f32_e32 v148, v206, v148
	v_mul_f32_e32 v149, v206, v149
	v_mul_f32_e32 v138, v206, v138
	v_mul_f32_e32 v139, v206, v139
	v_mul_f32_e32 v140, v206, v140
	v_mul_f32_e32 v141, v206, v141
	v_mul_f32_e32 v118, v208, v118
	v_mul_f32_e32 v119, v208, v119
	v_mul_f32_e32 v120, v208, v120
	v_mul_f32_e32 v121, v208, v121
	v_mul_f32_e32 v110, v208, v110
	v_mul_f32_e32 v111, v208, v111
	v_mul_f32_e32 v112, v208, v112
	v_mul_f32_e32 v113, v208, v113
	v_mul_f32_e32 v130, v208, v130
	v_mul_f32_e32 v131, v208, v131
	v_mul_f32_e32 v132, v208, v132
	v_mul_f32_e32 v133, v208, v133
	v_mul_f32_e32 v122, v208, v122
	v_mul_f32_e32 v123, v208, v123
	v_mul_f32_e32 v124, v208, v124
	v_mul_f32_e32 v125, v208, v125
	v_mul_f32_e32 v102, v210, v102
	v_mul_f32_e32 v103, v210, v103
	v_mul_f32_e32 v104, v210, v104
	v_mul_f32_e32 v105, v210, v105
	v_mul_f32_e32 v98, v210, v98
	v_mul_f32_e32 v99, v210, v99
	v_mul_f32_e32 v100, v210, v100
	v_mul_f32_e32 v101, v210, v101
	v_mul_f32_e32 v114, v210, v114
	v_mul_f32_e32 v115, v210, v115
	v_mul_f32_e32 v116, v210, v116
	v_mul_f32_e32 v117, v210, v117
	v_mul_f32_e32 v106, v210, v106
	v_mul_f32_e32 v107, v210, v107
	v_mul_f32_e32 v108, v210, v108
	v_mul_f32_e32 v109, v210, v109
	v_mul_f32_e32 v90, v211, v90
	v_mul_f32_e32 v91, v211, v91
	v_mul_f32_e32 v92, v211, v92
	v_mul_f32_e32 v93, v211, v93
	v_mul_f32_e32 v86, v211, v86
	v_mul_f32_e32 v87, v211, v87
	v_mul_f32_e32 v88, v211, v88
	v_mul_f32_e32 v89, v211, v89
	v_mul_f32_e32 v94, v211, v94
	v_mul_f32_e32 v95, v211, v95
	v_mul_f32_e32 v96, v211, v96
	v_mul_f32_e32 v97, v211, v97
	v_mul_f32_e32 v82, v211, v82
	v_mul_f32_e32 v83, v211, v83
	v_mul_f32_e32 v84, v211, v84
	v_mul_f32_e32 v85, v211, v85
	v_mul_f32_e32 v42, v212, v42
	v_mul_f32_e32 v43, v212, v43
	v_mul_f32_e32 v44, v212, v44
	v_mul_f32_e32 v45, v212, v45
	v_mul_f32_e32 v38, v212, v38
	v_mul_f32_e32 v39, v212, v39
	v_mul_f32_e32 v40, v212, v40
	v_mul_f32_e32 v41, v212, v41
	v_mul_f32_e32 v46, v212, v46
	v_mul_f32_e32 v47, v212, v47
	v_mul_f32_e32 v48, v212, v48
	v_mul_f32_e32 v49, v212, v49
	v_mul_f32_e32 v34, v212, v34
	v_mul_f32_e32 v35, v212, v35
	v_mul_f32_e32 v36, v212, v36
	v_mul_f32_e32 v37, v212, v37
	v_mul_f32_e32 v26, v214, v26
	v_mul_f32_e32 v27, v214, v27
	v_mul_f32_e32 v28, v214, v28
	v_mul_f32_e32 v29, v214, v29
	v_mul_f32_e32 v22, v214, v22
	v_mul_f32_e32 v23, v214, v23
	v_mul_f32_e32 v24, v214, v24
; __device__ __forceinline__ u32x4 pack8(const float (&f)[8]) { u32x4 o; o.x = cvt_pk_bf16(f[0], f[1]); o.y = cvt_pk_bf16(f[2], f[3]); o.z = cvt_pk_bf16(f[4], f[5]); o.w = cvt_pk_bf16(f[6], f[7]); return o; }
; __device__ __forceinline__ float sigmoidf_(float x) { return __builtin_amdgcn_rcpf(1.0f + __expf(-x)); }
; __device__ __forceinline__ float dpp_ror1(float x) { return __builtin_bit_cast(float, __builtin_amdgcn_update_dpp(0, __builtin_bit_cast(int, x), 0x121, 0xf, 0xf, false)); }
; __device__ __forceinline__ float dpp_ror2(float x) { return __builtin_bit_cast(float, __builtin_amdgcn_update_dpp(0, __builtin_bit_cast(int, x), 0x122, 0xf, 0xf, false)); }
;     __device__ __forceinline__ void operator()(const f32x4 (&acc)[2][2][4][2], const Unit& u, int wr, int wc, int fr, int fq) const {
;     ...
;                 for (int m = 0; m < 4; ++m) { const int r = rbase + ai * HALF + 16 * m; const bool hi = r >= rb; const int t = hi ? r - rb : r - b0 * TP, b = hi ? b0 + 1 : b0;
;                     float o[8], uu[8], gg[8];
; #pragma unroll
;                     for (int k = 0; k < 8; ++k) { const float x = acc[ai][0][m][k >> 2][k & 3], g = acc[ai][1][m][k >> 2][k & 3]; uu[k] = x; gg[k] = g;
;                         float u1 = dpp_ror1(x), u2 = dpp_ror2(x);
;                         if (m > 0) { const float xp = acc[ai][0][m > 0 ? m - 1 : 0][k >> 2][k & 3]; const float p1 = dpp_ror1(xp), p2 = dpp_ror2(xp); u1 = fr >= 1 ? u1 : p1; u2 = fr >= 2 ? u2 : p2; }
;                         if (t == 0) u1 = 0.f; if (t <= 1) u2 = 0.f;
;                         const float uc = w0[k] * u2 + w1[k] * u1 + w2[k] * x + bb[k]; o[k] = uc * sigmoidf_(uc) * g; }
;                     if (m > 0 || fr >= 2) *(u32x4*)(ACT + (size_t)r * DFF + ch0) = pack8(o);
;                     if (m == 0 && fr < 2) { const int blk = r >> 6; *(u32x4*)(EF + ((size_t)(blk * 2 + fr) * 2) * DFF + ch0) = pack8(uu); *(u32x4*)(EF + ((size_t)(blk * 2 + fr) * 2 + 1) * DFF + ch0) = pack8(gg); }
	v_mul_f32_e32 v25, v214, v25
	v_mul_f32_e32 v30, v214, v30
	v_mul_f32_e32 v31, v214, v31
	v_mul_f32_e32 v32, v214, v32
	v_mul_f32_e32 v33, v214, v33
	v_mul_f32_e32 v18, v214, v18
	v_mul_f32_e32 v19, v214, v19
	v_mul_f32_e32 v20, v214, v20
	v_mul_f32_e32 v21, v214, v21
	v_mul_f32_e32 v10, v223, v10
	v_mul_f32_e32 v11, v223, v11
	v_mul_f32_e32 v12, v223, v12
	v_mul_f32_e32 v13, v223, v13
	v_mul_f32_e32 v6, v223, v6
	v_mul_f32_e32 v7, v223, v7
	v_mul_f32_e32 v8, v223, v8
	v_mul_f32_e32 v9, v223, v9
	v_mul_f32_e32 v14, v223, v14
	v_mul_f32_e32 v15, v223, v15
	v_mul_f32_e32 v16, v223, v16
	v_mul_f32_e32 v17, v223, v17
	v_mul_f32_e32 v2, v223, v2
	v_mul_f32_e32 v3, v223, v3
	v_mul_f32_e32 v4, v223, v4
	v_mul_f32_e32 v5, v223, v5
	s_add_i32 s55, s91, 0
	s_cmp_ge_i32 s55, s85
	s_cselect_b32 s83, s54, s35
	s_mul_i32 s32, s83, 0x810
	s_sub_i32 s32, s55, s32
	s_mul_i32 s10, s55, 0x1600
	s_add_u32 s92, s60, s10
	s_addc_u32 s93, s61, 0
	v_fma_f32 v184, v66, v150, v74
	v_fma_f32 v185, v67, v151, v75
	v_fma_f32 v186, v68, v152, v76
	v_fma_f32 v187, v69, v153, v77
	v_fma_f32 v188, v70, v142, v78
	v_fma_f32 v189, v71, v143, v79
	v_fma_f32 v190, v72, v144, v80
	v_fma_f32 v191, v73, v145, v81
	v_fmac_f32_dpp v184, v150, v58 row_shr:1 row_mask:0xf bank_mask:0xf
	v_fmac_f32_dpp v185, v151, v59 row_shr:1 row_mask:0xf bank_mask:0xf
	v_fmac_f32_dpp v186, v152, v60 row_shr:1 row_mask:0xf bank_mask:0xf
	v_fmac_f32_dpp v187, v153, v61 row_shr:1 row_mask:0xf bank_mask:0xf
	v_fmac_f32_dpp v188, v142, v62 row_shr:1 row_mask:0xf bank_mask:0xf
	v_fmac_f32_dpp v189, v143, v63 row_shr:1 row_mask:0xf bank_mask:0xf
	v_fmac_f32_dpp v190, v144, v64 row_shr:1 row_mask:0xf bank_mask:0xf
	v_fmac_f32_dpp v191, v145, v65 row_shr:1 row_mask:0xf bank_mask:0xf
	v_fmac_f32_dpp v184, v150, v50 row_shr:2 row_mask:0xf bank_mask:0xf
	v_fmac_f32_dpp v185, v151, v51 row_shr:2 row_mask:0xf bank_mask:0xf
	v_fmac_f32_dpp v186, v152, v52 row_shr:2 row_mask:0xf bank_mask:0xf
	v_fmac_f32_dpp v187, v153, v53 row_shr:2 row_mask:0xf bank_mask:0xf
	v_fmac_f32_dpp v188, v142, v54 row_shr:2 row_mask:0xf bank_mask:0xf
	v_fmac_f32_dpp v189, v143, v55 row_shr:2 row_mask:0xf bank_mask:0xf
	v_fmac_f32_dpp v190, v144, v56 row_shr:2 row_mask:0xf bank_mask:0xf
	v_fmac_f32_dpp v191, v145, v57 row_shr:2 row_mask:0xf bank_mask:0xf
	v_mul_f32_e32 v192, 0xbfb8aa3b, v184
	v_mul_f32_e32 v193, 0xbfb8aa3b, v185
	v_mul_f32_e32 v194, 0xbfb8aa3b, v186
	v_mul_f32_e32 v195, 0xbfb8aa3b, v187
	v_mul_f32_e32 v196, 0xbfb8aa3b, v188
	v_mul_f32_e32 v197, 0xbfb8aa3b, v189
	v_mul_f32_e32 v198, 0xbfb8aa3b, v190
	v_mul_f32_e32 v199, 0xbfb8aa3b, v191
	v_exp_f32_e32 v192, v192
	v_exp_f32_e32 v193, v193
	v_exp_f32_e32 v194, v194
	v_exp_f32_e32 v195, v195
	v_exp_f32_e32 v196, v196
	v_exp_f32_e32 v197, v197
	v_exp_f32_e32 v198, v198
	v_exp_f32_e32 v199, v199
	v_add_f32_e32 v192, 1.0, v192
	v_add_f32_e32 v193, 1.0, v193
	v_add_f32_e32 v194, 1.0, v194
	v_add_f32_e32 v195, 1.0, v195
	v_add_f32_e32 v196, 1.0, v196
	v_add_f32_e32 v197, 1.0, v197
	v_add_f32_e32 v198, 1.0, v198
	v_add_f32_e32 v199, 1.0, v199
	v_rcp_f32_e32 v192, v192
	v_rcp_f32_e32 v193, v193
	v_rcp_f32_e32 v194, v194
	v_rcp_f32_e32 v195, v195
	v_rcp_f32_e32 v196, v196
	v_rcp_f32_e32 v197, v197
	v_rcp_f32_e32 v198, v198
	v_rcp_f32_e32 v199, v199
	v_mul_f32_e32 v184, v184, v192
	v_mul_f32_e32 v185, v185, v193
	v_mul_f32_e32 v186, v186, v194
	v_mul_f32_e32 v187, v187, v195
	v_mul_f32_e32 v188, v188, v196
	v_mul_f32_e32 v189, v189, v197
	v_mul_f32_e32 v190, v190, v198
	v_mul_f32_e32 v191, v191, v199
	v_mul_f32_e32 v184, v158, v184
	v_mul_f32_e32 v185, v159, v185
	v_mul_f32_e32 v186, v160, v186
	v_mul_f32_e32 v187, v161, v187
	v_mul_f32_e32 v188, v154, v188
	v_mul_f32_e32 v189, v155, v189
	v_mul_f32_e32 v190, v156, v190
	v_mul_f32_e32 v191, v157, v191
	v_cvt_pk_bf16_f32 v200, v184, v185
	v_cvt_pk_bf16_f32 v201, v186, v187
	v_cvt_pk_bf16_f32 v202, v188, v189
	v_cvt_pk_bf16_f32 v203, v190, v191
	s_lshr_b32 s10, s55, 6
	s_mul_i32 s10, s10, 0x5800
	s_add_u32 s94, s62, s10
	s_addc_u32 s95, s63, 0
	s_mov_b64 exec, s[4:5]
	global_store_dwordx4 v183, v[200:203], s[92:93]
	s_mov_b64 exec, s[6:7]
	v_cvt_pk_bf16_f32 v228, v150, v151
	v_cvt_pk_bf16_f32 v229, v152, v153
	v_cvt_pk_bf16_f32 v230, v142, v143
	v_cvt_pk_bf16_f32 v231, v144, v145
	v_cvt_pk_bf16_f32 v232, v158, v159
	v_cvt_pk_bf16_f32 v233, v160, v161
	v_cvt_pk_bf16_f32 v234, v154, v155
	v_cvt_pk_bf16_f32 v235, v156, v157
	global_store_dwordx4 v236, v[228:231], s[94:95]
	global_store_dwordx4 v237, v[232:235], s[94:95]
	s_mov_b64 exec, -1
	s_cmpk_lg_i32 s32, 0x800
	s_cbranch_scc1 .Lp8e_noout_00
	s_mul_i32 s10, s83, 0x5800
	s_add_u32 s94, s72, s10
	s_addc_u32 s95, s73, 0
	s_mov_b64 exec, s[8:9]
	global_store_dwordx4 v239, v[150:153], s[94:95]
	global_store_dwordx4 v239, v[142:145], s[94:95] offset:16
	s_mov_b64 exec, -1

; __device__ __forceinline__ u32x4 pack8(const float (&f)[8]) { u32x4 o; o.x = cvt_pk_bf16(f[0], f[1]); o.y = cvt_pk_bf16(f[2], f[3]); o.z = cvt_pk_bf16(f[4], f[5]); o.w = cvt_pk_bf16(f[6], f[7]); return o; }
; __device__ __forceinline__ float sigmoidf_(float x) { return __builtin_amdgcn_rcpf(1.0f + __expf(-x)); }
; __device__ __forceinline__ float dpp_ror1(float x) { return __builtin_bit_cast(float, __builtin_amdgcn_update_dpp(0, __builtin_bit_cast(int, x), 0x121, 0xf, 0xf, false)); }
; __device__ __forceinline__ float dpp_ror2(float x) { return __builtin_bit_cast(float, __builtin_amdgcn_update_dpp(0, __builtin_bit_cast(int, x), 0x122, 0xf, 0xf, false)); }
;     __device__ __forceinline__ void operator()(const f32x4 (&acc)[2][2][4][2], const Unit& u, int wr, int wc, int fr, int fq) const {
;     ...
;                 for (int m = 0; m < 4; ++m) { const int r = rbase + ai * HALF + 16 * m; const bool hi = r >= rb; const int t = hi ? r - rb : r - b0 * TP, b = hi ? b0 + 1 : b0;
;                     float o[8], uu[8], gg[8];
; #pragma unroll
;                     for (int k = 0; k < 8; ++k) { const float x = acc[ai][0][m][k >> 2][k & 3], g = acc[ai][1][m][k >> 2][k & 3]; uu[k] = x; gg[k] = g;
;                         float u1 = dpp_ror1(x), u2 = dpp_ror2(x);
;                         if (m > 0) { const float xp = acc[ai][0][m > 0 ? m - 1 : 0][k >> 2][k & 3]; const float p1 = dpp_ror1(xp), p2 = dpp_ror2(xp); u1 = fr >= 1 ? u1 : p1; u2 = fr >= 2 ? u2 : p2; }
;                         if (t == 0) u1 = 0.f; if (t <= 1) u2 = 0.f;
;                         const float uc = w0[k] * u2 + w1[k] * u1 + w2[k] * x + bb[k]; o[k] = uc * sigmoidf_(uc) * g; }
;                     if (m > 0 || fr >= 2) *(u32x4*)(ACT + (size_t)r * DFF + ch0) = pack8(o);
;                     if (m == 0 && fr < 2) { const int blk = r >> 6; *(u32x4*)(EF + ((size_t)(blk * 2 + fr) * 2) * DFF + ch0) = pack8(uu); *(u32x4*)(EF + ((size_t)(blk * 2 + fr) * 2 + 1) * DFF + ch0) = pack8(gg); }
;                     if (m == 3 && fr >= 14) { const int blk = r >> 6; *(u32x4*)(EL + (size_t)(blk * 2 + (fr - 14)) * DFF + ch0) = pack8(uu); }
;                     if (t >= TP - 2) store8f(outp + ((size_t)(b * 2) + (t - (TP - 2))) * DFF + ch0, uu); }
.Lp8e_noout_03:
	s_cmp_eq_u32 s90, 64
	s_cbranch_scc1 .Lp8e_smp_10
	s_add_i32 s55, s91, 128
	s_cmp_ge_i32 s55, s85
	s_cselect_b32 s83, s54, s35
	s_mul_i32 s32, s83, 0x810
	s_sub_i32 s32, s55, s32
	s_mul_i32 s10, s55, 0x1600
	s_add_u32 s92, s60, s10
	s_addc_u32 s93, s61, 0
	v_fma_f32 v184, v66, v90, v74
	v_fma_f32 v185, v67, v91, v75
	v_fma_f32 v186, v68, v92, v76
	v_fma_f32 v187, v69, v93, v77
	v_fma_f32 v188, v70, v86, v78
	v_fma_f32 v189, v71, v87, v79
	v_fma_f32 v190, v72, v88, v80
	v_fma_f32 v191, v73, v89, v81
	v_fmac_f32_dpp v184, v90, v58 row_shr:1 row_mask:0xf bank_mask:0xf
	v_fmac_f32_dpp v185, v91, v59 row_shr:1 row_mask:0xf bank_mask:0xf
	v_fmac_f32_dpp v186, v92, v60 row_shr:1 row_mask:0xf bank_mask:0xf
	v_fmac_f32_dpp v187, v93, v61 row_shr:1 row_mask:0xf bank_mask:0xf
	v_fmac_f32_dpp v188, v86, v62 row_shr:1 row_mask:0xf bank_mask:0xf
	v_fmac_f32_dpp v189, v87, v63 row_shr:1 row_mask:0xf bank_mask:0xf
	v_fmac_f32_dpp v190, v88, v64 row_shr:1 row_mask:0xf bank_mask:0xf
	v_fmac_f32_dpp v191, v89, v65 row_shr:1 row_mask:0xf bank_mask:0xf
	v_fmac_f32_dpp v184, v90, v50 row_shr:2 row_mask:0xf bank_mask:0xf
	v_fmac_f32_dpp v185, v91, v51 row_shr:2 row_mask:0xf bank_mask:0xf
	v_fmac_f32_dpp v186, v92, v52 row_shr:2 row_mask:0xf bank_mask:0xf
	v_fmac_f32_dpp v187, v93, v53 row_shr:2 row_mask:0xf bank_mask:0xf
	v_fmac_f32_dpp v188, v86, v54 row_shr:2 row_mask:0xf bank_mask:0xf
	v_fmac_f32_dpp v189, v87, v55 row_shr:2 row_mask:0xf bank_mask:0xf
	v_fmac_f32_dpp v190, v88, v56 row_shr:2 row_mask:0xf bank_mask:0xf
	v_fmac_f32_dpp v191, v89, v57 row_shr:2 row_mask:0xf bank_mask:0xf
	v_mul_f32_e32 v192, 0xbfb8aa3b, v184
	v_mul_f32_e32 v193, 0xbfb8aa3b, v185
	v_mul_f32_e32 v194, 0xbfb8aa3b, v186
	v_mul_f32_e32 v195, 0xbfb8aa3b, v187
	v_mul_f32_e32 v196, 0xbfb8aa3b, v188
	v_mul_f32_e32 v197, 0xbfb8aa3b, v189
	v_mul_f32_e32 v198, 0xbfb8aa3b, v190
	v_mul_f32_e32 v199, 0xbfb8aa3b, v191
	v_exp_f32_e32 v192, v192
	v_exp_f32_e32 v193, v193
	v_exp_f32_e32 v194, v194
	v_exp_f32_e32 v195, v195
	v_exp_f32_e32 v196, v196
	v_exp_f32_e32 v197, v197
	v_exp_f32_e32 v198, v198
	v_exp_f32_e32 v199, v199
	v_add_f32_e32 v192, 1.0, v192
	v_add_f32_e32 v193, 1.0, v193
	v_add_f32_e32 v194, 1.0, v194
	v_add_f32_e32 v195, 1.0, v195
	v_add_f32_e32 v196, 1.0, v196
	v_add_f32_e32 v197, 1.0, v197
	v_add_f32_e32 v198, 1.0, v198
	v_add_f32_e32 v199, 1.0, v199
	v_rcp_f32_e32 v192, v192
	v_rcp_f32_e32 v193, v193
	v_rcp_f32_e32 v194, v194
	v_rcp_f32_e32 v195, v195
	v_rcp_f32_e32 v196, v196
	v_rcp_f32_e32 v197, v197
	v_rcp_f32_e32 v198, v198
	v_rcp_f32_e32 v199, v199
	v_mul_f32_e32 v184, v184, v192
	v_mul_f32_e32 v185, v185, v193
	v_mul_f32_e32 v186, v186, v194
	v_mul_f32_e32 v187, v187, v195
	v_mul_f32_e32 v188, v188, v196
	v_mul_f32_e32 v189, v189, v197
	v_mul_f32_e32 v190, v190, v198
	v_mul_f32_e32 v191, v191, v199
	v_mul_f32_e32 v184, v94, v184
	v_mul_f32_e32 v185, v95, v185
	v_mul_f32_e32 v186, v96, v186
	v_mul_f32_e32 v187, v97, v187
	v_mul_f32_e32 v188, v82, v188
	v_mul_f32_e32 v189, v83, v189
	v_mul_f32_e32 v190, v84, v190
	v_mul_f32_e32 v191, v85, v191
	v_cvt_pk_bf16_f32 v200, v184, v185
	v_cvt_pk_bf16_f32 v201, v186, v187
	v_cvt_pk_bf16_f32 v202, v188, v189
	v_cvt_pk_bf16_f32 v203, v190, v191
	s_lshr_b32 s10, s55, 6
	s_mul_i32 s10, s10, 0x5800
	s_add_u32 s94, s62, s10
	s_addc_u32 s95, s63, 0
	s_mov_b64 exec, s[4:5]
	global_store_dwordx4 v183, v[200:203], s[92:93]
	s_mov_b64 exec, s[6:7]
	v_cvt_pk_bf16_f32 v228, v90, v91
	v_cvt_pk_bf16_f32 v229, v92, v93
	v_cvt_pk_bf16_f32 v230, v86, v87
	v_cvt_pk_bf16_f32 v231, v88, v89
	v_cvt_pk_bf16_f32 v232, v94, v95
	v_cvt_pk_bf16_f32 v233, v96, v97
	v_cvt_pk_bf16_f32 v234, v82, v83
	v_cvt_pk_bf16_f32 v235, v84, v85
	global_store_dwordx4 v236, v[228:231], s[94:95]
	global_store_dwordx4 v237, v[232:235], s[94:95]
	s_mov_b64 exec, -1
	s_cmpk_lg_i32 s32, 0x800
	s_cbranch_scc1 .Lp8e_noout_10
	s_mul_i32 s10, s83, 0x5800
	s_add_u32 s94, s72, s10
	s_addc_u32 s95, s73, 0
	s_mov_b64 exec, s[8:9]
	global_store_dwordx4 v239, v[90:93], s[94:95]
	global_store_dwordx4 v239, v[86:89], s[94:95] offset:16
	s_mov_b64 exec, -1

; __device__ __forceinline__ u32x4 pack8(const float (&f)[8]) { u32x4 o; o.x = cvt_pk_bf16(f[0], f[1]); o.y = cvt_pk_bf16(f[2], f[3]); o.z = cvt_pk_bf16(f[4], f[5]); o.w = cvt_pk_bf16(f[6], f[7]); return o; }
; __device__ __forceinline__ float sigmoidf_(float x) { return __builtin_amdgcn_rcpf(1.0f + __expf(-x)); }
; __device__ __forceinline__ float dpp_ror1(float x) { return __builtin_bit_cast(float, __builtin_amdgcn_update_dpp(0, __builtin_bit_cast(int, x), 0x121, 0xf, 0xf, false)); }
;     __device__ __forceinline__ void operator()(const f32x4 (&acc)[2][2][4][2], const Unit& u, int wr, int wc, int fr, int fq) const {
;     ...
;             if (u.pm == 64 && ai == 1) {
; #pragma unroll
;                 for (int m = 0; m < 4; ++m) { const int r = rbase + HALF + 16 * m, sb = r - MP;
;                     float u2[8], u1[8], o[8], uu[8]; load8f(st + (size_t)(sb * 2) * DFF + ch0, u2); load8f(st + (size_t)(sb * 2 + 1) * DFF + ch0, u1);
; #pragma unroll
;                     for (int k = 0; k < 8; ++k) { const float x = acc[1][0][m][k >> 2][k & 3], g = acc[1][1][m][k >> 2][k & 3]; uu[k] = x;
;                         const float uc = w0[k] * u2[k] + w1[k] * u1[k] + w2[k] * x + bb[k]; o[k] = uc * sigmoidf_(uc) * g; }
;                     *(u32x4*)(ACT + (size_t)r * DFF + ch0) = pack8(o);
;                     store8f(outs + (size_t)(sb * 2) * DFF + ch0, u1); store8f(outs + (size_t)(sb * 2 + 1) * DFF + ch0, uu); }
;     ...
;                 for (int m = 0; m < 4; ++m) { const int r = rbase + ai * HALF + 16 * m; const bool hi = r >= rb; const int t = hi ? r - rb : r - b0 * TP, b = hi ? b0 + 1 : b0;
;                     float o[8], uu[8], gg[8];
; #pragma unroll
;                     for (int k = 0; k < 8; ++k) { const float x = acc[ai][0][m][k >> 2][k & 3], g = acc[ai][1][m][k >> 2][k & 3]; uu[k] = x; gg[k] = g;
;                         float u1 = dpp_ror1(x), u2 = dpp_ror2(x);
;                         if (m > 0) { const float xp = acc[ai][0][m > 0 ? m - 1 : 0][k >> 2][k & 3]; const float p1 = dpp_ror1(xp), p2 = dpp_ror2(xp); u1 = fr >= 1 ? u1 : p1; u2 = fr >= 2 ? u2 : p2; }
;                         if (t == 0) u1 = 0.f; if (t <= 1) u2 = 0.f;
;                         const float uc = w0[k] * u2 + w1[k] * u1 + w2[k] * x + bb[k]; o[k] = uc * sigmoidf_(uc) * g; }
.Lp8e_smp_10:
	s_add_i32 s55, s91, 128
	s_mul_i32 s10, s55, 0x1600
	s_add_u32 s92, s60, s10
	s_addc_u32 s93, s61, 0
	s_add_i32 s10, s18, 0
	s_mul_i32 s10, s10, 0x5800
	s_add_u32 s94, s70, s10
	s_addc_u32 s95, s71, 0
	s_add_u32 s98, s94, 0x2c00
	s_addc_u32 s99, s95, 0
	global_load_dwordx4 v[228:231], v248, s[94:95]
	global_load_dwordx4 v[232:235], v248, s[94:95] offset:16
	global_load_dwordx4 v[240:243], v248, s[98:99]
	global_load_dwordx4 v[244:247], v248, s[98:99] offset:16
	s_add_u32 s94, s74, s10
	s_addc_u32 s95, s75, 0
	s_add_u32 s98, s94, 0x2c00
	s_addc_u32 s99, s95, 0
	v_fma_f32 v184, v66, v90, v74
	v_fma_f32 v185, v67, v91, v75
	v_fma_f32 v186, v68, v92, v76
	v_fma_f32 v187, v69, v93, v77
	v_fma_f32 v188, v70, v86, v78
	v_fma_f32 v189, v71, v87, v79
	v_fma_f32 v190, v72, v88, v80
	v_fma_f32 v191, v73, v89, v81
	s_waitcnt vmcnt(0)
	v_fmac_f32_e32 v184, v58, v240
	v_fmac_f32_e32 v185, v59, v241
	v_fmac_f32_e32 v186, v60, v242
	v_fmac_f32_e32 v187, v61, v243
	v_fmac_f32_e32 v188, v62, v244
	v_fmac_f32_e32 v189, v63, v245
	v_fmac_f32_e32 v190, v64, v246
	v_fmac_f32_e32 v191, v65, v247
	v_fmac_f32_e32 v184, v50, v228
	v_fmac_f32_e32 v185, v51, v229
	v_fmac_f32_e32 v186, v52, v230
	v_fmac_f32_e32 v187, v53, v231
	v_fmac_f32_e32 v188, v54, v232
	v_fmac_f32_e32 v189, v55, v233
	v_fmac_f32_e32 v190, v56, v234
	v_fmac_f32_e32 v191, v57, v235
	v_mul_f32_e32 v192, 0xbfb8aa3b, v184
	v_mul_f32_e32 v193, 0xbfb8aa3b, v185
	v_mul_f32_e32 v194, 0xbfb8aa3b, v186
	v_mul_f32_e32 v195, 0xbfb8aa3b, v187
	v_mul_f32_e32 v196, 0xbfb8aa3b, v188
	v_mul_f32_e32 v197, 0xbfb8aa3b, v189
	v_mul_f32_e32 v198, 0xbfb8aa3b, v190
	v_mul_f32_e32 v199, 0xbfb8aa3b, v191
	v_exp_f32_e32 v192, v192
	v_exp_f32_e32 v193, v193
	v_exp_f32_e32 v194, v194
	v_exp_f32_e32 v195, v195
	v_exp_f32_e32 v196, v196
	v_exp_f32_e32 v197, v197
	v_exp_f32_e32 v198, v198
	v_exp_f32_e32 v199, v199
	v_add_f32_e32 v192, 1.0, v192
	v_add_f32_e32 v193, 1.0, v193
	v_add_f32_e32 v194, 1.0, v194
	v_add_f32_e32 v195, 1.0, v195
	v_add_f32_e32 v196, 1.0, v196
	v_add_f32_e32 v197, 1.0, v197
	v_add_f32_e32 v198, 1.0, v198
	v_add_f32_e32 v199, 1.0, v199
	v_rcp_f32_e32 v192, v192
	v_rcp_f32_e32 v193, v193
	v_rcp_f32_e32 v194, v194
	v_rcp_f32_e32 v195, v195
	v_rcp_f32_e32 v196, v196
	v_rcp_f32_e32 v197, v197
	v_rcp_f32_e32 v198, v198
	v_rcp_f32_e32 v199, v199
	v_mul_f32_e32 v184, v184, v192
	v_mul_f32_e32 v185, v185, v193
	v_mul_f32_e32 v186, v186, v194
	v_mul_f32_e32 v187, v187, v195
	v_mul_f32_e32 v188, v188, v196
	v_mul_f32_e32 v189, v189, v197
	v_mul_f32_e32 v190, v190, v198
	v_mul_f32_e32 v191, v191, v199
	v_mul_f32_e32 v184, v94, v184
	v_mul_f32_e32 v185, v95, v185
	v_mul_f32_e32 v186, v96, v186
	v_mul_f32_e32 v187, v97, v187
	v_mul_f32_e32 v188, v82, v188
	v_mul_f32_e32 v189, v83, v189
	v_mul_f32_e32 v190, v84, v190
	v_mul_f32_e32 v191, v85, v191
	v_cvt_pk_bf16_f32 v200, v184, v185
	v_cvt_pk_bf16_f32 v201, v186, v187
	v_cvt_pk_bf16_f32 v202, v188, v189
	v_cvt_pk_bf16_f32 v203, v190, v191
	global_store_dwordx4 v183, v[200:203], s[92:93]
	global_store_dwordx4 v248, v[240:243], s[94:95]
	global_store_dwordx4 v248, v[244:247], s[94:95] offset:16
	global_store_dwordx4 v248, v[90:93], s[98:99]
	global_store_dwordx4 v248, v[86:89], s[98:99] offset:16
	s_nop 1
.Lp8e_end_10:
	s_cmp_eq_u32 s90, 64
	s_cbranch_scc1 .Lp8e_smp_11
	s_add_i32 s55, s91, 144
	s_cmp_ge_i32 s55, s85
	s_cselect_b32 s83, s54, s35
	s_mul_i32 s32, s83, 0x810
	s_sub_i32 s32, s55, s32
	s_mul_i32 s10, s55, 0x1600
	s_add_u32 s92, s60, s10
	s_addc_u32 s93, s61, 0
	v_fma_f32 v184, v66, v42, v74
	v_fma_f32 v185, v67, v43, v75
	v_fma_f32 v186, v68, v44, v76
	v_fma_f32 v187, v69, v45, v77
	v_fma_f32 v188, v70, v38, v78
	v_fma_f32 v189, v71, v39, v79
	v_fma_f32 v190, v72, v40, v80
	v_fma_f32 v191, v73, v41, v81
	v_fmac_f32_dpp v184, v42, v58 row_shr:1 row_mask:0xf bank_mask:0xf
	v_fmac_f32_dpp v185, v43, v59 row_shr:1 row_mask:0xf bank_mask:0xf
	v_fmac_f32_dpp v186, v44, v60 row_shr:1 row_mask:0xf bank_mask:0xf
	v_fmac_f32_dpp v187, v45, v61 row_shr:1 row_mask:0xf bank_mask:0xf
	v_fmac_f32_dpp v188, v38, v62 row_shr:1 row_mask:0xf bank_mask:0xf
	v_fmac_f32_dpp v189, v39, v63 row_shr:1 row_mask:0xf bank_mask:0xf
	v_fmac_f32_dpp v190, v40, v64 row_shr:1 row_mask:0xf bank_mask:0xf
	v_fmac_f32_dpp v191, v41, v65 row_shr:1 row_mask:0xf bank_mask:0xf
	v_fmac_f32_dpp v184, v42, v50 row_shr:2 row_mask:0xf bank_mask:0xf
	v_fmac_f32_dpp v185, v43, v51 row_shr:2 row_mask:0xf bank_mask:0xf
	v_fmac_f32_dpp v186, v44, v52 row_shr:2 row_mask:0xf bank_mask:0xf
	v_fmac_f32_dpp v187, v45, v53 row_shr:2 row_mask:0xf bank_mask:0xf
	v_fmac_f32_dpp v188, v38, v54 row_shr:2 row_mask:0xf bank_mask:0xf
	v_fmac_f32_dpp v189, v39, v55 row_shr:2 row_mask:0xf bank_mask:0xf
	v_fmac_f32_dpp v190, v40, v56 row_shr:2 row_mask:0xf bank_mask:0xf
	v_fmac_f32_dpp v191, v41, v57 row_shr:2 row_mask:0xf bank_mask:0xf
	s_cmp_eq_u32 s32, 0
	s_cbranch_scc1 .Lp8e_nohalo_11
	v_fmac_f32_dpp v184, v90, v58 row_shl:15 row_mask:0xf bank_mask:0xf
	v_fmac_f32_dpp v185, v91, v59 row_shl:15 row_mask:0xf bank_mask:0xf
	v_fmac_f32_dpp v186, v92, v60 row_shl:15 row_mask:0xf bank_mask:0xf
	v_fmac_f32_dpp v187, v93, v61 row_shl:15 row_mask:0xf bank_mask:0xf
	v_fmac_f32_dpp v188, v86, v62 row_shl:15 row_mask:0xf bank_mask:0xf
	v_fmac_f32_dpp v189, v87, v63 row_shl:15 row_mask:0xf bank_mask:0xf
	v_fmac_f32_dpp v190, v88, v64 row_shl:15 row_mask:0xf bank_mask:0xf
	v_fmac_f32_dpp v191, v89, v65 row_shl:15 row_mask:0xf bank_mask:0xf
	v_fmac_f32_dpp v184, v90, v50 row_shl:14 row_mask:0xf bank_mask:0xf
	v_fmac_f32_dpp v185, v91, v51 row_shl:14 row_mask:0xf bank_mask:0xf
	v_fmac_f32_dpp v186, v92, v52 row_shl:14 row_mask:0xf bank_mask:0xf
	v_fmac_f32_dpp v187, v93, v53 row_shl:14 row_mask:0xf bank_mask:0xf
	v_fmac_f32_dpp v188, v86, v54 row_shl:14 row_mask:0xf bank_mask:0xf
	v_fmac_f32_dpp v189, v87, v55 row_shl:14 row_mask:0xf bank_mask:0xf
	v_fmac_f32_dpp v190, v88, v56 row_shl:14 row_mask:0xf bank_mask:0xf
	v_fmac_f32_dpp v191, v89, v57 row_shl:14 row_mask:0xf bank_mask:0xf
; __device__ __forceinline__ u32x4 pack8(const float (&f)[8]) { u32x4 o; o.x = cvt_pk_bf16(f[0], f[1]); o.y = cvt_pk_bf16(f[2], f[3]); o.z = cvt_pk_bf16(f[4], f[5]); o.w = cvt_pk_bf16(f[6], f[7]); return o; }
; __device__ __forceinline__ float sigmoidf_(float x) { return __builtin_amdgcn_rcpf(1.0f + __expf(-x)); }
;     __device__ __forceinline__ void operator()(const f32x4 (&acc)[2][2][4][2], const Unit& u, int wr, int wc, int fr, int fq) const {
;     ...
;             if (u.pm == 64 && ai == 1) {
; #pragma unroll
;                 for (int m = 0; m < 4; ++m) { const int r = rbase + HALF + 16 * m, sb = r - MP;
;                     float u2[8], u1[8], o[8], uu[8]; load8f(st + (size_t)(sb * 2) * DFF + ch0, u2); load8f(st + (size_t)(sb * 2 + 1) * DFF + ch0, u1);
; #pragma unroll
;                     for (int k = 0; k < 8; ++k) { const float x = acc[1][0][m][k >> 2][k & 3], g = acc[1][1][m][k >> 2][k & 3]; uu[k] = x;
;                         const float uc = w0[k] * u2[k] + w1[k] * u1[k] + w2[k] * x + bb[k]; o[k] = uc * sigmoidf_(uc) * g; }
;                     *(u32x4*)(ACT + (size_t)r * DFF + ch0) = pack8(o);
;                     store8f(outs + (size_t)(sb * 2) * DFF + ch0, u1); store8f(outs + (size_t)(sb * 2 + 1) * DFF + ch0, uu); }
;     ...
;                         const float uc = w0[k] * u2 + w1[k] * u1 + w2[k] * x + bb[k]; o[k] = uc * sigmoidf_(uc) * g; }
;                     if (m > 0 || fr >= 2) *(u32x4*)(ACT + (size_t)r * DFF + ch0) = pack8(o);
;                     if (m == 0 && fr < 2) { const int blk = r >> 6; *(u32x4*)(EF + ((size_t)(blk * 2 + fr) * 2) * DFF + ch0) = pack8(uu); *(u32x4*)(EF + ((size_t)(blk * 2 + fr) * 2 + 1) * DFF + ch0) = pack8(gg); }
;                     if (m == 3 && fr >= 14) { const int blk = r >> 6; *(u32x4*)(EL + (size_t)(blk * 2 + (fr - 14)) * DFF + ch0) = pack8(uu); }
;                     if (t >= TP - 2) store8f(outp + ((size_t)(b * 2) + (t - (TP - 2))) * DFF + ch0, uu); }
.Lp8e_nohalo_11:
	v_mul_f32_e32 v192, 0xbfb8aa3b, v184
	v_mul_f32_e32 v193, 0xbfb8aa3b, v185
	v_mul_f32_e32 v194, 0xbfb8aa3b, v186
	v_mul_f32_e32 v195, 0xbfb8aa3b, v187
	v_mul_f32_e32 v196, 0xbfb8aa3b, v188
	v_mul_f32_e32 v197, 0xbfb8aa3b, v189
	v_mul_f32_e32 v198, 0xbfb8aa3b, v190
	v_mul_f32_e32 v199, 0xbfb8aa3b, v191
	v_exp_f32_e32 v192, v192
	v_exp_f32_e32 v193, v193
	v_exp_f32_e32 v194, v194
	v_exp_f32_e32 v195, v195
	v_exp_f32_e32 v196, v196
	v_exp_f32_e32 v197, v197
	v_exp_f32_e32 v198, v198
	v_exp_f32_e32 v199, v199
	v_add_f32_e32 v192, 1.0, v192
	v_add_f32_e32 v193, 1.0, v193
	v_add_f32_e32 v194, 1.0, v194
	v_add_f32_e32 v195, 1.0, v195
	v_add_f32_e32 v196, 1.0, v196
	v_add_f32_e32 v197, 1.0, v197
	v_add_f32_e32 v198, 1.0, v198
	v_add_f32_e32 v199, 1.0, v199
	v_rcp_f32_e32 v192, v192
	v_rcp_f32_e32 v193, v193
	v_rcp_f32_e32 v194, v194
	v_rcp_f32_e32 v195, v195
	v_rcp_f32_e32 v196, v196
	v_rcp_f32_e32 v197, v197
	v_rcp_f32_e32 v198, v198
	v_rcp_f32_e32 v199, v199
	v_mul_f32_e32 v184, v184, v192
	v_mul_f32_e32 v185, v185, v193
	v_mul_f32_e32 v186, v186, v194
	v_mul_f32_e32 v187, v187, v195
	v_mul_f32_e32 v188, v188, v196
	v_mul_f32_e32 v189, v189, v197
	v_mul_f32_e32 v190, v190, v198
	v_mul_f32_e32 v191, v191, v199
	v_mul_f32_e32 v184, v46, v184
	v_mul_f32_e32 v185, v47, v185
	v_mul_f32_e32 v186, v48, v186
	v_mul_f32_e32 v187, v49, v187
	v_mul_f32_e32 v188, v34, v188
	v_mul_f32_e32 v189, v35, v189
	v_mul_f32_e32 v190, v36, v190
	v_mul_f32_e32 v191, v37, v191
	v_cvt_pk_bf16_f32 v224, v184, v185
	v_cvt_pk_bf16_f32 v225, v186, v187
	v_cvt_pk_bf16_f32 v226, v188, v189
	v_cvt_pk_bf16_f32 v227, v190, v191
	global_store_dwordx4 v183, v[224:227], s[92:93]
	s_cmpk_lg_i32 s32, 0x800
	s_cbranch_scc1 .Lp8e_noout_11
	s_mul_i32 s10, s83, 0x5800
	s_add_u32 s94, s72, s10
	s_addc_u32 s95, s73, 0
	s_mov_b64 exec, s[8:9]
	global_store_dwordx4 v239, v[42:45], s[94:95]
	global_store_dwordx4 v239, v[38:41], s[94:95] offset:16
	s_mov_b64 exec, -1
.Lp8e_noout_11:
	s_branch .Lp8e_end_11
.Lp8e_smp_11:
	s_add_i32 s55, s91, 144
	s_mul_i32 s10, s55, 0x1600
	s_add_u32 s92, s60, s10
	s_addc_u32 s93, s61, 0
	s_add_i32 s10, s18, 16
	s_mul_i32 s10, s10, 0x5800
	s_add_u32 s94, s70, s10
	s_addc_u32 s95, s71, 0
	s_add_u32 s98, s94, 0x2c00
	s_addc_u32 s99, s95, 0
	global_load_dwordx4 v[228:231], v248, s[94:95]
	global_load_dwordx4 v[232:235], v248, s[94:95] offset:16
	global_load_dwordx4 v[240:243], v248, s[98:99]
	global_load_dwordx4 v[244:247], v248, s[98:99] offset:16
	s_add_u32 s94, s74, s10
	s_addc_u32 s95, s75, 0
	s_add_u32 s98, s94, 0x2c00
	s_addc_u32 s99, s95, 0
	v_fma_f32 v184, v66, v42, v74
	v_fma_f32 v185, v67, v43, v75
	v_fma_f32 v186, v68, v44, v76
	v_fma_f32 v187, v69, v45, v77
	v_fma_f32 v188, v70, v38, v78
	v_fma_f32 v189, v71, v39, v79
	v_fma_f32 v190, v72, v40, v80
	v_fma_f32 v191, v73, v41, v81
	s_waitcnt vmcnt(0)
	v_fmac_f32_e32 v184, v58, v240
	v_fmac_f32_e32 v185, v59, v241
	v_fmac_f32_e32 v186, v60, v242
	v_fmac_f32_e32 v187, v61, v243
	v_fmac_f32_e32 v188, v62, v244
	v_fmac_f32_e32 v189, v63, v245
	v_fmac_f32_e32 v190, v64, v246
	v_fmac_f32_e32 v191, v65, v247
	v_fmac_f32_e32 v184, v50, v228
	v_fmac_f32_e32 v185, v51, v229
	v_fmac_f32_e32 v186, v52, v230
	v_fmac_f32_e32 v187, v53, v231
	v_fmac_f32_e32 v188, v54, v232
	v_fmac_f32_e32 v189, v55, v233
	v_fmac_f32_e32 v190, v56, v234
	v_fmac_f32_e32 v191, v57, v235
	v_mul_f32_e32 v192, 0xbfb8aa3b, v184
	v_mul_f32_e32 v193, 0xbfb8aa3b, v185
	v_mul_f32_e32 v194, 0xbfb8aa3b, v186
	v_mul_f32_e32 v195, 0xbfb8aa3b, v187
	v_mul_f32_e32 v196, 0xbfb8aa3b, v188
	v_mul_f32_e32 v197, 0xbfb8aa3b, v189
	v_mul_f32_e32 v198, 0xbfb8aa3b, v190
	v_mul_f32_e32 v199, 0xbfb8aa3b, v191
	v_exp_f32_e32 v192, v192
	v_exp_f32_e32 v193, v193
	v_exp_f32_e32 v194, v194
	v_exp_f32_e32 v195, v195
	v_exp_f32_e32 v196, v196
	v_exp_f32_e32 v197, v197
	v_exp_f32_e32 v198, v198
	v_exp_f32_e32 v199, v199
	v_add_f32_e32 v192, 1.0, v192
	v_add_f32_e32 v193, 1.0, v193
	v_add_f32_e32 v194, 1.0, v194
	v_add_f32_e32 v195, 1.0, v195
	v_add_f32_e32 v196, 1.0, v196
	v_add_f32_e32 v197, 1.0, v197
	v_add_f32_e32 v198, 1.0, v198
	v_add_f32_e32 v199, 1.0, v199
	v_rcp_f32_e32 v192, v192
	v_rcp_f32_e32 v193, v193
	v_rcp_f32_e32 v194, v194
	v_rcp_f32_e32 v195, v195
	v_rcp_f32_e32 v196, v196
	v_rcp_f32_e32 v197, v197
	v_rcp_f32_e32 v198, v198
	v_rcp_f32_e32 v199, v199
	v_mul_f32_e32 v184, v184, v192
	v_mul_f32_e32 v185, v185, v193
	v_mul_f32_e32 v186, v186, v194
	v_mul_f32_e32 v187, v187, v195
	v_mul_f32_e32 v188, v188, v196
	v_mul_f32_e32 v189, v189, v197
	v_mul_f32_e32 v190, v190, v198
	v_mul_f32_e32 v191, v191, v199
	v_mul_f32_e32 v184, v46, v184
	v_mul_f32_e32 v185, v47, v185
	v_mul_f32_e32 v186, v48, v186
	v_mul_f32_e32 v187, v49, v187
	v_mul_f32_e32 v188, v34, v188
	v_mul_f32_e32 v189, v35, v189
	v_mul_f32_e32 v190, v36, v190
	v_mul_f32_e32 v191, v37, v191
	v_cvt_pk_bf16_f32 v224, v184, v185
	v_cvt_pk_bf16_f32 v225, v186, v187
	v_cvt_pk_bf16_f32 v226, v188, v189
	v_cvt_pk_bf16_f32 v227, v190, v191
	global_store_dwordx4 v183, v[224:227], s[92:93]
	global_store_dwordx4 v248, v[240:243], s[94:95]
	global_store_dwordx4 v248, v[244:247], s[94:95] offset:16
	global_store_dwordx4 v248, v[42:45], s[98:99]
	global_store_dwordx4 v248, v[38:41], s[98:99] offset:16
	s_nop 1
; __device__ __forceinline__ u32x4 pack8(const float (&f)[8]) { u32x4 o; o.x = cvt_pk_bf16(f[0], f[1]); o.y = cvt_pk_bf16(f[2], f[3]); o.z = cvt_pk_bf16(f[4], f[5]); o.w = cvt_pk_bf16(f[6], f[7]); return o; }
; __device__ __forceinline__ float sigmoidf_(float x) { return __builtin_amdgcn_rcpf(1.0f + __expf(-x)); }
; __device__ __forceinline__ float dpp_ror1(float x) { return __builtin_bit_cast(float, __builtin_amdgcn_update_dpp(0, __builtin_bit_cast(int, x), 0x121, 0xf, 0xf, false)); }
; __device__ __forceinline__ float dpp_ror2(float x) { return __builtin_bit_cast(float, __builtin_amdgcn_update_dpp(0, __builtin_bit_cast(int, x), 0x122, 0xf, 0xf, false)); }
;     __device__ __forceinline__ void operator()(const f32x4 (&acc)[2][2][4][2], const Unit& u, int wr, int wc, int fr, int fq) const {
;     ...
;                 for (int m = 0; m < 4; ++m) { const int r = rbase + ai * HALF + 16 * m; const bool hi = r >= rb; const int t = hi ? r - rb : r - b0 * TP, b = hi ? b0 + 1 : b0;
;                     float o[8], uu[8], gg[8];
; #pragma unroll
;                     for (int k = 0; k < 8; ++k) { const float x = acc[ai][0][m][k >> 2][k & 3], g = acc[ai][1][m][k >> 2][k & 3]; uu[k] = x; gg[k] = g;
;                         float u1 = dpp_ror1(x), u2 = dpp_ror2(x);
;                         if (m > 0) { const float xp = acc[ai][0][m > 0 ? m - 1 : 0][k >> 2][k & 3]; const float p1 = dpp_ror1(xp), p2 = dpp_ror2(xp); u1 = fr >= 1 ? u1 : p1; u2 = fr >= 2 ? u2 : p2; }
;                         if (t == 0) u1 = 0.f; if (t <= 1) u2 = 0.f;
;                         const float uc = w0[k] * u2 + w1[k] * u1 + w2[k] * x + bb[k]; o[k] = uc * sigmoidf_(uc) * g; }
;                     if (m > 0 || fr >= 2) *(u32x4*)(ACT + (size_t)r * DFF + ch0) = pack8(o);
;                     if (m == 0 && fr < 2) { const int blk = r >> 6; *(u32x4*)(EF + ((size_t)(blk * 2 + fr) * 2) * DFF + ch0) = pack8(uu); *(u32x4*)(EF + ((size_t)(blk * 2 + fr) * 2 + 1) * DFF + ch0) = pack8(gg); }
;                     if (m == 3 && fr >= 14) { const int blk = r >> 6; *(u32x4*)(EL + (size_t)(blk * 2 + (fr - 14)) * DFF + ch0) = pack8(uu); }
;                     if (t >= TP - 2) store8f(outp + ((size_t)(b * 2) + (t - (TP - 2))) * DFF + ch0, uu); }
.Lp8e_end_11:
	s_cmp_eq_u32 s90, 64
	s_cbranch_scc1 .Lp8e_smp_12
	s_add_i32 s55, s91, 160
	s_cmp_ge_i32 s55, s85
	s_cselect_b32 s83, s54, s35
	s_mul_i32 s32, s83, 0x810
	s_sub_i32 s32, s55, s32
	s_mul_i32 s10, s55, 0x1600
	s_add_u32 s92, s60, s10
	s_addc_u32 s93, s61, 0
	v_fma_f32 v184, v66, v26, v74
	v_fma_f32 v185, v67, v27, v75
	v_fma_f32 v186, v68, v28, v76
	v_fma_f32 v187, v69, v29, v77
	v_fma_f32 v188, v70, v22, v78
	v_fma_f32 v189, v71, v23, v79
	v_fma_f32 v190, v72, v24, v80
	v_fma_f32 v191, v73, v25, v81
	v_fmac_f32_dpp v184, v26, v58 row_shr:1 row_mask:0xf bank_mask:0xf
	v_fmac_f32_dpp v185, v27, v59 row_shr:1 row_mask:0xf bank_mask:0xf
	v_fmac_f32_dpp v186, v28, v60 row_shr:1 row_mask:0xf bank_mask:0xf
	v_fmac_f32_dpp v187, v29, v61 row_shr:1 row_mask:0xf bank_mask:0xf
	v_fmac_f32_dpp v188, v22, v62 row_shr:1 row_mask:0xf bank_mask:0xf
	v_fmac_f32_dpp v189, v23, v63 row_shr:1 row_mask:0xf bank_mask:0xf
	v_fmac_f32_dpp v190, v24, v64 row_shr:1 row_mask:0xf bank_mask:0xf
	v_fmac_f32_dpp v191, v25, v65 row_shr:1 row_mask:0xf bank_mask:0xf
	v_fmac_f32_dpp v184, v26, v50 row_shr:2 row_mask:0xf bank_mask:0xf
	v_fmac_f32_dpp v185, v27, v51 row_shr:2 row_mask:0xf bank_mask:0xf
	v_fmac_f32_dpp v186, v28, v52 row_shr:2 row_mask:0xf bank_mask:0xf
	v_fmac_f32_dpp v187, v29, v53 row_shr:2 row_mask:0xf bank_mask:0xf
	v_fmac_f32_dpp v188, v22, v54 row_shr:2 row_mask:0xf bank_mask:0xf
	v_fmac_f32_dpp v189, v23, v55 row_shr:2 row_mask:0xf bank_mask:0xf
	v_fmac_f32_dpp v190, v24, v56 row_shr:2 row_mask:0xf bank_mask:0xf
	v_fmac_f32_dpp v191, v25, v57 row_shr:2 row_mask:0xf bank_mask:0xf
	s_cmp_eq_u32 s32, 0
	s_cbranch_scc1 .Lp8e_nohalo_12
	v_fmac_f32_dpp v184, v42, v58 row_shl:15 row_mask:0xf bank_mask:0xf
	v_fmac_f32_dpp v185, v43, v59 row_shl:15 row_mask:0xf bank_mask:0xf
	v_fmac_f32_dpp v186, v44, v60 row_shl:15 row_mask:0xf bank_mask:0xf
	v_fmac_f32_dpp v187, v45, v61 row_shl:15 row_mask:0xf bank_mask:0xf
	v_fmac_f32_dpp v188, v38, v62 row_shl:15 row_mask:0xf bank_mask:0xf
	v_fmac_f32_dpp v189, v39, v63 row_shl:15 row_mask:0xf bank_mask:0xf
	v_fmac_f32_dpp v190, v40, v64 row_shl:15 row_mask:0xf bank_mask:0xf
	v_fmac_f32_dpp v191, v41, v65 row_shl:15 row_mask:0xf bank_mask:0xf
	v_fmac_f32_dpp v184, v42, v50 row_shl:14 row_mask:0xf bank_mask:0xf
	v_fmac_f32_dpp v185, v43, v51 row_shl:14 row_mask:0xf bank_mask:0xf
	v_fmac_f32_dpp v186, v44, v52 row_shl:14 row_mask:0xf bank_mask:0xf
	v_fmac_f32_dpp v187, v45, v53 row_shl:14 row_mask:0xf bank_mask:0xf
	v_fmac_f32_dpp v188, v38, v54 row_shl:14 row_mask:0xf bank_mask:0xf
	v_fmac_f32_dpp v189, v39, v55 row_shl:14 row_mask:0xf bank_mask:0xf
	v_fmac_f32_dpp v190, v40, v56 row_shl:14 row_mask:0xf bank_mask:0xf
	v_fmac_f32_dpp v191, v41, v57 row_shl:14 row_mask:0xf bank_mask:0xf
.Lp8e_nohalo_12:
	v_mul_f32_e32 v192, 0xbfb8aa3b, v184
	v_mul_f32_e32 v193, 0xbfb8aa3b, v185
	v_mul_f32_e32 v194, 0xbfb8aa3b, v186
	v_mul_f32_e32 v195, 0xbfb8aa3b, v187
	v_mul_f32_e32 v196, 0xbfb8aa3b, v188
	v_mul_f32_e32 v197, 0xbfb8aa3b, v189
	v_mul_f32_e32 v198, 0xbfb8aa3b, v190
	v_mul_f32_e32 v199, 0xbfb8aa3b, v191
	v_exp_f32_e32 v192, v192
	v_exp_f32_e32 v193, v193
	v_exp_f32_e32 v194, v194
	v_exp_f32_e32 v195, v195
	v_exp_f32_e32 v196, v196
	v_exp_f32_e32 v197, v197
	v_exp_f32_e32 v198, v198
	v_exp_f32_e32 v199, v199
	v_add_f32_e32 v192, 1.0, v192
	v_add_f32_e32 v193, 1.0, v193
	v_add_f32_e32 v194, 1.0, v194
	v_add_f32_e32 v195, 1.0, v195
	v_add_f32_e32 v196, 1.0, v196
	v_add_f32_e32 v197, 1.0, v197
	v_add_f32_e32 v198, 1.0, v198
	v_add_f32_e32 v199, 1.0, v199
	v_rcp_f32_e32 v192, v192
	v_rcp_f32_e32 v193, v193
	v_rcp_f32_e32 v194, v194
	v_rcp_f32_e32 v195, v195
	v_rcp_f32_e32 v196, v196
	v_rcp_f32_e32 v197, v197
	v_rcp_f32_e32 v198, v198
	v_rcp_f32_e32 v199, v199
	v_mul_f32_e32 v184, v184, v192
	v_mul_f32_e32 v185, v185, v193
	v_mul_f32_e32 v186, v186, v194
	v_mul_f32_e32 v187, v187, v195
	v_mul_f32_e32 v188, v188, v196
	v_mul_f32_e32 v189, v189, v197
	v_mul_f32_e32 v190, v190, v198
	v_mul_f32_e32 v191, v191, v199
	v_mul_f32_e32 v184, v30, v184
	v_mul_f32_e32 v185, v31, v185
	v_mul_f32_e32 v186, v32, v186
	v_mul_f32_e32 v187, v33, v187
	v_mul_f32_e32 v188, v18, v188
	v_mul_f32_e32 v189, v19, v189
	v_mul_f32_e32 v190, v20, v190
	v_mul_f32_e32 v191, v21, v191
	v_cvt_pk_bf16_f32 v200, v184, v185
	v_cvt_pk_bf16_f32 v201, v186, v187
	v_cvt_pk_bf16_f32 v202, v188, v189
	v_cvt_pk_bf16_f32 v203, v190, v191
	global_store_dwordx4 v183, v[200:203], s[92:93]
	s_cmpk_lg_i32 s32, 0x800
	s_cbranch_scc1 .Lp8e_noout_12
	s_mul_i32 s10, s83, 0x5800
	s_add_u32 s94, s72, s10
	s_addc_u32 s95, s73, 0
	s_mov_b64 exec, s[8:9]
	global_store_dwordx4 v239, v[26:29], s[94:95]
	global_store_dwordx4 v239, v[22:25], s[94:95] offset:16
	s_mov_b64 exec, -1
.Lp8e_noout_12:
	s_branch .Lp8e_end_12
; __device__ __forceinline__ u32x4 pack8(const float (&f)[8]) { u32x4 o; o.x = cvt_pk_bf16(f[0], f[1]); o.y = cvt_pk_bf16(f[2], f[3]); o.z = cvt_pk_bf16(f[4], f[5]); o.w = cvt_pk_bf16(f[6], f[7]); return o; }
; __device__ __forceinline__ float sigmoidf_(float x) { return __builtin_amdgcn_rcpf(1.0f + __expf(-x)); }
; __device__ __forceinline__ float dpp_ror1(float x) { return __builtin_bit_cast(float, __builtin_amdgcn_update_dpp(0, __builtin_bit_cast(int, x), 0x121, 0xf, 0xf, false)); }
; __device__ __forceinline__ float dpp_ror2(float x) { return __builtin_bit_cast(float, __builtin_amdgcn_update_dpp(0, __builtin_bit_cast(int, x), 0x122, 0xf, 0xf, false)); }
;     __device__ __forceinline__ void operator()(const f32x4 (&acc)[2][2][4][2], const Unit& u, int wr, int wc, int fr, int fq) const {
;     ...
;                 for (int m = 0; m < 4; ++m) { const int r = rbase + HALF + 16 * m, sb = r - MP;
;                     float u2[8], u1[8], o[8], uu[8]; load8f(st + (size_t)(sb * 2) * DFF + ch0, u2); load8f(st + (size_t)(sb * 2 + 1) * DFF + ch0, u1);
; #pragma unroll
;                     for (int k = 0; k < 8; ++k) { const float x = acc[1][0][m][k >> 2][k & 3], g = acc[1][1][m][k >> 2][k & 3]; uu[k] = x;
;                         const float uc = w0[k] * u2[k] + w1[k] * u1[k] + w2[k] * x + bb[k]; o[k] = uc * sigmoidf_(uc) * g; }
;                     *(u32x4*)(ACT + (size_t)r * DFF + ch0) = pack8(o);
;                     store8f(outs + (size_t)(sb * 2) * DFF + ch0, u1); store8f(outs + (size_t)(sb * 2 + 1) * DFF + ch0, uu); }
;             } else {
; #pragma unroll
;                 for (int m = 0; m < 4; ++m) { const int r = rbase + ai * HALF + 16 * m; const bool hi = r >= rb; const int t = hi ? r - rb : r - b0 * TP, b = hi ? b0 + 1 : b0;
;                     float o[8], uu[8], gg[8];
; #pragma unroll
;                     for (int k = 0; k < 8; ++k) { const float x = acc[ai][0][m][k >> 2][k & 3], g = acc[ai][1][m][k >> 2][k & 3]; uu[k] = x; gg[k] = g;
;                         float u1 = dpp_ror1(x), u2 = dpp_ror2(x);
;                         if (m > 0) { const float xp = acc[ai][0][m > 0 ? m - 1 : 0][k >> 2][k & 3]; const float p1 = dpp_ror1(xp), p2 = dpp_ror2(xp); u1 = fr >= 1 ? u1 : p1; u2 = fr >= 2 ? u2 : p2; }
.Lp8e_smp_12:
	s_add_i32 s55, s91, 160
	s_mul_i32 s10, s55, 0x1600
	s_add_u32 s92, s60, s10
	s_addc_u32 s93, s61, 0
	s_add_i32 s10, s18, 32
	s_mul_i32 s10, s10, 0x5800
	s_add_u32 s94, s70, s10
	s_addc_u32 s95, s71, 0
	s_add_u32 s98, s94, 0x2c00
	s_addc_u32 s99, s95, 0
	global_load_dwordx4 v[228:231], v248, s[94:95]
	global_load_dwordx4 v[232:235], v248, s[94:95] offset:16
	global_load_dwordx4 v[240:243], v248, s[98:99]
	global_load_dwordx4 v[244:247], v248, s[98:99] offset:16
	s_add_u32 s94, s74, s10
	s_addc_u32 s95, s75, 0
	s_add_u32 s98, s94, 0x2c00
	s_addc_u32 s99, s95, 0
	v_fma_f32 v184, v66, v26, v74
	v_fma_f32 v185, v67, v27, v75
	v_fma_f32 v186, v68, v28, v76
	v_fma_f32 v187, v69, v29, v77
	v_fma_f32 v188, v70, v22, v78
	v_fma_f32 v189, v71, v23, v79
	v_fma_f32 v190, v72, v24, v80
	v_fma_f32 v191, v73, v25, v81
	s_waitcnt vmcnt(0)
	v_fmac_f32_e32 v184, v58, v240
	v_fmac_f32_e32 v185, v59, v241
	v_fmac_f32_e32 v186, v60, v242
	v_fmac_f32_e32 v187, v61, v243
	v_fmac_f32_e32 v188, v62, v244
	v_fmac_f32_e32 v189, v63, v245
	v_fmac_f32_e32 v190, v64, v246
	v_fmac_f32_e32 v191, v65, v247
	v_fmac_f32_e32 v184, v50, v228
	v_fmac_f32_e32 v185, v51, v229
	v_fmac_f32_e32 v186, v52, v230
	v_fmac_f32_e32 v187, v53, v231
	v_fmac_f32_e32 v188, v54, v232
	v_fmac_f32_e32 v189, v55, v233
	v_fmac_f32_e32 v190, v56, v234
	v_fmac_f32_e32 v191, v57, v235
	v_mul_f32_e32 v192, 0xbfb8aa3b, v184
	v_mul_f32_e32 v193, 0xbfb8aa3b, v185
	v_mul_f32_e32 v194, 0xbfb8aa3b, v186
	v_mul_f32_e32 v195, 0xbfb8aa3b, v187
	v_mul_f32_e32 v196, 0xbfb8aa3b, v188
	v_mul_f32_e32 v197, 0xbfb8aa3b, v189
	v_mul_f32_e32 v198, 0xbfb8aa3b, v190
	v_mul_f32_e32 v199, 0xbfb8aa3b, v191
	v_exp_f32_e32 v192, v192
	v_exp_f32_e32 v193, v193
	v_exp_f32_e32 v194, v194
	v_exp_f32_e32 v195, v195
	v_exp_f32_e32 v196, v196
	v_exp_f32_e32 v197, v197
	v_exp_f32_e32 v198, v198
	v_exp_f32_e32 v199, v199
	v_add_f32_e32 v192, 1.0, v192
	v_add_f32_e32 v193, 1.0, v193
	v_add_f32_e32 v194, 1.0, v194
	v_add_f32_e32 v195, 1.0, v195
	v_add_f32_e32 v196, 1.0, v196
	v_add_f32_e32 v197, 1.0, v197
	v_add_f32_e32 v198, 1.0, v198
	v_add_f32_e32 v199, 1.0, v199
	v_rcp_f32_e32 v192, v192
	v_rcp_f32_e32 v193, v193
	v_rcp_f32_e32 v194, v194
	v_rcp_f32_e32 v195, v195
	v_rcp_f32_e32 v196, v196
	v_rcp_f32_e32 v197, v197
	v_rcp_f32_e32 v198, v198
	v_rcp_f32_e32 v199, v199
	v_mul_f32_e32 v184, v184, v192
	v_mul_f32_e32 v185, v185, v193
	v_mul_f32_e32 v186, v186, v194
	v_mul_f32_e32 v187, v187, v195
	v_mul_f32_e32 v188, v188, v196
	v_mul_f32_e32 v189, v189, v197
	v_mul_f32_e32 v190, v190, v198
	v_mul_f32_e32 v191, v191, v199
	v_mul_f32_e32 v184, v30, v184
	v_mul_f32_e32 v185, v31, v185
	v_mul_f32_e32 v186, v32, v186
	v_mul_f32_e32 v187, v33, v187
	v_mul_f32_e32 v188, v18, v188
	v_mul_f32_e32 v189, v19, v189
	v_mul_f32_e32 v190, v20, v190
	v_mul_f32_e32 v191, v21, v191
	v_cvt_pk_bf16_f32 v200, v184, v185
	v_cvt_pk_bf16_f32 v201, v186, v187
	v_cvt_pk_bf16_f32 v202, v188, v189
	v_cvt_pk_bf16_f32 v203, v190, v191
	global_store_dwordx4 v183, v[200:203], s[92:93]
	global_store_dwordx4 v248, v[240:243], s[94:95]
	global_store_dwordx4 v248, v[244:247], s[94:95] offset:16
	global_store_dwordx4 v248, v[26:29], s[98:99]
	global_store_dwordx4 v248, v[22:25], s[98:99] offset:16
	s_nop 1
.Lp8e_end_12:
	s_cmp_eq_u32 s90, 64
	s_cbranch_scc1 .Lp8e_smp_13
	s_add_i32 s55, s91, 176
	s_cmp_ge_i32 s55, s85
	s_cselect_b32 s83, s54, s35
	s_mul_i32 s32, s83, 0x810
	s_sub_i32 s32, s55, s32
	s_mul_i32 s10, s55, 0x1600
	s_add_u32 s92, s60, s10
	s_addc_u32 s93, s61, 0
	v_fma_f32 v184, v66, v10, v74
	v_fma_f32 v185, v67, v11, v75
	v_fma_f32 v186, v68, v12, v76
	v_fma_f32 v187, v69, v13, v77
	v_fma_f32 v188, v70, v6, v78
	v_fma_f32 v189, v71, v7, v79
	v_fma_f32 v190, v72, v8, v80
	v_fma_f32 v191, v73, v9, v81
	v_fmac_f32_dpp v184, v10, v58 row_shr:1 row_mask:0xf bank_mask:0xf
	v_fmac_f32_dpp v185, v11, v59 row_shr:1 row_mask:0xf bank_mask:0xf
	v_fmac_f32_dpp v186, v12, v60 row_shr:1 row_mask:0xf bank_mask:0xf
	v_fmac_f32_dpp v187, v13, v61 row_shr:1 row_mask:0xf bank_mask:0xf
	v_fmac_f32_dpp v188, v6, v62 row_shr:1 row_mask:0xf bank_mask:0xf
	v_fmac_f32_dpp v189, v7, v63 row_shr:1 row_mask:0xf bank_mask:0xf
	v_fmac_f32_dpp v190, v8, v64 row_shr:1 row_mask:0xf bank_mask:0xf
	v_fmac_f32_dpp v191, v9, v65 row_shr:1 row_mask:0xf bank_mask:0xf
	v_fmac_f32_dpp v184, v10, v50 row_shr:2 row_mask:0xf bank_mask:0xf
	v_fmac_f32_dpp v185, v11, v51 row_shr:2 row_mask:0xf bank_mask:0xf
	v_fmac_f32_dpp v186, v12, v52 row_shr:2 row_mask:0xf bank_mask:0xf
	v_fmac_f32_dpp v187, v13, v53 row_shr:2 row_mask:0xf bank_mask:0xf
	v_fmac_f32_dpp v188, v6, v54 row_shr:2 row_mask:0xf bank_mask:0xf
	v_fmac_f32_dpp v189, v7, v55 row_shr:2 row_mask:0xf bank_mask:0xf
	v_fmac_f32_dpp v190, v8, v56 row_shr:2 row_mask:0xf bank_mask:0xf
	v_fmac_f32_dpp v191, v9, v57 row_shr:2 row_mask:0xf bank_mask:0xf
	s_cmp_eq_u32 s32, 0
	s_cbranch_scc1 .Lp8e_nohalo_13
	v_fmac_f32_dpp v184, v26, v58 row_shl:15 row_mask:0xf bank_mask:0xf
	v_fmac_f32_dpp v185, v27, v59 row_shl:15 row_mask:0xf bank_mask:0xf
	v_fmac_f32_dpp v186, v28, v60 row_shl:15 row_mask:0xf bank_mask:0xf
	v_fmac_f32_dpp v187, v29, v61 row_shl:15 row_mask:0xf bank_mask:0xf
	v_fmac_f32_dpp v188, v22, v62 row_shl:15 row_mask:0xf bank_mask:0xf
	v_fmac_f32_dpp v189, v23, v63 row_shl:15 row_mask:0xf bank_mask:0xf
	v_fmac_f32_dpp v190, v24, v64 row_shl:15 row_mask:0xf bank_mask:0xf
	v_fmac_f32_dpp v191, v25, v65 row_shl:15 row_mask:0xf bank_mask:0xf
	v_fmac_f32_dpp v184, v26, v50 row_shl:14 row_mask:0xf bank_mask:0xf
	v_fmac_f32_dpp v185, v27, v51 row_shl:14 row_mask:0xf bank_mask:0xf
	v_fmac_f32_dpp v186, v28, v52 row_shl:14 row_mask:0xf bank_mask:0xf
	v_fmac_f32_dpp v187, v29, v53 row_shl:14 row_mask:0xf bank_mask:0xf
	v_fmac_f32_dpp v188, v22, v54 row_shl:14 row_mask:0xf bank_mask:0xf
	v_fmac_f32_dpp v189, v23, v55 row_shl:14 row_mask:0xf bank_mask:0xf
	v_fmac_f32_dpp v190, v24, v56 row_shl:14 row_mask:0xf bank_mask:0xf
	v_fmac_f32_dpp v191, v25, v57 row_shl:14 row_mask:0xf bank_mask:0xf
; __device__ __forceinline__ u32x4 pack8(const float (&f)[8]) { u32x4 o; o.x = cvt_pk_bf16(f[0], f[1]); o.y = cvt_pk_bf16(f[2], f[3]); o.z = cvt_pk_bf16(f[4], f[5]); o.w = cvt_pk_bf16(f[6], f[7]); return o; }
; __device__ __forceinline__ float sigmoidf_(float x) { return __builtin_amdgcn_rcpf(1.0f + __expf(-x)); }
;     __device__ __forceinline__ void operator()(const f32x4 (&acc)[2][2][4][2], const Unit& u, int wr, int wc, int fr, int fq) const {
;     ...
;                 for (int m = 0; m < 4; ++m) { const int r = rbase + HALF + 16 * m, sb = r - MP;
;                     float u2[8], u1[8], o[8], uu[8]; load8f(st + (size_t)(sb * 2) * DFF + ch0, u2); load8f(st + (size_t)(sb * 2 + 1) * DFF + ch0, u1);
; #pragma unroll
;                     for (int k = 0; k < 8; ++k) { const float x = acc[1][0][m][k >> 2][k & 3], g = acc[1][1][m][k >> 2][k & 3]; uu[k] = x;
;                         const float uc = w0[k] * u2[k] + w1[k] * u1[k] + w2[k] * x + bb[k]; o[k] = uc * sigmoidf_(uc) * g; }
;                     *(u32x4*)(ACT + (size_t)r * DFF + ch0) = pack8(o);
;                     store8f(outs + (size_t)(sb * 2) * DFF + ch0, u1); store8f(outs + (size_t)(sb * 2 + 1) * DFF + ch0, uu); }
;     ...
;                         const float uc = w0[k] * u2 + w1[k] * u1 + w2[k] * x + bb[k]; o[k] = uc * sigmoidf_(uc) * g; }
;                     if (m > 0 || fr >= 2) *(u32x4*)(ACT + (size_t)r * DFF + ch0) = pack8(o);
;                     if (m == 0 && fr < 2) { const int blk = r >> 6; *(u32x4*)(EF + ((size_t)(blk * 2 + fr) * 2) * DFF + ch0) = pack8(uu); *(u32x4*)(EF + ((size_t)(blk * 2 + fr) * 2 + 1) * DFF + ch0) = pack8(gg); }
;                     if (m == 3 && fr >= 14) { const int blk = r >> 6; *(u32x4*)(EL + (size_t)(blk * 2 + (fr - 14)) * DFF + ch0) = pack8(uu); }
;                     if (t >= TP - 2) store8f(outp + ((size_t)(b * 2) + (t - (TP - 2))) * DFF + ch0, uu); }
.Lp8e_nohalo_13:
	v_mul_f32_e32 v192, 0xbfb8aa3b, v184
	v_mul_f32_e32 v193, 0xbfb8aa3b, v185
	v_mul_f32_e32 v194, 0xbfb8aa3b, v186
	v_mul_f32_e32 v195, 0xbfb8aa3b, v187
	v_mul_f32_e32 v196, 0xbfb8aa3b, v188
	v_mul_f32_e32 v197, 0xbfb8aa3b, v189
	v_mul_f32_e32 v198, 0xbfb8aa3b, v190
	v_mul_f32_e32 v199, 0xbfb8aa3b, v191
	v_exp_f32_e32 v192, v192
	v_exp_f32_e32 v193, v193
	v_exp_f32_e32 v194, v194
	v_exp_f32_e32 v195, v195
	v_exp_f32_e32 v196, v196
	v_exp_f32_e32 v197, v197
	v_exp_f32_e32 v198, v198
	v_exp_f32_e32 v199, v199
	v_add_f32_e32 v192, 1.0, v192
	v_add_f32_e32 v193, 1.0, v193
	v_add_f32_e32 v194, 1.0, v194
	v_add_f32_e32 v195, 1.0, v195
	v_add_f32_e32 v196, 1.0, v196
	v_add_f32_e32 v197, 1.0, v197
	v_add_f32_e32 v198, 1.0, v198
	v_add_f32_e32 v199, 1.0, v199
	v_rcp_f32_e32 v192, v192
	v_rcp_f32_e32 v193, v193
	v_rcp_f32_e32 v194, v194
	v_rcp_f32_e32 v195, v195
	v_rcp_f32_e32 v196, v196
	v_rcp_f32_e32 v197, v197
	v_rcp_f32_e32 v198, v198
	v_rcp_f32_e32 v199, v199
	v_mul_f32_e32 v184, v184, v192
	v_mul_f32_e32 v185, v185, v193
	v_mul_f32_e32 v186, v186, v194
	v_mul_f32_e32 v187, v187, v195
	v_mul_f32_e32 v188, v188, v196
	v_mul_f32_e32 v189, v189, v197
	v_mul_f32_e32 v190, v190, v198
	v_mul_f32_e32 v191, v191, v199
	v_mul_f32_e32 v184, v14, v184
	v_mul_f32_e32 v185, v15, v185
	v_mul_f32_e32 v186, v16, v186
	v_mul_f32_e32 v187, v17, v187
	v_mul_f32_e32 v188, v2, v188
	v_mul_f32_e32 v189, v3, v189
	v_mul_f32_e32 v190, v4, v190
	v_mul_f32_e32 v191, v5, v191
	v_cvt_pk_bf16_f32 v224, v184, v185
	v_cvt_pk_bf16_f32 v225, v186, v187
	v_cvt_pk_bf16_f32 v226, v188, v189
	v_cvt_pk_bf16_f32 v227, v190, v191
	global_store_dwordx4 v183, v[224:227], s[92:93]
	s_lshr_b32 s10, s55, 6
	s_mul_i32 s10, s10, 0x2c00
	s_add_u32 s94, s64, s10
	s_addc_u32 s95, s65, 0
	s_mov_b64 exec, s[8:9]
	v_cvt_pk_bf16_f32 v228, v10, v11
	v_cvt_pk_bf16_f32 v229, v12, v13
	v_cvt_pk_bf16_f32 v230, v6, v7
	v_cvt_pk_bf16_f32 v231, v8, v9
	global_store_dwordx4 v238, v[228:231], s[94:95]
	s_mov_b64 exec, -1
	s_cmpk_lg_i32 s32, 0x800
	s_cbranch_scc1 .Lp8e_noout_13
	s_mul_i32 s10, s83, 0x5800
	s_add_u32 s94, s72, s10
	s_addc_u32 s95, s73, 0
	s_mov_b64 exec, s[8:9]
	global_store_dwordx4 v239, v[10:13], s[94:95]
	global_store_dwordx4 v239, v[6:9], s[94:95] offset:16
	s_mov_b64 exec, -1
.Lp8e_noout_13:
	s_branch .Lp8e_end_13
.Lp8e_smp_13:
	s_add_i32 s55, s91, 176
	s_mul_i32 s10, s55, 0x1600
	s_add_u32 s92, s60, s10
	s_addc_u32 s93, s61, 0
	s_add_i32 s10, s18, 48
	s_mul_i32 s10, s10, 0x5800
	s_add_u32 s94, s70, s10
	s_addc_u32 s95, s71, 0
	s_add_u32 s98, s94, 0x2c00
	s_addc_u32 s99, s95, 0
	global_load_dwordx4 v[228:231], v248, s[94:95]
	global_load_dwordx4 v[232:235], v248, s[94:95] offset:16
	global_load_dwordx4 v[240:243], v248, s[98:99]
	global_load_dwordx4 v[244:247], v248, s[98:99] offset:16
	s_add_u32 s94, s74, s10
	s_addc_u32 s95, s75, 0
	s_add_u32 s98, s94, 0x2c00
	s_addc_u32 s99, s95, 0
	v_fma_f32 v184, v66, v10, v74
	v_fma_f32 v185, v67, v11, v75
	v_fma_f32 v186, v68, v12, v76
	v_fma_f32 v187, v69, v13, v77
	v_fma_f32 v188, v70, v6, v78
	v_fma_f32 v189, v71, v7, v79
	v_fma_f32 v190, v72, v8, v80
	v_fma_f32 v191, v73, v9, v81
	s_waitcnt vmcnt(0)
	v_fmac_f32_e32 v184, v58, v240
	v_fmac_f32_e32 v185, v59, v241
	v_fmac_f32_e32 v186, v60, v242
	v_fmac_f32_e32 v187, v61, v243
	v_fmac_f32_e32 v188, v62, v244
	v_fmac_f32_e32 v189, v63, v245
	v_fmac_f32_e32 v190, v64, v246
	v_fmac_f32_e32 v191, v65, v247
	v_fmac_f32_e32 v184, v50, v228
	v_fmac_f32_e32 v185, v51, v229
	v_fmac_f32_e32 v186, v52, v230
	v_fmac_f32_e32 v187, v53, v231
	v_fmac_f32_e32 v188, v54, v232
	v_fmac_f32_e32 v189, v55, v233
	v_fmac_f32_e32 v190, v56, v234
	v_fmac_f32_e32 v191, v57, v235
	v_mul_f32_e32 v192, 0xbfb8aa3b, v184
	v_mul_f32_e32 v193, 0xbfb8aa3b, v185
	v_mul_f32_e32 v194, 0xbfb8aa3b, v186
	v_mul_f32_e32 v195, 0xbfb8aa3b, v187
	v_mul_f32_e32 v196, 0xbfb8aa3b, v188
	v_mul_f32_e32 v197, 0xbfb8aa3b, v189
	v_mul_f32_e32 v198, 0xbfb8aa3b, v190
	v_mul_f32_e32 v199, 0xbfb8aa3b, v191
	v_exp_f32_e32 v192, v192
	v_exp_f32_e32 v193, v193
	v_exp_f32_e32 v194, v194
	v_exp_f32_e32 v195, v195
	v_exp_f32_e32 v196, v196
	v_exp_f32_e32 v197, v197
	v_exp_f32_e32 v198, v198
	v_exp_f32_e32 v199, v199
	v_add_f32_e32 v192, 1.0, v192
	v_add_f32_e32 v193, 1.0, v193
	v_add_f32_e32 v194, 1.0, v194
	v_add_f32_e32 v195, 1.0, v195
	v_add_f32_e32 v196, 1.0, v196
	v_add_f32_e32 v197, 1.0, v197
	v_add_f32_e32 v198, 1.0, v198
	v_add_f32_e32 v199, 1.0, v199
	v_rcp_f32_e32 v192, v192
	v_rcp_f32_e32 v193, v193
	v_rcp_f32_e32 v194, v194
	v_rcp_f32_e32 v195, v195
	v_rcp_f32_e32 v196, v196
	v_rcp_f32_e32 v197, v197
	v_rcp_f32_e32 v198, v198
	v_rcp_f32_e32 v199, v199
	v_mul_f32_e32 v184, v184, v192
	v_mul_f32_e32 v185, v185, v193
	v_mul_f32_e32 v186, v186, v194
	v_mul_f32_e32 v187, v187, v195
	v_mul_f32_e32 v188, v188, v196
	v_mul_f32_e32 v189, v189, v197
	v_mul_f32_e32 v190, v190, v198
	v_mul_f32_e32 v191, v191, v199
	v_mul_f32_e32 v184, v14, v184
	v_mul_f32_e32 v185, v15, v185
	v_mul_f32_e32 v186, v16, v186
	v_mul_f32_e32 v187, v17, v187
	v_mul_f32_e32 v188, v2, v188
	v_mul_f32_e32 v189, v3, v189
	v_mul_f32_e32 v190, v4, v190
	v_mul_f32_e32 v191, v5, v191
	v_cvt_pk_bf16_f32 v224, v184, v185
	v_cvt_pk_bf16_f32 v225, v186, v187
	v_cvt_pk_bf16_f32 v226, v188, v189
	v_cvt_pk_bf16_f32 v227, v190, v191
	global_store_dwordx4 v183, v[224:227], s[92:93]
	global_store_dwordx4 v248, v[240:243], s[94:95]
	global_store_dwordx4 v248, v[244:247], s[94:95] offset:16
	global_store_dwordx4 v248, v[10:13], s[98:99]
	global_store_dwordx4 v248, v[6:9], s[98:99] offset:16
	s_nop 1
.Lp8e_end_13:
	s_mov_b64 s[12:13], 0
	s_branch .LBB0_913
.LBB0_913:
	s_and_saveexec_b64 s[10:11], s[12:13]
	s_cbranch_execz .LBB0_915
	v_lshl_add_u64 v[2:3], v[174:175], 2, v[98:99]
	global_store_dwordx4 v[2:3], v[10:13], off
	global_store_dwordx4 v[2:3], v[6:9], off offset:16
	s_or_b64 exec, exec, s[10:11]
	s_cmp_eq_u32 s21, s23
	s_mov_b64 s[10:11], -1
	s_cbranch_scc1 .LBB0_872
	s_branch .LBB0_916

; #define PG8_WAIT_V(n) asm volatile("s_waitcnt vmcnt(" #n ")" ::: "memory")
; #define PG8_BAR __builtin_amdgcn_s_barrier()
; template <class Epi, bool ALIGN_EPI = true, bool SP2 = true>
; __device__ __forceinline__ void gemm_phase(LAS unsigned char* lds, const Gemm g, const Order& S, const Epi& E) {
;     ...
;         if (!has_next) break;
;         if (!chained) {
; #pragma unroll
;         for (int a = 0; a < 2; ++a)
; #pragma unroll
;             for (int b = 0; b < 2; ++b)
; #pragma unroll
;                 for (int m = 0; m < 4; ++m)
; #pragma unroll
;                     for (int n = 0; n < 2; ++n) acc[a][b][m][n] = (f32x4){0.f, 0.f, 0.f, 0.f};
;         }
;         cur = nxt; cA = nA; cB = nB; ++ui;
;         if constexpr (ALIGN_EPI) { if (wr == 1) PG8_BAR; }
;     }
;     PG8_WAIT_V(0);
;     if constexpr (!ALIGN_EPI) { if (wr == 0) PG8_BAR; }
;     PG8_BAR;
.LBB0_916:
	s_andn2_b64 vcc, exec, s[58:59]
	s_cbranch_vccnz .LBB0_871
	s_barrier
	s_branch .LBB0_871
.LBB0_920:
	s_waitcnt vmcnt(0)
	s_movk_i32 s88, 0x7000
	s_mov_b32 s89, 0xe000
	s_mov_b32 s91, 0x15000
	s_mov_b32 s92, 0x1c000
	s_mov_b32 s93, 0x23000
	s_mov_b32 s45, 0x2a000
	s_mov_b32 s46, 0x31000
	s_mov_b32 s81, 0x38000
	s_mov_b32 s82, 0x3f000
	s_mov_b32 s49, 0x46000
	v_readlane_b32 s2, v255, 0
	s_mov_b32 s42, 0x7e000
	s_mov_b32 s40, 0x85000
	v_readlane_b32 s52, v255, 3
	v_readlane_b32 s50, v255, 4
	s_mov_b32 s80, 0x40000
	s_mov_b32 s76, 0x48000
	s_mov_b32 s77, 0x50000
	s_mov_b64 s[78:79], 0x40000
	s_mov_b64 s[74:75], 0x48000
	s_mov_b32 s69, s0
	s_mul_hi_u32 s67, s56, 0x8400
	s_mul_i32 s66, s56, 0x8400
	s_mul_i32 s68, s56, 0x2c00
	s_barrier

; __device__ __forceinline__ u32x4 pack8(const float (&f)[8]) { u32x4 o; o.x = cvt_pk_bf16(f[0], f[1]); o.y = cvt_pk_bf16(f[2], f[3]); o.z = cvt_pk_bf16(f[4], f[5]); o.w = cvt_pk_bf16(f[6], f[7]); return o; }
;     __device__ __forceinline__ void operator()(const f32x4 (&acc)[2][2][4][2], const Unit& u, int wr, int wc, int fr, int fq) const {
;     ...
;         if (u.nkt == ntFull) {
; #pragma unroll
;             for (int ai = 0; ai < 2; ++ai)
; #pragma unroll
;                 for (int m = 0; m < 4; ++m) { bf16_t* rowp = X + (size_t)(row0 + ai * HALF + m * 16) * D + col0;
; #pragma unroll
;                     for (int bj = 0; bj < 2; ++bj) { u32x4* p = (u32x4*)(rowp + bj * HALF); float x[8]; unpack8(*p, x); const f32x4 a0 = acc[ai][bj][m][0], a1 = acc[ai][bj][m][1];
; #pragma unroll
;                         for (int e = 0; e < 4; ++e) { x[e] += a0[e]; x[4 + e] += a1[e]; }
;                         *p = pack8(x); }
;                     asm volatile("" ::: "memory"); }
.LBB0_1101:
	v_lshl_add_u32 v252, s68, 8, v136
	v_lshlrev_b32_e32 v162, 11, v252
	v_lshl_add_u32 v162, v158, 1, v162
	v_lshrrev_b32_e32 v163, 8, v158
	v_bfe_u32 v248, v158, 3, 4
	v_lshl_or_b32 v163, v163, 4, v248
	v_lshlrev_b32_e32 v163, 2, v163
	v_lshl_add_u32 v163, v252, 8, v163
	s_mov_b32 s70, s8
	s_mov_b32 s71, s9
	global_load_dwordx4 v[164:167], v162, s[70:71]
	global_load_dwordx4 v[168:171], v162, s[70:71] offset:256
	s_add_u32 s70, s70, 0x8000
	s_addc_u32 s71, s71, 0
	global_load_dwordx4 v[172:175], v162, s[70:71]
	global_load_dwordx4 v[176:179], v162, s[70:71] offset:256
	s_add_u32 s70, s70, 0x8000
	s_addc_u32 s71, s71, 0
	global_load_dwordx4 v[180:183], v162, s[70:71]
	global_load_dwordx4 v[184:187], v162, s[70:71] offset:256
	s_add_u32 s70, s70, 0x8000
	s_addc_u32 s71, s71, 0
	global_load_dwordx4 v[188:191], v162, s[70:71]
	global_load_dwordx4 v[192:195], v162, s[70:71] offset:256
	s_add_u32 s70, s70, 0x28000
	s_addc_u32 s71, s71, 0
	global_load_dwordx4 v[196:199], v162, s[70:71]
	global_load_dwordx4 v[200:203], v162, s[70:71] offset:256
	s_add_u32 s70, s70, 0x8000
	s_addc_u32 s71, s71, 0
	global_load_dwordx4 v[224:227], v162, s[70:71]
	global_load_dwordx4 v[228:231], v162, s[70:71] offset:256
	s_add_u32 s70, s70, 0x8000
	s_addc_u32 s71, s71, 0
	global_load_dwordx4 v[232:235], v162, s[70:71]
	global_load_dwordx4 v[236:239], v162, s[70:71] offset:256
	s_add_u32 s70, s70, 0x8000
	s_addc_u32 s71, s71, 0
	global_load_dwordx4 v[240:243], v162, s[70:71]
	global_load_dwordx4 v[244:247], v162, s[70:71] offset:256
	s_mov_b32 s70, s8
	s_mov_b32 s71, s9
	s_add_u32 s72, s8, 0x16680000
	s_addc_u32 s73, s9, 0
	s_waitcnt vmcnt(15)
	v_lshlrev_b32_e32 v248, 16, v164
	v_lshlrev_b32_e32 v249, 16, v165
	v_lshlrev_b32_e32 v250, 16, v166
	v_lshlrev_b32_e32 v251, 16, v167
	v_and_b32_e32 v164, 0xffff0000, v164
	v_and_b32_e32 v165, 0xffff0000, v165
	v_and_b32_e32 v166, 0xffff0000, v166
	v_and_b32_e32 v167, 0xffff0000, v167
	v_add_f32_e32 v126, v126, v248
	v_add_f32_e32 v127, v127, v164
	v_add_f32_e32 v128, v128, v249
	v_add_f32_e32 v129, v129, v165
	v_add_f32_e32 v122, v122, v250
	v_add_f32_e32 v123, v123, v166
	v_add_f32_e32 v124, v124, v251
	v_add_f32_e32 v125, v125, v167
	v_mul_f32_e32 v158, v126, v126
	v_fmac_f32_e32 v158, v127, v127
	v_fmac_f32_e32 v158, v128, v128
	v_fmac_f32_e32 v158, v129, v129
	v_fmac_f32_e32 v158, v122, v122
	v_fmac_f32_e32 v158, v123, v123
	v_fmac_f32_e32 v158, v124, v124
	v_fmac_f32_e32 v158, v125, v125
	v_cvt_pk_bf16_f32 v164, v126, v127
	v_cvt_pk_bf16_f32 v165, v128, v129
	v_cvt_pk_bf16_f32 v166, v122, v123
	v_cvt_pk_bf16_f32 v167, v124, v125
	global_store_dwordx4 v162, v[164:167], s[70:71]
	s_waitcnt vmcnt(15)
	v_lshlrev_b32_e32 v248, 16, v168
	v_lshlrev_b32_e32 v249, 16, v169
	v_lshlrev_b32_e32 v250, 16, v170
	v_lshlrev_b32_e32 v251, 16, v171
	v_and_b32_e32 v168, 0xffff0000, v168
	v_and_b32_e32 v169, 0xffff0000, v169
	v_and_b32_e32 v170, 0xffff0000, v170
	v_and_b32_e32 v171, 0xffff0000, v171
	v_add_f32_e32 v118, v118, v248
	v_add_f32_e32 v119, v119, v168
	v_add_f32_e32 v120, v120, v249
	v_add_f32_e32 v121, v121, v169
	v_add_f32_e32 v114, v114, v250
	v_add_f32_e32 v115, v115, v170
	v_add_f32_e32 v116, v116, v251
	v_add_f32_e32 v117, v117, v171
	v_fmac_f32_e32 v158, v118, v118
	v_fmac_f32_e32 v158, v119, v119
	v_fmac_f32_e32 v158, v120, v120
	v_fmac_f32_e32 v158, v121, v121
	v_fmac_f32_e32 v158, v114, v114
	v_fmac_f32_e32 v158, v115, v115
	v_fmac_f32_e32 v158, v116, v116
	v_fmac_f32_e32 v158, v117, v117
	v_cvt_pk_bf16_f32 v168, v118, v119
	v_cvt_pk_bf16_f32 v169, v120, v121
	v_cvt_pk_bf16_f32 v170, v114, v115
	v_cvt_pk_bf16_f32 v171, v116, v117
	global_store_dwordx4 v162, v[168:171], s[70:71] offset:256
	global_store_dword v163, v158, s[72:73]
	s_add_u32 s70, s70, 0x8000
	s_addc_u32 s71, s71, 0
	s_add_u32 s72, s72, 0x1000
	s_addc_u32 s73, s73, 0
	s_waitcnt vmcnt(15)
	v_lshlrev_b32_e32 v248, 16, v172
	v_lshlrev_b32_e32 v249, 16, v173
	v_lshlrev_b32_e32 v250, 16, v174
	v_lshlrev_b32_e32 v251, 16, v175
	v_and_b32_e32 v172, 0xffff0000, v172
	v_and_b32_e32 v173, 0xffff0000, v173
	v_and_b32_e32 v174, 0xffff0000, v174
	v_and_b32_e32 v175, 0xffff0000, v175
	v_add_f32_e32 v110, v110, v248
	v_add_f32_e32 v111, v111, v172
	v_add_f32_e32 v112, v112, v249
	v_add_f32_e32 v113, v113, v173
	v_add_f32_e32 v106, v106, v250
	v_add_f32_e32 v107, v107, v174
	v_add_f32_e32 v108, v108, v251
	v_add_f32_e32 v109, v109, v175
	v_mul_f32_e32 v159, v110, v110
	v_fmac_f32_e32 v159, v111, v111
	v_fmac_f32_e32 v159, v112, v112
	v_fmac_f32_e32 v159, v113, v113
	v_fmac_f32_e32 v159, v106, v106
	v_fmac_f32_e32 v159, v107, v107
	v_fmac_f32_e32 v159, v108, v108
	v_fmac_f32_e32 v159, v109, v109
	v_cvt_pk_bf16_f32 v172, v110, v111
	v_cvt_pk_bf16_f32 v173, v112, v113
	v_cvt_pk_bf16_f32 v174, v106, v107
	v_cvt_pk_bf16_f32 v175, v108, v109
	global_store_dwordx4 v162, v[172:175], s[70:71]
	s_waitcnt vmcnt(15)
	v_lshlrev_b32_e32 v248, 16, v176
	v_lshlrev_b32_e32 v249, 16, v177
	v_lshlrev_b32_e32 v250, 16, v178
	v_lshlrev_b32_e32 v251, 16, v179
	v_and_b32_e32 v176, 0xffff0000, v176
	v_and_b32_e32 v177, 0xffff0000, v177
	v_and_b32_e32 v178, 0xffff0000, v178
	v_and_b32_e32 v179, 0xffff0000, v179
	v_add_f32_e32 v102, v102, v248
	v_add_f32_e32 v103, v103, v176
	v_add_f32_e32 v104, v104, v249
	v_add_f32_e32 v105, v105, v177
	v_add_f32_e32 v98, v98, v250
	v_add_f32_e32 v99, v99, v178
	v_add_f32_e32 v100, v100, v251
	v_add_f32_e32 v101, v101, v179
	v_fmac_f32_e32 v159, v102, v102
	v_fmac_f32_e32 v159, v103, v103
	v_fmac_f32_e32 v159, v104, v104
	v_fmac_f32_e32 v159, v105, v105
	v_fmac_f32_e32 v159, v98, v98
	v_fmac_f32_e32 v159, v99, v99
	v_fmac_f32_e32 v159, v100, v100
	v_fmac_f32_e32 v159, v101, v101
	v_cvt_pk_bf16_f32 v176, v102, v103
	v_cvt_pk_bf16_f32 v177, v104, v105
	v_cvt_pk_bf16_f32 v178, v98, v99
	v_cvt_pk_bf16_f32 v179, v100, v101
	global_store_dwordx4 v162, v[176:179], s[70:71] offset:256
	global_store_dword v163, v159, s[72:73]
	s_add_u32 s70, s70, 0x8000
	s_addc_u32 s71, s71, 0
	s_add_u32 s72, s72, 0x1000
	s_addc_u32 s73, s73, 0
	s_waitcnt vmcnt(15)
; __device__ __forceinline__ u32x4 pack8(const float (&f)[8]) { u32x4 o; o.x = cvt_pk_bf16(f[0], f[1]); o.y = cvt_pk_bf16(f[2], f[3]); o.z = cvt_pk_bf16(f[4], f[5]); o.w = cvt_pk_bf16(f[6], f[7]); return o; }
;     __device__ __forceinline__ void operator()(const f32x4 (&acc)[2][2][4][2], const Unit& u, int wr, int wc, int fr, int fq) const {
;     ...
;         if (u.nkt == ntFull) {
; #pragma unroll
;             for (int ai = 0; ai < 2; ++ai)
; #pragma unroll
;                 for (int m = 0; m < 4; ++m) { bf16_t* rowp = X + (size_t)(row0 + ai * HALF + m * 16) * D + col0;
; #pragma unroll
;                     for (int bj = 0; bj < 2; ++bj) { u32x4* p = (u32x4*)(rowp + bj * HALF); float x[8]; unpack8(*p, x); const f32x4 a0 = acc[ai][bj][m][0], a1 = acc[ai][bj][m][1];
; #pragma unroll
;                         for (int e = 0; e < 4; ++e) { x[e] += a0[e]; x[4 + e] += a1[e]; }
;                         *p = pack8(x); }
;                     asm volatile("" ::: "memory"); }
	v_lshlrev_b32_e32 v248, 16, v180
	v_lshlrev_b32_e32 v249, 16, v181
	v_lshlrev_b32_e32 v250, 16, v182
	v_lshlrev_b32_e32 v251, 16, v183
	v_and_b32_e32 v180, 0xffff0000, v180
	v_and_b32_e32 v181, 0xffff0000, v181
	v_and_b32_e32 v182, 0xffff0000, v182
	v_and_b32_e32 v183, 0xffff0000, v183
	v_add_f32_e32 v94, v94, v248
	v_add_f32_e32 v95, v95, v180
	v_add_f32_e32 v96, v96, v249
	v_add_f32_e32 v97, v97, v181
	v_add_f32_e32 v90, v90, v250
	v_add_f32_e32 v91, v91, v182
	v_add_f32_e32 v92, v92, v251
	v_add_f32_e32 v93, v93, v183
	v_mul_f32_e32 v205, v94, v94
	v_fmac_f32_e32 v205, v95, v95
	v_fmac_f32_e32 v205, v96, v96
	v_fmac_f32_e32 v205, v97, v97
	v_fmac_f32_e32 v205, v90, v90
	v_fmac_f32_e32 v205, v91, v91
	v_fmac_f32_e32 v205, v92, v92
	v_fmac_f32_e32 v205, v93, v93
	v_cvt_pk_bf16_f32 v180, v94, v95
	v_cvt_pk_bf16_f32 v181, v96, v97
	v_cvt_pk_bf16_f32 v182, v90, v91
	v_cvt_pk_bf16_f32 v183, v92, v93
	global_store_dwordx4 v162, v[180:183], s[70:71]
	s_waitcnt vmcnt(15)
	v_lshlrev_b32_e32 v248, 16, v184
	v_lshlrev_b32_e32 v249, 16, v185
	v_lshlrev_b32_e32 v250, 16, v186
	v_lshlrev_b32_e32 v251, 16, v187
	v_and_b32_e32 v184, 0xffff0000, v184
	v_and_b32_e32 v185, 0xffff0000, v185
	v_and_b32_e32 v186, 0xffff0000, v186
	v_and_b32_e32 v187, 0xffff0000, v187
	v_add_f32_e32 v86, v86, v248
	v_add_f32_e32 v87, v87, v184
	v_add_f32_e32 v88, v88, v249
	v_add_f32_e32 v89, v89, v185
	v_add_f32_e32 v82, v82, v250
	v_add_f32_e32 v83, v83, v186
	v_add_f32_e32 v84, v84, v251
	v_add_f32_e32 v85, v85, v187
	v_fmac_f32_e32 v205, v86, v86
	v_fmac_f32_e32 v205, v87, v87
	v_fmac_f32_e32 v205, v88, v88
	v_fmac_f32_e32 v205, v89, v89
	v_fmac_f32_e32 v205, v82, v82
	v_fmac_f32_e32 v205, v83, v83
	v_fmac_f32_e32 v205, v84, v84
	v_fmac_f32_e32 v205, v85, v85
	v_cvt_pk_bf16_f32 v184, v86, v87
	v_cvt_pk_bf16_f32 v185, v88, v89
	v_cvt_pk_bf16_f32 v186, v82, v83
	v_cvt_pk_bf16_f32 v187, v84, v85
	global_store_dwordx4 v162, v[184:187], s[70:71] offset:256
	global_store_dword v163, v205, s[72:73]
	s_add_u32 s70, s70, 0x8000
	s_addc_u32 s71, s71, 0
	s_add_u32 s72, s72, 0x1000
	s_addc_u32 s73, s73, 0
	s_waitcnt vmcnt(15)
	v_lshlrev_b32_e32 v248, 16, v188
	v_lshlrev_b32_e32 v249, 16, v189
	v_lshlrev_b32_e32 v250, 16, v190
	v_lshlrev_b32_e32 v251, 16, v191
	v_and_b32_e32 v188, 0xffff0000, v188
	v_and_b32_e32 v189, 0xffff0000, v189
	v_and_b32_e32 v190, 0xffff0000, v190
	v_and_b32_e32 v191, 0xffff0000, v191
	v_add_f32_e32 v78, v78, v248
	v_add_f32_e32 v79, v79, v188
	v_add_f32_e32 v80, v80, v249
	v_add_f32_e32 v81, v81, v189
	v_add_f32_e32 v74, v74, v250
	v_add_f32_e32 v75, v75, v190
	v_add_f32_e32 v76, v76, v251
	v_add_f32_e32 v77, v77, v191
	v_mul_f32_e32 v206, v78, v78
	v_fmac_f32_e32 v206, v79, v79
	v_fmac_f32_e32 v206, v80, v80
	v_fmac_f32_e32 v206, v81, v81
	v_fmac_f32_e32 v206, v74, v74
	v_fmac_f32_e32 v206, v75, v75
	v_fmac_f32_e32 v206, v76, v76
	v_fmac_f32_e32 v206, v77, v77
	v_cvt_pk_bf16_f32 v188, v78, v79
	v_cvt_pk_bf16_f32 v189, v80, v81
	v_cvt_pk_bf16_f32 v190, v74, v75
	v_cvt_pk_bf16_f32 v191, v76, v77
	global_store_dwordx4 v162, v[188:191], s[70:71]
	s_waitcnt vmcnt(15)
	v_lshlrev_b32_e32 v248, 16, v192
	v_lshlrev_b32_e32 v249, 16, v193
	v_lshlrev_b32_e32 v250, 16, v194
	v_lshlrev_b32_e32 v251, 16, v195
	v_and_b32_e32 v192, 0xffff0000, v192
	v_and_b32_e32 v193, 0xffff0000, v193
	v_and_b32_e32 v194, 0xffff0000, v194
	v_and_b32_e32 v195, 0xffff0000, v195
	v_add_f32_e32 v70, v70, v248
	v_add_f32_e32 v71, v71, v192
	v_add_f32_e32 v72, v72, v249
	v_add_f32_e32 v73, v73, v193
	v_add_f32_e32 v66, v66, v250
	v_add_f32_e32 v67, v67, v194
	v_add_f32_e32 v68, v68, v251
	v_add_f32_e32 v69, v69, v195
	v_fmac_f32_e32 v206, v70, v70
	v_fmac_f32_e32 v206, v71, v71
	v_fmac_f32_e32 v206, v72, v72
	v_fmac_f32_e32 v206, v73, v73
	v_fmac_f32_e32 v206, v66, v66
	v_fmac_f32_e32 v206, v67, v67
	v_fmac_f32_e32 v206, v68, v68
	v_fmac_f32_e32 v206, v69, v69
	v_cvt_pk_bf16_f32 v192, v70, v71
	v_cvt_pk_bf16_f32 v193, v72, v73
	v_cvt_pk_bf16_f32 v194, v66, v67
	v_cvt_pk_bf16_f32 v195, v68, v69
	global_store_dwordx4 v162, v[192:195], s[70:71] offset:256
	global_store_dword v163, v206, s[72:73]
	s_add_u32 s70, s70, 0x28000
	s_addc_u32 s71, s71, 0
	s_add_u32 s72, s72, 0x5000
	s_addc_u32 s73, s73, 0
	s_waitcnt vmcnt(15)
	v_lshlrev_b32_e32 v248, 16, v196
	v_lshlrev_b32_e32 v249, 16, v197
	v_lshlrev_b32_e32 v250, 16, v198
	v_lshlrev_b32_e32 v251, 16, v199
	v_and_b32_e32 v196, 0xffff0000, v196
	v_and_b32_e32 v197, 0xffff0000, v197
	v_and_b32_e32 v198, 0xffff0000, v198
	v_and_b32_e32 v199, 0xffff0000, v199
	v_add_f32_e32 v62, v62, v248
	v_add_f32_e32 v63, v63, v196
	v_add_f32_e32 v64, v64, v249
	v_add_f32_e32 v65, v65, v197
	v_add_f32_e32 v58, v58, v250
	v_add_f32_e32 v59, v59, v198
	v_add_f32_e32 v60, v60, v251
	v_add_f32_e32 v61, v61, v199
	v_mul_f32_e32 v208, v62, v62
	v_fmac_f32_e32 v208, v63, v63
	v_fmac_f32_e32 v208, v64, v64
	v_fmac_f32_e32 v208, v65, v65
	v_fmac_f32_e32 v208, v58, v58
	v_fmac_f32_e32 v208, v59, v59
	v_fmac_f32_e32 v208, v60, v60
	v_fmac_f32_e32 v208, v61, v61
	v_cvt_pk_bf16_f32 v196, v62, v63
	v_cvt_pk_bf16_f32 v197, v64, v65
	v_cvt_pk_bf16_f32 v198, v58, v59
	v_cvt_pk_bf16_f32 v199, v60, v61
	global_store_dwordx4 v162, v[196:199], s[70:71]
	s_waitcnt vmcnt(15)
; __device__ __forceinline__ u32x4 pack8(const float (&f)[8]) { u32x4 o; o.x = cvt_pk_bf16(f[0], f[1]); o.y = cvt_pk_bf16(f[2], f[3]); o.z = cvt_pk_bf16(f[4], f[5]); o.w = cvt_pk_bf16(f[6], f[7]); return o; }
;     __device__ __forceinline__ void operator()(const f32x4 (&acc)[2][2][4][2], const Unit& u, int wr, int wc, int fr, int fq) const {
;     ...
;         if (u.nkt == ntFull) {
; #pragma unroll
;             for (int ai = 0; ai < 2; ++ai)
; #pragma unroll
;                 for (int m = 0; m < 4; ++m) { bf16_t* rowp = X + (size_t)(row0 + ai * HALF + m * 16) * D + col0;
; #pragma unroll
;                     for (int bj = 0; bj < 2; ++bj) { u32x4* p = (u32x4*)(rowp + bj * HALF); float x[8]; unpack8(*p, x); const f32x4 a0 = acc[ai][bj][m][0], a1 = acc[ai][bj][m][1];
; #pragma unroll
;                         for (int e = 0; e < 4; ++e) { x[e] += a0[e]; x[4 + e] += a1[e]; }
;                         *p = pack8(x); }
;                     asm volatile("" ::: "memory"); }
	v_lshlrev_b32_e32 v248, 16, v200
	v_lshlrev_b32_e32 v249, 16, v201
	v_lshlrev_b32_e32 v250, 16, v202
	v_lshlrev_b32_e32 v251, 16, v203
	v_and_b32_e32 v200, 0xffff0000, v200
	v_and_b32_e32 v201, 0xffff0000, v201
	v_and_b32_e32 v202, 0xffff0000, v202
	v_and_b32_e32 v203, 0xffff0000, v203
	v_add_f32_e32 v54, v54, v248
	v_add_f32_e32 v55, v55, v200
	v_add_f32_e32 v56, v56, v249
	v_add_f32_e32 v57, v57, v201
	v_add_f32_e32 v50, v50, v250
	v_add_f32_e32 v51, v51, v202
	v_add_f32_e32 v52, v52, v251
	v_add_f32_e32 v53, v53, v203
	v_fmac_f32_e32 v208, v54, v54
	v_fmac_f32_e32 v208, v55, v55
	v_fmac_f32_e32 v208, v56, v56
	v_fmac_f32_e32 v208, v57, v57
	v_fmac_f32_e32 v208, v50, v50
	v_fmac_f32_e32 v208, v51, v51
	v_fmac_f32_e32 v208, v52, v52
	v_fmac_f32_e32 v208, v53, v53
	v_cvt_pk_bf16_f32 v200, v54, v55
	v_cvt_pk_bf16_f32 v201, v56, v57
	v_cvt_pk_bf16_f32 v202, v50, v51
	v_cvt_pk_bf16_f32 v203, v52, v53
	global_store_dwordx4 v162, v[200:203], s[70:71] offset:256
	global_store_dword v163, v208, s[72:73]
	s_add_u32 s70, s70, 0x8000
	s_addc_u32 s71, s71, 0
	s_add_u32 s72, s72, 0x1000
	s_addc_u32 s73, s73, 0
	s_waitcnt vmcnt(15)
	v_lshlrev_b32_e32 v248, 16, v224
	v_lshlrev_b32_e32 v249, 16, v225
	v_lshlrev_b32_e32 v250, 16, v226
	v_lshlrev_b32_e32 v251, 16, v227
	v_and_b32_e32 v224, 0xffff0000, v224
	v_and_b32_e32 v225, 0xffff0000, v225
	v_and_b32_e32 v226, 0xffff0000, v226
	v_and_b32_e32 v227, 0xffff0000, v227
	v_add_f32_e32 v46, v46, v248
	v_add_f32_e32 v47, v47, v224
	v_add_f32_e32 v48, v48, v249
	v_add_f32_e32 v49, v49, v225
	v_add_f32_e32 v42, v42, v250
	v_add_f32_e32 v43, v43, v226
	v_add_f32_e32 v44, v44, v251
	v_add_f32_e32 v45, v45, v227
	v_mul_f32_e32 v210, v46, v46
	v_fmac_f32_e32 v210, v47, v47
	v_fmac_f32_e32 v210, v48, v48
	v_fmac_f32_e32 v210, v49, v49
	v_fmac_f32_e32 v210, v42, v42
	v_fmac_f32_e32 v210, v43, v43
	v_fmac_f32_e32 v210, v44, v44
	v_fmac_f32_e32 v210, v45, v45
	v_cvt_pk_bf16_f32 v224, v46, v47
	v_cvt_pk_bf16_f32 v225, v48, v49
	v_cvt_pk_bf16_f32 v226, v42, v43
	v_cvt_pk_bf16_f32 v227, v44, v45
	global_store_dwordx4 v162, v[224:227], s[70:71]
	s_waitcnt vmcnt(15)
	v_lshlrev_b32_e32 v248, 16, v228
	v_lshlrev_b32_e32 v249, 16, v229
	v_lshlrev_b32_e32 v250, 16, v230
	v_lshlrev_b32_e32 v251, 16, v231
	v_and_b32_e32 v228, 0xffff0000, v228
	v_and_b32_e32 v229, 0xffff0000, v229
	v_and_b32_e32 v230, 0xffff0000, v230
	v_and_b32_e32 v231, 0xffff0000, v231
	v_add_f32_e32 v38, v38, v248
	v_add_f32_e32 v39, v39, v228
	v_add_f32_e32 v40, v40, v249
	v_add_f32_e32 v41, v41, v229
	v_add_f32_e32 v34, v34, v250
	v_add_f32_e32 v35, v35, v230
	v_add_f32_e32 v36, v36, v251
	v_add_f32_e32 v37, v37, v231
	v_fmac_f32_e32 v210, v38, v38
	v_fmac_f32_e32 v210, v39, v39
	v_fmac_f32_e32 v210, v40, v40
	v_fmac_f32_e32 v210, v41, v41
	v_fmac_f32_e32 v210, v34, v34
	v_fmac_f32_e32 v210, v35, v35
	v_fmac_f32_e32 v210, v36, v36
	v_fmac_f32_e32 v210, v37, v37
	v_cvt_pk_bf16_f32 v228, v38, v39
	v_cvt_pk_bf16_f32 v229, v40, v41
	v_cvt_pk_bf16_f32 v230, v34, v35
	v_cvt_pk_bf16_f32 v231, v36, v37
	global_store_dwordx4 v162, v[228:231], s[70:71] offset:256
	global_store_dword v163, v210, s[72:73]
	s_add_u32 s70, s70, 0x8000
	s_addc_u32 s71, s71, 0
	s_add_u32 s72, s72, 0x1000
	s_addc_u32 s73, s73, 0
	s_waitcnt vmcnt(15)
; __device__ __forceinline__ u32x4 pack8(const float (&f)[8]) { u32x4 o; o.x = cvt_pk_bf16(f[0], f[1]); o.y = cvt_pk_bf16(f[2], f[3]); o.z = cvt_pk_bf16(f[4], f[5]); o.w = cvt_pk_bf16(f[6], f[7]); return o; }
;     __device__ __forceinline__ void operator()(const f32x4 (&acc)[2][2][4][2], const Unit& u, int wr, int wc, int fr, int fq) const {
;     ...
;         if (u.nkt == ntFull) {
; #pragma unroll
;             for (int ai = 0; ai < 2; ++ai)
; #pragma unroll
;                 for (int m = 0; m < 4; ++m) { bf16_t* rowp = X + (size_t)(row0 + ai * HALF + m * 16) * D + col0;
; #pragma unroll
;                     for (int bj = 0; bj < 2; ++bj) { u32x4* p = (u32x4*)(rowp + bj * HALF); float x[8]; unpack8(*p, x); const f32x4 a0 = acc[ai][bj][m][0], a1 = acc[ai][bj][m][1];
; #pragma unroll
;                         for (int e = 0; e < 4; ++e) { x[e] += a0[e]; x[4 + e] += a1[e]; }
;                         *p = pack8(x); }
;                     asm volatile("" ::: "memory"); }
	v_lshlrev_b32_e32 v248, 16, v232
	v_lshlrev_b32_e32 v249, 16, v233
	v_lshlrev_b32_e32 v250, 16, v234
	v_lshlrev_b32_e32 v251, 16, v235
	v_and_b32_e32 v232, 0xffff0000, v232
	v_and_b32_e32 v233, 0xffff0000, v233
	v_and_b32_e32 v234, 0xffff0000, v234
	v_and_b32_e32 v235, 0xffff0000, v235
	v_add_f32_e32 v30, v30, v248
	v_add_f32_e32 v31, v31, v232
	v_add_f32_e32 v32, v32, v249
	v_add_f32_e32 v33, v33, v233
	v_add_f32_e32 v26, v26, v250
	v_add_f32_e32 v27, v27, v234
	v_add_f32_e32 v28, v28, v251
	v_add_f32_e32 v29, v29, v235
	v_mul_f32_e32 v211, v30, v30
	v_fmac_f32_e32 v211, v31, v31
	v_fmac_f32_e32 v211, v32, v32
	v_fmac_f32_e32 v211, v33, v33
	v_fmac_f32_e32 v211, v26, v26
	v_fmac_f32_e32 v211, v27, v27
	v_fmac_f32_e32 v211, v28, v28
	v_fmac_f32_e32 v211, v29, v29
	v_cvt_pk_bf16_f32 v232, v30, v31
	v_cvt_pk_bf16_f32 v233, v32, v33
	v_cvt_pk_bf16_f32 v234, v26, v27
	v_cvt_pk_bf16_f32 v235, v28, v29
	global_store_dwordx4 v162, v[232:235], s[70:71]
	s_waitcnt vmcnt(15)
	v_lshlrev_b32_e32 v248, 16, v236
	v_lshlrev_b32_e32 v249, 16, v237
	v_lshlrev_b32_e32 v250, 16, v238
	v_lshlrev_b32_e32 v251, 16, v239
	v_and_b32_e32 v236, 0xffff0000, v236
	v_and_b32_e32 v237, 0xffff0000, v237
	v_and_b32_e32 v238, 0xffff0000, v238
	v_and_b32_e32 v239, 0xffff0000, v239
	v_add_f32_e32 v22, v22, v248
	v_add_f32_e32 v23, v23, v236
	v_add_f32_e32 v24, v24, v249
	v_add_f32_e32 v25, v25, v237
	v_add_f32_e32 v18, v18, v250
	v_add_f32_e32 v19, v19, v238
	v_add_f32_e32 v20, v20, v251
	v_add_f32_e32 v21, v21, v239
	v_fmac_f32_e32 v211, v22, v22
	v_fmac_f32_e32 v211, v23, v23
	v_fmac_f32_e32 v211, v24, v24
	v_fmac_f32_e32 v211, v25, v25
	v_fmac_f32_e32 v211, v18, v18
	v_fmac_f32_e32 v211, v19, v19
	v_fmac_f32_e32 v211, v20, v20
	v_fmac_f32_e32 v211, v21, v21
	v_cvt_pk_bf16_f32 v236, v22, v23
	v_cvt_pk_bf16_f32 v237, v24, v25
	v_cvt_pk_bf16_f32 v238, v18, v19
	v_cvt_pk_bf16_f32 v239, v20, v21
	global_store_dwordx4 v162, v[236:239], s[70:71] offset:256
	global_store_dword v163, v211, s[72:73]
	s_add_u32 s70, s70, 0x8000
	s_addc_u32 s71, s71, 0
	s_add_u32 s72, s72, 0x1000
	s_addc_u32 s73, s73, 0
	s_waitcnt vmcnt(15)
	v_lshlrev_b32_e32 v248, 16, v240
	v_lshlrev_b32_e32 v249, 16, v241
	v_lshlrev_b32_e32 v250, 16, v242
	v_lshlrev_b32_e32 v251, 16, v243
	v_and_b32_e32 v240, 0xffff0000, v240
	v_and_b32_e32 v241, 0xffff0000, v241
	v_and_b32_e32 v242, 0xffff0000, v242
	v_and_b32_e32 v243, 0xffff0000, v243
	v_add_f32_e32 v14, v14, v248
	v_add_f32_e32 v15, v15, v240
	v_add_f32_e32 v16, v16, v249
	v_add_f32_e32 v17, v17, v241
	v_add_f32_e32 v10, v10, v250
	v_add_f32_e32 v11, v11, v242
	v_add_f32_e32 v12, v12, v251
	v_add_f32_e32 v13, v13, v243
	v_mul_f32_e32 v212, v14, v14
	v_fmac_f32_e32 v212, v15, v15
	v_fmac_f32_e32 v212, v16, v16
	v_fmac_f32_e32 v212, v17, v17
	v_fmac_f32_e32 v212, v10, v10
	v_fmac_f32_e32 v212, v11, v11
	v_fmac_f32_e32 v212, v12, v12
	v_fmac_f32_e32 v212, v13, v13
	v_cvt_pk_bf16_f32 v240, v14, v15
	v_cvt_pk_bf16_f32 v241, v16, v17
	v_cvt_pk_bf16_f32 v242, v10, v11
	v_cvt_pk_bf16_f32 v243, v12, v13
	global_store_dwordx4 v162, v[240:243], s[70:71]
	s_waitcnt vmcnt(15)
	v_lshlrev_b32_e32 v248, 16, v244
	v_lshlrev_b32_e32 v249, 16, v245
	v_lshlrev_b32_e32 v250, 16, v246
	v_lshlrev_b32_e32 v251, 16, v247
	v_and_b32_e32 v244, 0xffff0000, v244
	v_and_b32_e32 v245, 0xffff0000, v245
	v_and_b32_e32 v246, 0xffff0000, v246
	v_and_b32_e32 v247, 0xffff0000, v247
	v_add_f32_e32 v6, v6, v248
	v_add_f32_e32 v7, v7, v244
	v_add_f32_e32 v8, v8, v249
	v_add_f32_e32 v9, v9, v245
	v_add_f32_e32 v2, v2, v250
	v_add_f32_e32 v3, v3, v246
	v_add_f32_e32 v4, v4, v251
	v_add_f32_e32 v5, v5, v247
	v_fmac_f32_e32 v212, v6, v6
	v_fmac_f32_e32 v212, v7, v7
	v_fmac_f32_e32 v212, v8, v8
	v_fmac_f32_e32 v212, v9, v9
	v_fmac_f32_e32 v212, v2, v2
	v_fmac_f32_e32 v212, v3, v3
	v_fmac_f32_e32 v212, v4, v4
	v_fmac_f32_e32 v212, v5, v5
	v_cvt_pk_bf16_f32 v244, v6, v7
	v_cvt_pk_bf16_f32 v245, v8, v9
	v_cvt_pk_bf16_f32 v246, v2, v3
	v_cvt_pk_bf16_f32 v247, v4, v5
	global_store_dwordx4 v162, v[244:247], s[70:71] offset:256
	global_store_dword v163, v212, s[72:73]
	s_and_b64 vcc, exec, s[4:5]
	s_mov_b64 s[4:5], -1
	s_cbranch_vccnz .LBB0_1083
	s_branch .LBB0_1108
